# MFMA order in GEMM K-loops: accumulate chains visited in a 32-wide snake (A fragment shared across both column blocks, no unshared transition inside a segment), K order of each pair chosen to start wi
# speedup vs baseline: 1.0180x; 1.0027x over previous
; #define PG8_STAGE(bufoff, gbase, voff) do { _Pragma("unroll") for (int _i = 0; _i < 2; ++_i) \
;         __builtin_amdgcn_global_load_lds((const unsigned*)((const char*)(gbase) + (voff)[_i]), (LAS unsigned*)(lds + (bufoff) + ldsw + _i * 8192), 16, 0, 0); } while (0)
; #define PG8_LDA(dst, b, h) do { _Pragma("unroll") for (int m = 0; m < 4; ++m) _Pragma("unroll") for (int k = 0; k < 2; ++k) dst[m][k] = *(const LAS bf16x8*)(lds + PG8_SA(b, h) + aoff + m * 2048 + k * 1024); } while (0)
; #define PG8_LDB(dst, b, h) do { _Pragma("unroll") for (int n = 0; n < 2; ++n) _Pragma("unroll") for (int k = 0; k < 2; ++k) dst[n][k] = *(const LAS bf16x8*)(lds + PG8_SB(b, h) + boff + n * 2048 + k * 1024); } while (0)
; #define PG8_SCHED __builtin_amdgcn_sched_barrier(0)
; template <class Epi, bool ALIGN_EPI>
; __device__ __forceinline__ void gemm_phase(LAS unsigned char* lds, const Gemm g, const StaticOrder& S, const Epi& E, const int tid) {
;     ...
;         const char* nA = has_next ? (const char*)g.A + (size_t)nxt.pm * tstepA + (size_t)nxt.pn * g.acs : cA; const char* nB = has_next ? (const char*)g.Bt + (size_t)nxt.pn * tstepB : cB;
;         for (int t = 0; t < nt; t += 2) {
;             const bool last = (t == nt - 2);
;             const char* a1 = cA + (size_t)(t + 1) * kstepA;
;             const char* a2 = last ? nA : cA + (size_t)(t + 2) * kstepA; const char* b2 = last ? nB : cB + (size_t)(t + 2) * kstepB;
;             const char* a3 = a2 + kstepA; const char* b3 = b2 + kstepB;
;             PG8_LDB(B0, 0, 0); PG8_LDB(B1, 0, 1); PG8_SCHED; PG8_LDA(At, 0, 0); PG8_STAGE(PG8_SA(1, 1), a1 + hstepA, voffA);
.LBB0_211:
	s_add_u32 s50, s48, 0x4000
	s_addc_u32 s51, s49, 0
	s_cmp_eq_u32 s89, 28
	s_cselect_b32 s54, s87, s50
	s_cselect_b32 s55, s43, s51
	s_cselect_b32 s52, vcc_lo, vcc_hi
	s_cselect_b32 s53, s35, s88
	s_add_u32 s50, s54, 0x8000
	s_addc_u32 s51, s55, 0
	s_add_i32 s90, 0, 0x10000
	v_add_u32_e32 v0, s90, v160
	s_add_i32 s92, 0, 0x14000
	ds_read_b128 v[132:135], v0
	ds_read_b128 v[136:139], v0 offset:1024
	ds_read_b128 v[152:155], v0 offset:2048
	ds_read_b128 v[156:159], v0 offset:3072
	v_add_u32_e32 v0, s92, v160
	ds_read_b128 v[162:165], v0
	ds_read_b128 v[166:169], v0 offset:1024
	ds_read_b128 v[170:173], v0 offset:2048
	ds_read_b128 v[174:177], v0 offset:3072
	s_add_i32 m0, s72, 0xc000
	ds_read_b128 v[178:181], v161
	ds_read_b128 v[182:185], v161 offset:1024
	ds_read_b128 v[186:189], v161 offset:2048
	ds_read_b128 v[190:193], v161 offset:3072
	ds_read_b128 v[194:197], v161 offset:4096
	ds_read_b128 v[198:201], v161 offset:5120
	ds_read_b128 v[214:217], v161 offset:6144

; #define PG8_STAGE(bufoff, gbase, voff) do { _Pragma("unroll") for (int _i = 0; _i < 2; ++_i) \
;         __builtin_amdgcn_global_load_lds((const unsigned*)((const char*)(gbase) + (voff)[_i]), (LAS unsigned*)(lds + (bufoff) + ldsw + _i * 8192), 16, 0, 0); } while (0)
; #define PG8_LDA(dst, b, h) do { _Pragma("unroll") for (int m = 0; m < 4; ++m) _Pragma("unroll") for (int k = 0; k < 2; ++k) dst[m][k] = *(const LAS bf16x8*)(lds + PG8_SA(b, h) + aoff + m * 2048 + k * 1024); } while (0)
; #define PG8_LDB(dst, b, h) do { _Pragma("unroll") for (int n = 0; n < 2; ++n) _Pragma("unroll") for (int k = 0; k < 2; ++k) dst[n][k] = *(const LAS bf16x8*)(lds + PG8_SB(b, h) + boff + n * 2048 + k * 1024); } while (0)
; #define PG8_MMA(ai, bj, At, Bt) do { __builtin_amdgcn_s_setprio(1); _Pragma("unroll") for (int m = 0; m < 4; ++m) _Pragma("unroll") for (int n = 0; n < 2; ++n) _Pragma("unroll") for (int k = 0; k < 2; ++k) \
;         acc[ai][bj][m][n] = __builtin_amdgcn_mfma_f32_16x16x32_bf16(Bt[n][k], At[m][k], acc[ai][bj][m][n], 0, 0, 0); __builtin_amdgcn_s_setprio(0); } while (0)
; #define PG8_WAIT_V(n) asm volatile("s_waitcnt vmcnt(" #n ")" ::: "memory")
; #define PG8_WAIT_L(n) asm volatile("s_waitcnt lgkmcnt(" #n ")" ::: "memory")
; #define PG8_BAR __builtin_amdgcn_s_barrier()
; #define PG8_SCHED __builtin_amdgcn_sched_barrier(0)
; template <class Epi, bool ALIGN_EPI>
; __device__ __forceinline__ void gemm_phase(LAS unsigned char* lds, const Gemm g, const StaticOrder& S, const Epi& E, const int tid) {
;     ...
;             PG8_LDB(B0, 0, 0); PG8_LDB(B1, 0, 1); PG8_SCHED; PG8_LDA(At, 0, 0); PG8_STAGE(PG8_SA(1, 1), a1 + hstepA, voffA);
;             PG8_WAIT_V(8); PG8_WAIT_L(0); PG8_BAR; PG8_MMA(0, 0, At, B0); PG8_MMA(0, 1, At, B1); PG8_BAR; PG8_SCHED;
	global_load_lds_dwordx4 v148, s[48:49]
	s_add_i32 m0, s72, 0xe000
	ds_read_b128 v[218:221], v161 offset:7168
	global_load_lds_dwordx4 v150, s[48:49]
	s_waitcnt vmcnt(8)
	s_waitcnt lgkmcnt(0)
	s_barrier


; #define PG8_MMA(ai, bj, At, Bt) do { __builtin_amdgcn_s_setprio(1); _Pragma("unroll") for (int m = 0; m < 4; ++m) _Pragma("unroll") for (int n = 0; n < 2; ++n) _Pragma("unroll") for (int k = 0; k < 2; ++k) \
;         acc[ai][bj][m][n] = __builtin_amdgcn_mfma_f32_16x16x32_bf16(Bt[n][k], At[m][k], acc[ai][bj][m][n], 0, 0, 0); __builtin_amdgcn_s_setprio(0); } while (0)
; #define PG8_WAIT_V(n) asm volatile("s_waitcnt vmcnt(" #n ")" ::: "memory")
; #define PG8_WAIT_L(n) asm volatile("s_waitcnt lgkmcnt(" #n ")" ::: "memory")
; #define PG8_BAR __builtin_amdgcn_s_barrier()
; #define PG8_SCHED __builtin_amdgcn_sched_barrier(0)
; template <class Epi, bool ALIGN_EPI>
; __device__ __forceinline__ void gemm_phase(LAS unsigned char* lds, const Gemm g, const StaticOrder& S, const Epi& E, const int tid) {
;     ...
;             PG8_WAIT_V(8); PG8_WAIT_L(0); PG8_BAR; PG8_MMA(0, 0, At, B0); PG8_MMA(0, 1, At, B1); PG8_BAR; PG8_SCHED;
	v_mfma_f32_16x16x32_bf16 v[88:91], v[132:135], v[178:181], v[88:91]
	v_mfma_f32_16x16x32_bf16 v[88:91], v[136:139], v[182:185], v[88:91]
	v_mfma_f32_16x16x32_bf16 v[124:127], v[156:159], v[182:185], v[124:127]
	v_mfma_f32_16x16x32_bf16 v[124:127], v[152:155], v[178:181], v[124:127]
	v_mfma_f32_16x16x32_bf16 v[128:131], v[170:173], v[178:181], v[128:131]
	v_mfma_f32_16x16x32_bf16 v[128:131], v[174:177], v[182:185], v[128:131]
	v_mfma_f32_16x16x32_bf16 v[80:83], v[166:169], v[182:185], v[80:83]
	v_mfma_f32_16x16x32_bf16 v[80:83], v[162:165], v[178:181], v[80:83]
	v_mfma_f32_16x16x32_bf16 v[68:71], v[162:165], v[186:189], v[68:71]
	v_mfma_f32_16x16x32_bf16 v[68:71], v[166:169], v[190:193], v[68:71]
	v_mfma_f32_16x16x32_bf16 v[108:111], v[174:177], v[190:193], v[108:111]
	v_mfma_f32_16x16x32_bf16 v[108:111], v[170:173], v[186:189], v[108:111]
	v_mfma_f32_16x16x32_bf16 v[120:123], v[152:155], v[186:189], v[120:123]
	v_mfma_f32_16x16x32_bf16 v[120:123], v[156:159], v[190:193], v[120:123]
	v_mfma_f32_16x16x32_bf16 v[52:55], v[136:139], v[190:193], v[52:55]
	v_mfma_f32_16x16x32_bf16 v[52:55], v[132:135], v[186:189], v[52:55]


; #define PG8_MMA(ai, bj, At, Bt) do { __builtin_amdgcn_s_setprio(1); _Pragma("unroll") for (int m = 0; m < 4; ++m) _Pragma("unroll") for (int n = 0; n < 2; ++n) _Pragma("unroll") for (int k = 0; k < 2; ++k) \
;         acc[ai][bj][m][n] = __builtin_amdgcn_mfma_f32_16x16x32_bf16(Bt[n][k], At[m][k], acc[ai][bj][m][n], 0, 0, 0); __builtin_amdgcn_s_setprio(0); } while (0)
; #define PG8_WAIT_V(n) asm volatile("s_waitcnt vmcnt(" #n ")" ::: "memory")
; #define PG8_WAIT_L(n) asm volatile("s_waitcnt lgkmcnt(" #n ")" ::: "memory")
; #define PG8_BAR __builtin_amdgcn_s_barrier()
; #define PG8_SCHED __builtin_amdgcn_sched_barrier(0)
; template <class Epi, bool ALIGN_EPI>
; __device__ __forceinline__ void gemm_phase(LAS unsigned char* lds, const Gemm g, const StaticOrder& S, const Epi& E, const int tid) {
;     ...
;             PG8_WAIT_V(8); PG8_WAIT_L(0); PG8_BAR; PG8_MMA(0, 0, At, B0); PG8_MMA(0, 1, At, B1); PG8_BAR; PG8_SCHED;
	v_mfma_f32_16x16x32_bf16 v[40:43], v[132:135], v[194:197], v[40:43]
	v_mfma_f32_16x16x32_bf16 v[40:43], v[136:139], v[198:201], v[40:43]
	v_mfma_f32_16x16x32_bf16 v[116:119], v[156:159], v[198:201], v[116:119]
	v_mfma_f32_16x16x32_bf16 v[116:119], v[152:155], v[194:197], v[116:119]
	v_mfma_f32_16x16x32_bf16 v[104:107], v[170:173], v[194:197], v[104:107]
	v_mfma_f32_16x16x32_bf16 v[104:107], v[174:177], v[198:201], v[104:107]
	v_mfma_f32_16x16x32_bf16 v[60:63], v[166:169], v[198:201], v[60:63]
	v_mfma_f32_16x16x32_bf16 v[60:63], v[162:165], v[194:197], v[60:63]
	v_mfma_f32_16x16x32_bf16 v[48:51], v[162:165], v[214:217], v[48:51]
	v_mfma_f32_16x16x32_bf16 v[48:51], v[166:169], v[218:221], v[48:51]
	v_mfma_f32_16x16x32_bf16 v[100:103], v[174:177], v[218:221], v[100:103]
	v_mfma_f32_16x16x32_bf16 v[100:103], v[170:173], v[214:217], v[100:103]
	v_mfma_f32_16x16x32_bf16 v[112:115], v[152:155], v[214:217], v[112:115]
	v_mfma_f32_16x16x32_bf16 v[112:115], v[156:159], v[218:221], v[112:115]
	v_mfma_f32_16x16x32_bf16 v[36:39], v[136:139], v[218:221], v[36:39]
	v_mfma_f32_16x16x32_bf16 v[36:39], v[132:135], v[214:217], v[36:39]

; #define PG8_STAGE(bufoff, gbase, voff) do { _Pragma("unroll") for (int _i = 0; _i < 2; ++_i) \
;         __builtin_amdgcn_global_load_lds((const unsigned*)((const char*)(gbase) + (voff)[_i]), (LAS unsigned*)(lds + (bufoff) + ldsw + _i * 8192), 16, 0, 0); } while (0)
; #define PG8_LDA(dst, b, h) do { _Pragma("unroll") for (int m = 0; m < 4; ++m) _Pragma("unroll") for (int k = 0; k < 2; ++k) dst[m][k] = *(const LAS bf16x8*)(lds + PG8_SA(b, h) + aoff + m * 2048 + k * 1024); } while (0)
; #define PG8_MMA(ai, bj, At, Bt) do { __builtin_amdgcn_s_setprio(1); _Pragma("unroll") for (int m = 0; m < 4; ++m) _Pragma("unroll") for (int n = 0; n < 2; ++n) _Pragma("unroll") for (int k = 0; k < 2; ++k) \
;         acc[ai][bj][m][n] = __builtin_amdgcn_mfma_f32_16x16x32_bf16(Bt[n][k], At[m][k], acc[ai][bj][m][n], 0, 0, 0); __builtin_amdgcn_s_setprio(0); } while (0)
; #define PG8_WAIT_V(n) asm volatile("s_waitcnt vmcnt(" #n ")" ::: "memory")
; #define PG8_WAIT_L(n) asm volatile("s_waitcnt lgkmcnt(" #n ")" ::: "memory")
; #define PG8_BAR __builtin_amdgcn_s_barrier()
; #define PG8_SCHED __builtin_amdgcn_sched_barrier(0)
; template <class Epi, bool ALIGN_EPI>
; __device__ __forceinline__ void gemm_phase(LAS unsigned char* lds, const Gemm g, const StaticOrder& S, const Epi& E, const int tid) {
;     ...
;             PG8_WAIT_V(8); PG8_WAIT_L(0); PG8_BAR; PG8_MMA(0, 0, At, B0); PG8_MMA(0, 1, At, B1); PG8_BAR; PG8_SCHED;
;             PG8_LDA(At, 0, 1); PG8_STAGE(PG8_SB(0, 0), b2, voffB); PG8_STAGE(PG8_SB(0, 1), b2 + hstepB, voffB); PG8_STAGE(PG8_SA(0, 0), a2, voffA);
	s_barrier
	s_add_i32 s90, s90, s71
	s_mov_b32 m0, s90
	ds_read_b128 v[178:181], v161 offset:16384
	ds_read_b128 v[182:185], v161 offset:17408
	ds_read_b128 v[186:189], v161 offset:18432
	ds_read_b128 v[190:193], v161 offset:19456


; #define PG8_STAGE(bufoff, gbase, voff) do { _Pragma("unroll") for (int _i = 0; _i < 2; ++_i) \
;         __builtin_amdgcn_global_load_lds((const unsigned*)((const char*)(gbase) + (voff)[_i]), (LAS unsigned*)(lds + (bufoff) + ldsw + _i * 8192), 16, 0, 0); } while (0)
; #define PG8_LDA(dst, b, h) do { _Pragma("unroll") for (int m = 0; m < 4; ++m) _Pragma("unroll") for (int k = 0; k < 2; ++k) dst[m][k] = *(const LAS bf16x8*)(lds + PG8_SA(b, h) + aoff + m * 2048 + k * 1024); } while (0)
; #define PG8_MMA(ai, bj, At, Bt) do { __builtin_amdgcn_s_setprio(1); _Pragma("unroll") for (int m = 0; m < 4; ++m) _Pragma("unroll") for (int n = 0; n < 2; ++n) _Pragma("unroll") for (int k = 0; k < 2; ++k) \
;         acc[ai][bj][m][n] = __builtin_amdgcn_mfma_f32_16x16x32_bf16(Bt[n][k], At[m][k], acc[ai][bj][m][n], 0, 0, 0); __builtin_amdgcn_s_setprio(0); } while (0)
; #define PG8_WAIT_V(n) asm volatile("s_waitcnt vmcnt(" #n ")" ::: "memory")
; #define PG8_WAIT_L(n) asm volatile("s_waitcnt lgkmcnt(" #n ")" ::: "memory")
; #define PG8_BAR __builtin_amdgcn_s_barrier()
; #define PG8_SCHED __builtin_amdgcn_sched_barrier(0)
; template <class Epi, bool ALIGN_EPI>
; __device__ __forceinline__ void gemm_phase(LAS unsigned char* lds, const Gemm g, const StaticOrder& S, const Epi& E, const int tid) {
;     ...
;             PG8_LDA(At, 0, 1); PG8_STAGE(PG8_SB(0, 0), b2, voffB); PG8_STAGE(PG8_SB(0, 1), b2 + hstepB, voffB); PG8_STAGE(PG8_SA(0, 0), a2, voffA);
;             PG8_WAIT_V(8); PG8_WAIT_L(0); PG8_BAR; PG8_MMA(1, 0, At, B0); PG8_MMA(1, 1, At, B1); PG8_BAR; PG8_SCHED;
	global_load_lds_dwordx4 v144, s[52:53]
	s_add_i32 m0, s90, 0x2000
	s_add_u32 s90, s52, 0x4000
	s_addc_u32 s91, s53, 0
	s_add_i32 s92, s92, s71
	global_load_lds_dwordx4 v140, s[52:53]
	s_mov_b32 m0, s92
	ds_read_b128 v[218:221], v161 offset:23552
	global_load_lds_dwordx4 v144, s[90:91]
	s_add_i32 m0, s92, 0x2000
	ds_read_b128 v[214:217], v161 offset:22528
	global_load_lds_dwordx4 v140, s[90:91]
	s_mov_b32 m0, s72
	ds_read_b128 v[198:201], v161 offset:21504
	global_load_lds_dwordx4 v146, s[54:55]
	s_mov_b32 m0, s73
	ds_read_b128 v[194:197], v161 offset:20480
	global_load_lds_dwordx4 v142, s[54:55]
	s_waitcnt vmcnt(8)
	s_waitcnt lgkmcnt(0)
	s_barrier


; #define PG8_MMA(ai, bj, At, Bt) do { __builtin_amdgcn_s_setprio(1); _Pragma("unroll") for (int m = 0; m < 4; ++m) _Pragma("unroll") for (int n = 0; n < 2; ++n) _Pragma("unroll") for (int k = 0; k < 2; ++k) \
;         acc[ai][bj][m][n] = __builtin_amdgcn_mfma_f32_16x16x32_bf16(Bt[n][k], At[m][k], acc[ai][bj][m][n], 0, 0, 0); __builtin_amdgcn_s_setprio(0); } while (0)
; #define PG8_WAIT_V(n) asm volatile("s_waitcnt vmcnt(" #n ")" ::: "memory")
; #define PG8_WAIT_L(n) asm volatile("s_waitcnt lgkmcnt(" #n ")" ::: "memory")
; #define PG8_BAR __builtin_amdgcn_s_barrier()
; #define PG8_SCHED __builtin_amdgcn_sched_barrier(0)
; template <class Epi, bool ALIGN_EPI>
; __device__ __forceinline__ void gemm_phase(LAS unsigned char* lds, const Gemm g, const StaticOrder& S, const Epi& E, const int tid) {
;     ...
;             PG8_WAIT_V(8); PG8_WAIT_L(0); PG8_BAR; PG8_MMA(1, 0, At, B0); PG8_MMA(1, 1, At, B1); PG8_BAR; PG8_SCHED;
	v_mfma_f32_16x16x32_bf16 v[24:27], v[132:135], v[178:181], v[24:27]
	v_mfma_f32_16x16x32_bf16 v[24:27], v[136:139], v[182:185], v[24:27]
	v_mfma_f32_16x16x32_bf16 v[92:95], v[156:159], v[182:185], v[92:95]
	v_mfma_f32_16x16x32_bf16 v[92:95], v[152:155], v[178:181], v[92:95]
	v_mfma_f32_16x16x32_bf16 v[72:75], v[170:173], v[178:181], v[72:75]
	v_mfma_f32_16x16x32_bf16 v[72:75], v[174:177], v[182:185], v[72:75]
	v_mfma_f32_16x16x32_bf16 v[32:35], v[166:169], v[182:185], v[32:35]
	v_mfma_f32_16x16x32_bf16 v[32:35], v[162:165], v[178:181], v[32:35]
	v_mfma_f32_16x16x32_bf16 v[28:31], v[162:165], v[186:189], v[28:31]
	v_mfma_f32_16x16x32_bf16 v[28:31], v[166:169], v[190:193], v[28:31]
	v_mfma_f32_16x16x32_bf16 v[96:99], v[174:177], v[190:193], v[96:99]
	v_mfma_f32_16x16x32_bf16 v[96:99], v[170:173], v[186:189], v[96:99]
	v_mfma_f32_16x16x32_bf16 v[84:87], v[152:155], v[186:189], v[84:87]
	v_mfma_f32_16x16x32_bf16 v[84:87], v[156:159], v[190:193], v[84:87]
	v_mfma_f32_16x16x32_bf16 v[16:19], v[136:139], v[190:193], v[16:19]
	v_mfma_f32_16x16x32_bf16 v[16:19], v[132:135], v[186:189], v[16:19]


; #define PG8_MMA(ai, bj, At, Bt) do { __builtin_amdgcn_s_setprio(1); _Pragma("unroll") for (int m = 0; m < 4; ++m) _Pragma("unroll") for (int n = 0; n < 2; ++n) _Pragma("unroll") for (int k = 0; k < 2; ++k) \
;         acc[ai][bj][m][n] = __builtin_amdgcn_mfma_f32_16x16x32_bf16(Bt[n][k], At[m][k], acc[ai][bj][m][n], 0, 0, 0); __builtin_amdgcn_s_setprio(0); } while (0)
; #define PG8_WAIT_V(n) asm volatile("s_waitcnt vmcnt(" #n ")" ::: "memory")
; #define PG8_WAIT_L(n) asm volatile("s_waitcnt lgkmcnt(" #n ")" ::: "memory")
; #define PG8_BAR __builtin_amdgcn_s_barrier()
; #define PG8_SCHED __builtin_amdgcn_sched_barrier(0)
; template <class Epi, bool ALIGN_EPI>
; __device__ __forceinline__ void gemm_phase(LAS unsigned char* lds, const Gemm g, const StaticOrder& S, const Epi& E, const int tid) {
;     ...
;             PG8_WAIT_V(8); PG8_WAIT_L(0); PG8_BAR; PG8_MMA(1, 0, At, B0); PG8_MMA(1, 1, At, B1); PG8_BAR; PG8_SCHED;
	v_mfma_f32_16x16x32_bf16 v[8:11], v[132:135], v[194:197], v[8:11]
	v_mfma_f32_16x16x32_bf16 v[8:11], v[136:139], v[198:201], v[8:11]
	v_mfma_f32_16x16x32_bf16 v[76:79], v[156:159], v[198:201], v[76:79]
	v_mfma_f32_16x16x32_bf16 v[76:79], v[152:155], v[194:197], v[76:79]
	v_mfma_f32_16x16x32_bf16 v[56:59], v[170:173], v[194:197], v[56:59]
	v_mfma_f32_16x16x32_bf16 v[56:59], v[174:177], v[198:201], v[56:59]
	v_mfma_f32_16x16x32_bf16 v[20:23], v[166:169], v[198:201], v[20:23]
	v_mfma_f32_16x16x32_bf16 v[20:23], v[162:165], v[194:197], v[20:23]
	v_mfma_f32_16x16x32_bf16 v[12:15], v[162:165], v[214:217], v[12:15]
	v_mfma_f32_16x16x32_bf16 v[12:15], v[166:169], v[218:221], v[12:15]
	v_mfma_f32_16x16x32_bf16 v[44:47], v[174:177], v[218:221], v[44:47]
	v_mfma_f32_16x16x32_bf16 v[44:47], v[170:173], v[214:217], v[44:47]
	v_mfma_f32_16x16x32_bf16 v[64:67], v[152:155], v[214:217], v[64:67]
	v_mfma_f32_16x16x32_bf16 v[64:67], v[156:159], v[218:221], v[64:67]
	v_mfma_f32_16x16x32_bf16 v[2:5], v[132:135], v[214:217], v[4:7]
	v_mfma_f32_16x16x32_bf16 v[2:5], v[136:139], v[218:221], v[2:5]

; #define PG8_STAGE(bufoff, gbase, voff) do { _Pragma("unroll") for (int _i = 0; _i < 2; ++_i) \
;         __builtin_amdgcn_global_load_lds((const unsigned*)((const char*)(gbase) + (voff)[_i]), (LAS unsigned*)(lds + (bufoff) + ldsw + _i * 8192), 16, 0, 0); } while (0)
; #define PG8_LDA(dst, b, h) do { _Pragma("unroll") for (int m = 0; m < 4; ++m) _Pragma("unroll") for (int k = 0; k < 2; ++k) dst[m][k] = *(const LAS bf16x8*)(lds + PG8_SA(b, h) + aoff + m * 2048 + k * 1024); } while (0)
; #define PG8_LDB(dst, b, h) do { _Pragma("unroll") for (int n = 0; n < 2; ++n) _Pragma("unroll") for (int k = 0; k < 2; ++k) dst[n][k] = *(const LAS bf16x8*)(lds + PG8_SB(b, h) + boff + n * 2048 + k * 1024); } while (0)
; #define PG8_SCHED __builtin_amdgcn_sched_barrier(0)
; template <class Epi, bool ALIGN_EPI>
; __device__ __forceinline__ void gemm_phase(LAS unsigned char* lds, const Gemm g, const StaticOrder& S, const Epi& E, const int tid) {
;     ...
;             PG8_LDB(B0, 1, 0); PG8_LDB(B1, 1, 1); PG8_SCHED; PG8_LDA(At, 1, 0); PG8_STAGE(PG8_SA(0, 1), a2 + hstepA, voffA);
	s_barrier
	s_add_i32 s90, 0, 0x18000
	v_add_u32_e32 v0, s90, v160
	s_add_i32 s91, 0, 0x1c000
	ds_read_b128 v[132:135], v0
	ds_read_b128 v[136:139], v0 offset:1024
	ds_read_b128 v[152:155], v0 offset:2048
	ds_read_b128 v[156:159], v0 offset:3072
	v_add_u32_e32 v0, s91, v160
	ds_read_b128 v[162:165], v0
	ds_read_b128 v[166:169], v0 offset:1024
	ds_read_b128 v[170:173], v0 offset:2048
	ds_read_b128 v[174:177], v0 offset:3072
	s_add_u32 s54, s54, 0x4000
	s_addc_u32 s55, s55, 0
	s_mov_b32 m0, s74
	ds_read_b128 v[178:181], v161 offset:32768
	ds_read_b128 v[182:185], v161 offset:33792
	ds_read_b128 v[186:189], v161 offset:34816
	ds_read_b128 v[190:193], v161 offset:35840
	ds_read_b128 v[194:197], v161 offset:36864
	ds_read_b128 v[198:201], v161 offset:37888
	ds_read_b128 v[214:217], v161 offset:38912

; #define PG8_STAGE(bufoff, gbase, voff) do { _Pragma("unroll") for (int _i = 0; _i < 2; ++_i) \
;         __builtin_amdgcn_global_load_lds((const unsigned*)((const char*)(gbase) + (voff)[_i]), (LAS unsigned*)(lds + (bufoff) + ldsw + _i * 8192), 16, 0, 0); } while (0)
; #define PG8_LDA(dst, b, h) do { _Pragma("unroll") for (int m = 0; m < 4; ++m) _Pragma("unroll") for (int k = 0; k < 2; ++k) dst[m][k] = *(const LAS bf16x8*)(lds + PG8_SA(b, h) + aoff + m * 2048 + k * 1024); } while (0)
; #define PG8_LDB(dst, b, h) do { _Pragma("unroll") for (int n = 0; n < 2; ++n) _Pragma("unroll") for (int k = 0; k < 2; ++k) dst[n][k] = *(const LAS bf16x8*)(lds + PG8_SB(b, h) + boff + n * 2048 + k * 1024); } while (0)
; #define PG8_MMA(ai, bj, At, Bt) do { __builtin_amdgcn_s_setprio(1); _Pragma("unroll") for (int m = 0; m < 4; ++m) _Pragma("unroll") for (int n = 0; n < 2; ++n) _Pragma("unroll") for (int k = 0; k < 2; ++k) \
;         acc[ai][bj][m][n] = __builtin_amdgcn_mfma_f32_16x16x32_bf16(Bt[n][k], At[m][k], acc[ai][bj][m][n], 0, 0, 0); __builtin_amdgcn_s_setprio(0); } while (0)
; #define PG8_WAIT_V(n) asm volatile("s_waitcnt vmcnt(" #n ")" ::: "memory")
; #define PG8_WAIT_L(n) asm volatile("s_waitcnt lgkmcnt(" #n ")" ::: "memory")
; #define PG8_BAR __builtin_amdgcn_s_barrier()
; #define PG8_SCHED __builtin_amdgcn_sched_barrier(0)
; template <class Epi, bool ALIGN_EPI>
; __device__ __forceinline__ void gemm_phase(LAS unsigned char* lds, const Gemm g, const StaticOrder& S, const Epi& E, const int tid) {
;     ...
;             PG8_LDB(B0, 1, 0); PG8_LDB(B1, 1, 1); PG8_SCHED; PG8_LDA(At, 1, 0); PG8_STAGE(PG8_SA(0, 1), a2 + hstepA, voffA);
;             PG8_WAIT_V(8); PG8_WAIT_L(0); PG8_BAR; PG8_MMA(0, 0, At, B0); PG8_MMA(0, 1, At, B1); PG8_BAR; PG8_SCHED;
	global_load_lds_dwordx4 v146, s[54:55]
	s_mov_b32 m0, s75
	ds_read_b128 v[218:221], v161 offset:39936
	global_load_lds_dwordx4 v142, s[54:55]
	s_waitcnt vmcnt(8)
	s_waitcnt lgkmcnt(0)
	s_barrier


; #define PG8_MMA(ai, bj, At, Bt) do { __builtin_amdgcn_s_setprio(1); _Pragma("unroll") for (int m = 0; m < 4; ++m) _Pragma("unroll") for (int n = 0; n < 2; ++n) _Pragma("unroll") for (int k = 0; k < 2; ++k) \
;         acc[ai][bj][m][n] = __builtin_amdgcn_mfma_f32_16x16x32_bf16(Bt[n][k], At[m][k], acc[ai][bj][m][n], 0, 0, 0); __builtin_amdgcn_s_setprio(0); } while (0)
; #define PG8_WAIT_V(n) asm volatile("s_waitcnt vmcnt(" #n ")" ::: "memory")
; #define PG8_WAIT_L(n) asm volatile("s_waitcnt lgkmcnt(" #n ")" ::: "memory")
; #define PG8_BAR __builtin_amdgcn_s_barrier()
; #define PG8_SCHED __builtin_amdgcn_sched_barrier(0)
; template <class Epi, bool ALIGN_EPI>
; __device__ __forceinline__ void gemm_phase(LAS unsigned char* lds, const Gemm g, const StaticOrder& S, const Epi& E, const int tid) {
;     ...
;             PG8_WAIT_V(8); PG8_WAIT_L(0); PG8_BAR; PG8_MMA(0, 0, At, B0); PG8_MMA(0, 1, At, B1); PG8_BAR; PG8_SCHED;
	v_mfma_f32_16x16x32_bf16 v[88:91], v[132:135], v[178:181], v[88:91]
	v_mfma_f32_16x16x32_bf16 v[88:91], v[136:139], v[182:185], v[88:91]
	v_mfma_f32_16x16x32_bf16 v[124:127], v[156:159], v[182:185], v[124:127]
	v_mfma_f32_16x16x32_bf16 v[124:127], v[152:155], v[178:181], v[124:127]
	v_mfma_f32_16x16x32_bf16 v[128:131], v[170:173], v[178:181], v[128:131]
	v_mfma_f32_16x16x32_bf16 v[128:131], v[174:177], v[182:185], v[128:131]
	v_mfma_f32_16x16x32_bf16 v[80:83], v[166:169], v[182:185], v[80:83]
	v_mfma_f32_16x16x32_bf16 v[80:83], v[162:165], v[178:181], v[80:83]
	v_mfma_f32_16x16x32_bf16 v[68:71], v[162:165], v[186:189], v[68:71]
	v_mfma_f32_16x16x32_bf16 v[68:71], v[166:169], v[190:193], v[68:71]
	v_mfma_f32_16x16x32_bf16 v[108:111], v[174:177], v[190:193], v[108:111]
	v_mfma_f32_16x16x32_bf16 v[108:111], v[170:173], v[186:189], v[108:111]
	v_mfma_f32_16x16x32_bf16 v[120:123], v[152:155], v[186:189], v[120:123]
	v_mfma_f32_16x16x32_bf16 v[120:123], v[156:159], v[190:193], v[120:123]
	v_mfma_f32_16x16x32_bf16 v[52:55], v[136:139], v[190:193], v[52:55]
	v_mfma_f32_16x16x32_bf16 v[52:55], v[132:135], v[186:189], v[52:55]


; #define PG8_MMA(ai, bj, At, Bt) do { __builtin_amdgcn_s_setprio(1); _Pragma("unroll") for (int m = 0; m < 4; ++m) _Pragma("unroll") for (int n = 0; n < 2; ++n) _Pragma("unroll") for (int k = 0; k < 2; ++k) \
;         acc[ai][bj][m][n] = __builtin_amdgcn_mfma_f32_16x16x32_bf16(Bt[n][k], At[m][k], acc[ai][bj][m][n], 0, 0, 0); __builtin_amdgcn_s_setprio(0); } while (0)
; #define PG8_WAIT_V(n) asm volatile("s_waitcnt vmcnt(" #n ")" ::: "memory")
; #define PG8_WAIT_L(n) asm volatile("s_waitcnt lgkmcnt(" #n ")" ::: "memory")
; #define PG8_BAR __builtin_amdgcn_s_barrier()
; #define PG8_SCHED __builtin_amdgcn_sched_barrier(0)
; template <class Epi, bool ALIGN_EPI>
; __device__ __forceinline__ void gemm_phase(LAS unsigned char* lds, const Gemm g, const StaticOrder& S, const Epi& E, const int tid) {
;     ...
;             PG8_WAIT_V(8); PG8_WAIT_L(0); PG8_BAR; PG8_MMA(0, 0, At, B0); PG8_MMA(0, 1, At, B1); PG8_BAR; PG8_SCHED;
	v_mfma_f32_16x16x32_bf16 v[40:43], v[132:135], v[194:197], v[40:43]
	v_mfma_f32_16x16x32_bf16 v[40:43], v[136:139], v[198:201], v[40:43]
	v_mfma_f32_16x16x32_bf16 v[116:119], v[156:159], v[198:201], v[116:119]
	v_mfma_f32_16x16x32_bf16 v[116:119], v[152:155], v[194:197], v[116:119]
	v_mfma_f32_16x16x32_bf16 v[104:107], v[170:173], v[194:197], v[104:107]
	v_mfma_f32_16x16x32_bf16 v[104:107], v[174:177], v[198:201], v[104:107]
	v_mfma_f32_16x16x32_bf16 v[60:63], v[166:169], v[198:201], v[60:63]
	v_mfma_f32_16x16x32_bf16 v[60:63], v[162:165], v[194:197], v[60:63]
	v_mfma_f32_16x16x32_bf16 v[48:51], v[162:165], v[214:217], v[48:51]
	v_mfma_f32_16x16x32_bf16 v[48:51], v[166:169], v[218:221], v[48:51]
	v_mfma_f32_16x16x32_bf16 v[100:103], v[174:177], v[218:221], v[100:103]
	v_mfma_f32_16x16x32_bf16 v[100:103], v[170:173], v[214:217], v[100:103]
	v_mfma_f32_16x16x32_bf16 v[112:115], v[152:155], v[214:217], v[112:115]
	v_mfma_f32_16x16x32_bf16 v[112:115], v[156:159], v[218:221], v[112:115]
	v_mfma_f32_16x16x32_bf16 v[36:39], v[136:139], v[218:221], v[36:39]
	v_mfma_f32_16x16x32_bf16 v[36:39], v[132:135], v[214:217], v[36:39]

; #define PG8_STAGE(bufoff, gbase, voff) do { _Pragma("unroll") for (int _i = 0; _i < 2; ++_i) \
;         __builtin_amdgcn_global_load_lds((const unsigned*)((const char*)(gbase) + (voff)[_i]), (LAS unsigned*)(lds + (bufoff) + ldsw + _i * 8192), 16, 0, 0); } while (0)
; #define PG8_LDA(dst, b, h) do { _Pragma("unroll") for (int m = 0; m < 4; ++m) _Pragma("unroll") for (int k = 0; k < 2; ++k) dst[m][k] = *(const LAS bf16x8*)(lds + PG8_SA(b, h) + aoff + m * 2048 + k * 1024); } while (0)
; template <class Epi, bool ALIGN_EPI>
; __device__ __forceinline__ void gemm_phase(LAS unsigned char* lds, const Gemm g, const StaticOrder& S, const Epi& E, const int tid) {
;     ...
;             PG8_LDA(At, 1, 1); PG8_STAGE(PG8_SB(1, 0), b3, voffB); PG8_STAGE(PG8_SB(1, 1), b3 + hstepB, voffB); PG8_STAGE(PG8_SA(1, 0), a3, voffA);
	s_barrier
	s_add_u32 s54, s52, 0x8000
	s_addc_u32 s55, s53, 0
	s_add_i32 s90, s90, s71
	s_mov_b32 m0, s90
	ds_read_b128 v[178:181], v161 offset:49152
	ds_read_b128 v[182:185], v161 offset:50176
	ds_read_b128 v[186:189], v161 offset:51200
	ds_read_b128 v[190:193], v161 offset:52224


; #define PG8_STAGE(bufoff, gbase, voff) do { _Pragma("unroll") for (int _i = 0; _i < 2; ++_i) \
;         __builtin_amdgcn_global_load_lds((const unsigned*)((const char*)(gbase) + (voff)[_i]), (LAS unsigned*)(lds + (bufoff) + ldsw + _i * 8192), 16, 0, 0); } while (0)
; #define PG8_LDA(dst, b, h) do { _Pragma("unroll") for (int m = 0; m < 4; ++m) _Pragma("unroll") for (int k = 0; k < 2; ++k) dst[m][k] = *(const LAS bf16x8*)(lds + PG8_SA(b, h) + aoff + m * 2048 + k * 1024); } while (0)
; #define PG8_MMA(ai, bj, At, Bt) do { __builtin_amdgcn_s_setprio(1); _Pragma("unroll") for (int m = 0; m < 4; ++m) _Pragma("unroll") for (int n = 0; n < 2; ++n) _Pragma("unroll") for (int k = 0; k < 2; ++k) \
;         acc[ai][bj][m][n] = __builtin_amdgcn_mfma_f32_16x16x32_bf16(Bt[n][k], At[m][k], acc[ai][bj][m][n], 0, 0, 0); __builtin_amdgcn_s_setprio(0); } while (0)
; #define PG8_WAIT_V(n) asm volatile("s_waitcnt vmcnt(" #n ")" ::: "memory")
; #define PG8_WAIT_L(n) asm volatile("s_waitcnt lgkmcnt(" #n ")" ::: "memory")
; #define PG8_BAR __builtin_amdgcn_s_barrier()
; #define PG8_SCHED __builtin_amdgcn_sched_barrier(0)
; template <class Epi, bool ALIGN_EPI>
; __device__ __forceinline__ void gemm_phase(LAS unsigned char* lds, const Gemm g, const StaticOrder& S, const Epi& E, const int tid) {
;     ...
;             PG8_LDA(At, 1, 1); PG8_STAGE(PG8_SB(1, 0), b3, voffB); PG8_STAGE(PG8_SB(1, 1), b3 + hstepB, voffB); PG8_STAGE(PG8_SA(1, 0), a3, voffA);
;             PG8_WAIT_V(8); PG8_WAIT_L(0); PG8_BAR; PG8_MMA(1, 0, At, B0); PG8_MMA(1, 1, At, B1); PG8_BAR; PG8_SCHED;
	global_load_lds_dwordx4 v144, s[54:55]
	s_add_i32 m0, s90, 0x2000
	s_add_u32 s52, s52, 0xc000
	s_addc_u32 s53, s53, 0
	global_load_lds_dwordx4 v140, s[54:55]
	s_add_i32 s54, s91, s71
	s_mov_b32 m0, s54
	ds_read_b128 v[218:221], v161 offset:56320
	global_load_lds_dwordx4 v144, s[52:53]
	s_add_i32 m0, s54, 0x2000
	ds_read_b128 v[214:217], v161 offset:55296
	global_load_lds_dwordx4 v140, s[52:53]
	s_mov_b32 m0, s79
	ds_read_b128 v[198:201], v161 offset:54272
	global_load_lds_dwordx4 v146, s[50:51]
	s_mov_b32 m0, s80
	ds_read_b128 v[194:197], v161 offset:53248
	global_load_lds_dwordx4 v142, s[50:51]
	s_waitcnt vmcnt(8)
	s_waitcnt lgkmcnt(0)
	s_barrier


; #define PG8_MMA(ai, bj, At, Bt) do { __builtin_amdgcn_s_setprio(1); _Pragma("unroll") for (int m = 0; m < 4; ++m) _Pragma("unroll") for (int n = 0; n < 2; ++n) _Pragma("unroll") for (int k = 0; k < 2; ++k) \
;         acc[ai][bj][m][n] = __builtin_amdgcn_mfma_f32_16x16x32_bf16(Bt[n][k], At[m][k], acc[ai][bj][m][n], 0, 0, 0); __builtin_amdgcn_s_setprio(0); } while (0)
; #define PG8_WAIT_V(n) asm volatile("s_waitcnt vmcnt(" #n ")" ::: "memory")
; #define PG8_WAIT_L(n) asm volatile("s_waitcnt lgkmcnt(" #n ")" ::: "memory")
; #define PG8_BAR __builtin_amdgcn_s_barrier()
; #define PG8_SCHED __builtin_amdgcn_sched_barrier(0)
; template <class Epi, bool ALIGN_EPI>
; __device__ __forceinline__ void gemm_phase(LAS unsigned char* lds, const Gemm g, const StaticOrder& S, const Epi& E, const int tid) {
;     ...
;             PG8_WAIT_V(8); PG8_WAIT_L(0); PG8_BAR; PG8_MMA(1, 0, At, B0); PG8_MMA(1, 1, At, B1); PG8_BAR; PG8_SCHED;
	v_mfma_f32_16x16x32_bf16 v[24:27], v[132:135], v[178:181], v[24:27]
	v_mfma_f32_16x16x32_bf16 v[24:27], v[136:139], v[182:185], v[24:27]
	v_mfma_f32_16x16x32_bf16 v[92:95], v[156:159], v[182:185], v[92:95]
	v_mfma_f32_16x16x32_bf16 v[92:95], v[152:155], v[178:181], v[92:95]
	v_mfma_f32_16x16x32_bf16 v[72:75], v[170:173], v[178:181], v[72:75]
	v_mfma_f32_16x16x32_bf16 v[72:75], v[174:177], v[182:185], v[72:75]
	v_mfma_f32_16x16x32_bf16 v[32:35], v[166:169], v[182:185], v[32:35]
	v_mfma_f32_16x16x32_bf16 v[32:35], v[162:165], v[178:181], v[32:35]
	v_mfma_f32_16x16x32_bf16 v[28:31], v[162:165], v[186:189], v[28:31]
	v_mfma_f32_16x16x32_bf16 v[28:31], v[166:169], v[190:193], v[28:31]
	v_mfma_f32_16x16x32_bf16 v[96:99], v[174:177], v[190:193], v[96:99]
	v_mfma_f32_16x16x32_bf16 v[96:99], v[170:173], v[186:189], v[96:99]
	v_mfma_f32_16x16x32_bf16 v[84:87], v[152:155], v[186:189], v[84:87]
	v_mfma_f32_16x16x32_bf16 v[84:87], v[156:159], v[190:193], v[84:87]
	v_mfma_f32_16x16x32_bf16 v[16:19], v[136:139], v[190:193], v[16:19]
	v_mfma_f32_16x16x32_bf16 v[16:19], v[132:135], v[186:189], v[16:19]


; #define PG8_MMA(ai, bj, At, Bt) do { __builtin_amdgcn_s_setprio(1); _Pragma("unroll") for (int m = 0; m < 4; ++m) _Pragma("unroll") for (int n = 0; n < 2; ++n) _Pragma("unroll") for (int k = 0; k < 2; ++k) \
;         acc[ai][bj][m][n] = __builtin_amdgcn_mfma_f32_16x16x32_bf16(Bt[n][k], At[m][k], acc[ai][bj][m][n], 0, 0, 0); __builtin_amdgcn_s_setprio(0); } while (0)
; #define PG8_WAIT_V(n) asm volatile("s_waitcnt vmcnt(" #n ")" ::: "memory")
; #define PG8_WAIT_L(n) asm volatile("s_waitcnt lgkmcnt(" #n ")" ::: "memory")
; #define PG8_BAR __builtin_amdgcn_s_barrier()
; #define PG8_SCHED __builtin_amdgcn_sched_barrier(0)
; template <class Epi, bool ALIGN_EPI>
; __device__ __forceinline__ void gemm_phase(LAS unsigned char* lds, const Gemm g, const StaticOrder& S, const Epi& E, const int tid) {
;     ...
;             PG8_WAIT_V(8); PG8_WAIT_L(0); PG8_BAR; PG8_MMA(1, 0, At, B0); PG8_MMA(1, 1, At, B1); PG8_BAR; PG8_SCHED;
	v_mfma_f32_16x16x32_bf16 v[6:9], v[132:135], v[194:197], v[8:11]
	v_mfma_f32_16x16x32_bf16 v[8:11], v[136:139], v[198:201], v[6:9]
	v_mfma_f32_16x16x32_bf16 v[76:79], v[156:159], v[198:201], v[76:79]
	v_mfma_f32_16x16x32_bf16 v[76:79], v[152:155], v[194:197], v[76:79]
	v_mfma_f32_16x16x32_bf16 v[56:59], v[170:173], v[194:197], v[56:59]
	v_mfma_f32_16x16x32_bf16 v[56:59], v[174:177], v[198:201], v[56:59]
	v_mfma_f32_16x16x32_bf16 v[20:23], v[166:169], v[198:201], v[20:23]
	v_mfma_f32_16x16x32_bf16 v[20:23], v[162:165], v[194:197], v[20:23]
	v_mfma_f32_16x16x32_bf16 v[12:15], v[162:165], v[214:217], v[12:15]
	v_mfma_f32_16x16x32_bf16 v[12:15], v[166:169], v[218:221], v[12:15]
	v_mfma_f32_16x16x32_bf16 v[44:47], v[174:177], v[218:221], v[44:47]
	v_mfma_f32_16x16x32_bf16 v[44:47], v[170:173], v[214:217], v[44:47]
	v_mfma_f32_16x16x32_bf16 v[64:67], v[152:155], v[214:217], v[64:67]
	v_mfma_f32_16x16x32_bf16 v[64:67], v[156:159], v[218:221], v[64:67]
	v_mfma_f32_16x16x32_bf16 v[2:5], v[132:135], v[214:217], v[2:5]
	v_mfma_f32_16x16x32_bf16 v[4:7], v[136:139], v[218:221], v[2:5]

; #define PG8_MMA(ai, bj, At, Bt) do { __builtin_amdgcn_s_setprio(1); _Pragma("unroll") for (int m = 0; m < 4; ++m) _Pragma("unroll") for (int n = 0; n < 2; ++n) _Pragma("unroll") for (int k = 0; k < 2; ++k) \
;         acc[ai][bj][m][n] = __builtin_amdgcn_mfma_f32_16x16x32_bf16(Bt[n][k], At[m][k], acc[ai][bj][m][n], 0, 0, 0); __builtin_amdgcn_s_setprio(0); } while (0)
; #define PG8_WAIT_V(n) asm volatile("s_waitcnt vmcnt(" #n ")" ::: "memory")
; #define PG8_WAIT_L(n) asm volatile("s_waitcnt lgkmcnt(" #n ")" ::: "memory")
; #define PG8_BAR __builtin_amdgcn_s_barrier()
; #define PG8_SCHED __builtin_amdgcn_sched_barrier(0)
; template <class Epi, bool ALIGN_EPI>
; __device__ __forceinline__ void gemm_phase(LAS unsigned char* lds, const Gemm g, const StaticOrder& S, const Epi& E, const int tid) {
;     ...
;             PG8_WAIT_V(8); PG8_WAIT_L(0); PG8_BAR; PG8_MMA(1, 0, At, B0); PG8_MMA(1, 1, At, B1); PG8_BAR; PG8_SCHED;
;         }
;         if constexpr (ALIGN_EPI) { if (wr == 0) PG8_BAR; }
	s_barrier
	s_add_i32 s89, s89, 2
	s_add_u32 s48, s48, 0x10000
	s_addc_u32 s49, s49, 0
	s_add_u32 vcc_hi, vcc_hi, 0x10000
	s_addc_u32 s88, s88, 0
	s_cmp_gt_u32 s89, 29
	s_cbranch_scc0 .LBB0_211
	s_and_b64 vcc, exec, s[22:23]
	s_cbranch_vccz .LBB0_214
	s_barrier

; #define PG8_STAGE(bufoff, gbase, voff) do { _Pragma("unroll") for (int _i = 0; _i < 2; ++_i) \
;         __builtin_amdgcn_global_load_lds((const unsigned*)((const char*)(gbase) + (voff)[_i]), (LAS unsigned*)(lds + (bufoff) + ldsw + _i * 8192), 16, 0, 0); } while (0)
; #define PG8_LDA(dst, b, h) do { _Pragma("unroll") for (int m = 0; m < 4; ++m) _Pragma("unroll") for (int k = 0; k < 2; ++k) dst[m][k] = *(const LAS bf16x8*)(lds + PG8_SA(b, h) + aoff + m * 2048 + k * 1024); } while (0)
; #define PG8_LDB(dst, b, h) do { _Pragma("unroll") for (int n = 0; n < 2; ++n) _Pragma("unroll") for (int k = 0; k < 2; ++k) dst[n][k] = *(const LAS bf16x8*)(lds + PG8_SB(b, h) + boff + n * 2048 + k * 1024); } while (0)
; #define PG8_SCHED __builtin_amdgcn_sched_barrier(0)
; template <class Epi, bool ALIGN_EPI>
; __device__ __forceinline__ void gemm_phase(LAS unsigned char* lds, const Gemm g, const StaticOrder& S, const Epi& E, const int tid) {
;     ...
;         const char* nA = has_next ? (const char*)g.A + (size_t)nxt.pm * tstepA + (size_t)nxt.pn * g.acs : cA; const char* nB = has_next ? (const char*)g.Bt + (size_t)nxt.pn * tstepB : cB;
;         for (int t = 0; t < nt; t += 2) {
;             const bool last = (t == nt - 2);
;             const char* a1 = cA + (size_t)(t + 1) * kstepA;
;             const char* a2 = last ? nA : cA + (size_t)(t + 2) * kstepA; const char* b2 = last ? nB : cB + (size_t)(t + 2) * kstepB;
;             const char* a3 = a2 + kstepA; const char* b3 = b2 + kstepB;
;             PG8_LDB(B0, 0, 0); PG8_LDB(B1, 0, 1); PG8_SCHED; PG8_LDA(At, 0, 0); PG8_STAGE(PG8_SA(1, 1), a1 + hstepA, voffA);
.LBB0_294:
	s_add_u32 s22, s10, 0x4000
	s_addc_u32 s23, s11, 0
	s_cmpk_eq_i32 s86, 0x54
	s_cselect_b32 s42, s48, s22
	s_cselect_b32 s43, s49, s23
	s_cselect_b32 s34, s50, s84
	s_cselect_b32 s35, s51, s85
	s_add_u32 s22, s42, 0x8000
	s_addc_u32 s23, s43, 0
	s_add_i32 s87, 0, 0x10000
	v_add_u32_e32 v0, s87, v154
	s_add_i32 s90, 0, 0x14000
	s_waitcnt lgkmcnt(0)
	ds_read_b128 v[132:135], v0
	ds_read_b128 v[148:151], v0 offset:1024
	ds_read_b128 v[156:159], v0 offset:2048
	ds_read_b128 v[160:163], v0 offset:3072
	v_add_u32_e32 v0, s90, v154
	ds_read_b128 v[164:167], v0
	ds_read_b128 v[168:171], v0 offset:1024
	ds_read_b128 v[172:175], v0 offset:2048
	ds_read_b128 v[176:179], v0 offset:3072
	s_add_i32 m0, s57, 0xc000
	ds_read_b128 v[180:183], v155
	ds_read_b128 v[184:187], v155 offset:1024
	ds_read_b128 v[188:191], v155 offset:2048
	ds_read_b128 v[192:195], v155 offset:3072
	ds_read_b128 v[196:199], v155 offset:4096
	ds_read_b128 v[214:217], v155 offset:5120
	ds_read_b128 v[218:221], v155 offset:6144

; #define PG8_STAGE(bufoff, gbase, voff) do { _Pragma("unroll") for (int _i = 0; _i < 2; ++_i) \
;         __builtin_amdgcn_global_load_lds((const unsigned*)((const char*)(gbase) + (voff)[_i]), (LAS unsigned*)(lds + (bufoff) + ldsw + _i * 8192), 16, 0, 0); } while (0)
; #define PG8_LDA(dst, b, h) do { _Pragma("unroll") for (int m = 0; m < 4; ++m) _Pragma("unroll") for (int k = 0; k < 2; ++k) dst[m][k] = *(const LAS bf16x8*)(lds + PG8_SA(b, h) + aoff + m * 2048 + k * 1024); } while (0)
; #define PG8_LDB(dst, b, h) do { _Pragma("unroll") for (int n = 0; n < 2; ++n) _Pragma("unroll") for (int k = 0; k < 2; ++k) dst[n][k] = *(const LAS bf16x8*)(lds + PG8_SB(b, h) + boff + n * 2048 + k * 1024); } while (0)
; #define PG8_MMA(ai, bj, At, Bt) do { __builtin_amdgcn_s_setprio(1); _Pragma("unroll") for (int m = 0; m < 4; ++m) _Pragma("unroll") for (int n = 0; n < 2; ++n) _Pragma("unroll") for (int k = 0; k < 2; ++k) \
;         acc[ai][bj][m][n] = __builtin_amdgcn_mfma_f32_16x16x32_bf16(Bt[n][k], At[m][k], acc[ai][bj][m][n], 0, 0, 0); __builtin_amdgcn_s_setprio(0); } while (0)
; #define PG8_WAIT_V(n) asm volatile("s_waitcnt vmcnt(" #n ")" ::: "memory")
; #define PG8_WAIT_L(n) asm volatile("s_waitcnt lgkmcnt(" #n ")" ::: "memory")
; #define PG8_BAR __builtin_amdgcn_s_barrier()
; #define PG8_SCHED __builtin_amdgcn_sched_barrier(0)
; template <class Epi, bool ALIGN_EPI>
; __device__ __forceinline__ void gemm_phase(LAS unsigned char* lds, const Gemm g, const StaticOrder& S, const Epi& E, const int tid) {
;     ...
;             PG8_LDB(B0, 0, 0); PG8_LDB(B1, 0, 1); PG8_SCHED; PG8_LDA(At, 0, 0); PG8_STAGE(PG8_SA(1, 1), a1 + hstepA, voffA);
;             PG8_WAIT_V(8); PG8_WAIT_L(0); PG8_BAR; PG8_MMA(0, 0, At, B0); PG8_MMA(0, 1, At, B1); PG8_BAR; PG8_SCHED;
	global_load_lds_dwordx4 v144, s[10:11]
	s_add_i32 m0, s57, 0xe000
	ds_read_b128 v[222:225], v155 offset:7168
	global_load_lds_dwordx4 v146, s[10:11]
	s_waitcnt vmcnt(8)
	s_waitcnt lgkmcnt(0)
	s_barrier


; #define PG8_MMA(ai, bj, At, Bt) do { __builtin_amdgcn_s_setprio(1); _Pragma("unroll") for (int m = 0; m < 4; ++m) _Pragma("unroll") for (int n = 0; n < 2; ++n) _Pragma("unroll") for (int k = 0; k < 2; ++k) \
;         acc[ai][bj][m][n] = __builtin_amdgcn_mfma_f32_16x16x32_bf16(Bt[n][k], At[m][k], acc[ai][bj][m][n], 0, 0, 0); __builtin_amdgcn_s_setprio(0); } while (0)
; #define PG8_WAIT_V(n) asm volatile("s_waitcnt vmcnt(" #n ")" ::: "memory")
; #define PG8_WAIT_L(n) asm volatile("s_waitcnt lgkmcnt(" #n ")" ::: "memory")
; #define PG8_BAR __builtin_amdgcn_s_barrier()
; #define PG8_SCHED __builtin_amdgcn_sched_barrier(0)
; template <class Epi, bool ALIGN_EPI>
; __device__ __forceinline__ void gemm_phase(LAS unsigned char* lds, const Gemm g, const StaticOrder& S, const Epi& E, const int tid) {
;     ...
;             PG8_WAIT_V(8); PG8_WAIT_L(0); PG8_BAR; PG8_MMA(0, 0, At, B0); PG8_MMA(0, 1, At, B1); PG8_BAR; PG8_SCHED;
	v_mfma_f32_16x16x32_bf16 v[8:11], v[132:135], v[180:183], v[8:11]
	v_mfma_f32_16x16x32_bf16 v[8:11], v[148:151], v[184:187], v[8:11]
	v_mfma_f32_16x16x32_bf16 v[56:59], v[160:163], v[184:187], v[56:59]
	v_mfma_f32_16x16x32_bf16 v[56:59], v[156:159], v[180:183], v[56:59]
	v_mfma_f32_16x16x32_bf16 v[28:31], v[172:175], v[180:183], v[28:31]
	v_mfma_f32_16x16x32_bf16 v[28:31], v[176:179], v[184:187], v[28:31]
	v_mfma_f32_16x16x32_bf16 v[2:5], v[164:167], v[180:183], v[4:7]
	v_mfma_f32_16x16x32_bf16 v[2:5], v[168:171], v[184:187], v[2:5]
	v_mfma_f32_16x16x32_bf16 v[96:99], v[168:171], v[192:195], v[96:99]
	v_mfma_f32_16x16x32_bf16 v[96:99], v[164:167], v[188:191], v[96:99]
	v_mfma_f32_16x16x32_bf16 v[92:95], v[172:175], v[188:191], v[92:95]
	v_mfma_f32_16x16x32_bf16 v[92:95], v[176:179], v[192:195], v[92:95]
	v_mfma_f32_16x16x32_bf16 v[48:51], v[160:163], v[192:195], v[48:51]
	v_mfma_f32_16x16x32_bf16 v[48:51], v[156:159], v[188:191], v[48:51]
	v_mfma_f32_16x16x32_bf16 v[52:55], v[132:135], v[188:191], v[52:55]
	v_mfma_f32_16x16x32_bf16 v[52:55], v[148:151], v[192:195], v[52:55]


; #define PG8_MMA(ai, bj, At, Bt) do { __builtin_amdgcn_s_setprio(1); _Pragma("unroll") for (int m = 0; m < 4; ++m) _Pragma("unroll") for (int n = 0; n < 2; ++n) _Pragma("unroll") for (int k = 0; k < 2; ++k) \
;         acc[ai][bj][m][n] = __builtin_amdgcn_mfma_f32_16x16x32_bf16(Bt[n][k], At[m][k], acc[ai][bj][m][n], 0, 0, 0); __builtin_amdgcn_s_setprio(0); } while (0)
; #define PG8_WAIT_V(n) asm volatile("s_waitcnt vmcnt(" #n ")" ::: "memory")
; #define PG8_WAIT_L(n) asm volatile("s_waitcnt lgkmcnt(" #n ")" ::: "memory")
; #define PG8_BAR __builtin_amdgcn_s_barrier()
; #define PG8_SCHED __builtin_amdgcn_sched_barrier(0)
; template <class Epi, bool ALIGN_EPI>
; __device__ __forceinline__ void gemm_phase(LAS unsigned char* lds, const Gemm g, const StaticOrder& S, const Epi& E, const int tid) {
;     ...
;             PG8_WAIT_V(8); PG8_WAIT_L(0); PG8_BAR; PG8_MMA(0, 0, At, B0); PG8_MMA(0, 1, At, B1); PG8_BAR; PG8_SCHED;
	v_mfma_f32_16x16x32_bf16 v[44:47], v[148:151], v[214:217], v[44:47]
	v_mfma_f32_16x16x32_bf16 v[44:47], v[132:135], v[196:199], v[44:47]
	v_mfma_f32_16x16x32_bf16 v[40:43], v[156:159], v[196:199], v[40:43]
	v_mfma_f32_16x16x32_bf16 v[40:43], v[160:163], v[214:217], v[40:43]
	v_mfma_f32_16x16x32_bf16 v[84:87], v[176:179], v[214:217], v[84:87]
	v_mfma_f32_16x16x32_bf16 v[84:87], v[172:175], v[196:199], v[84:87]
	v_mfma_f32_16x16x32_bf16 v[88:91], v[164:167], v[196:199], v[88:91]
	v_mfma_f32_16x16x32_bf16 v[88:91], v[168:171], v[214:217], v[88:91]
	v_mfma_f32_16x16x32_bf16 v[80:83], v[168:171], v[222:225], v[80:83]
	v_mfma_f32_16x16x32_bf16 v[80:83], v[164:167], v[218:221], v[80:83]
	v_mfma_f32_16x16x32_bf16 v[76:79], v[172:175], v[218:221], v[76:79]
	v_mfma_f32_16x16x32_bf16 v[76:79], v[176:179], v[222:225], v[76:79]
	v_mfma_f32_16x16x32_bf16 v[32:35], v[160:163], v[222:225], v[32:35]
	v_mfma_f32_16x16x32_bf16 v[32:35], v[156:159], v[218:221], v[32:35]
	v_mfma_f32_16x16x32_bf16 v[36:39], v[132:135], v[218:221], v[36:39]
	v_mfma_f32_16x16x32_bf16 v[36:39], v[148:151], v[222:225], v[36:39]

; #define PG8_STAGE(bufoff, gbase, voff) do { _Pragma("unroll") for (int _i = 0; _i < 2; ++_i) \
;         __builtin_amdgcn_global_load_lds((const unsigned*)((const char*)(gbase) + (voff)[_i]), (LAS unsigned*)(lds + (bufoff) + ldsw + _i * 8192), 16, 0, 0); } while (0)
; #define PG8_LDA(dst, b, h) do { _Pragma("unroll") for (int m = 0; m < 4; ++m) _Pragma("unroll") for (int k = 0; k < 2; ++k) dst[m][k] = *(const LAS bf16x8*)(lds + PG8_SA(b, h) + aoff + m * 2048 + k * 1024); } while (0)
; #define PG8_MMA(ai, bj, At, Bt) do { __builtin_amdgcn_s_setprio(1); _Pragma("unroll") for (int m = 0; m < 4; ++m) _Pragma("unroll") for (int n = 0; n < 2; ++n) _Pragma("unroll") for (int k = 0; k < 2; ++k) \
;         acc[ai][bj][m][n] = __builtin_amdgcn_mfma_f32_16x16x32_bf16(Bt[n][k], At[m][k], acc[ai][bj][m][n], 0, 0, 0); __builtin_amdgcn_s_setprio(0); } while (0)
; #define PG8_WAIT_V(n) asm volatile("s_waitcnt vmcnt(" #n ")" ::: "memory")
; #define PG8_WAIT_L(n) asm volatile("s_waitcnt lgkmcnt(" #n ")" ::: "memory")
; #define PG8_BAR __builtin_amdgcn_s_barrier()
; #define PG8_SCHED __builtin_amdgcn_sched_barrier(0)
; template <class Epi, bool ALIGN_EPI>
; __device__ __forceinline__ void gemm_phase(LAS unsigned char* lds, const Gemm g, const StaticOrder& S, const Epi& E, const int tid) {
;     ...
;             PG8_WAIT_V(8); PG8_WAIT_L(0); PG8_BAR; PG8_MMA(0, 0, At, B0); PG8_MMA(0, 1, At, B1); PG8_BAR; PG8_SCHED;
;             PG8_LDA(At, 0, 1); PG8_STAGE(PG8_SB(0, 0), b2, voffB); PG8_STAGE(PG8_SB(0, 1), b2 + hstepB, voffB); PG8_STAGE(PG8_SA(0, 0), a2, voffA);
	s_barrier
	s_add_i32 s87, s87, s56
	s_mov_b32 m0, s87
	ds_read_b128 v[180:183], v155 offset:16384
	ds_read_b128 v[184:187], v155 offset:17408
	ds_read_b128 v[188:191], v155 offset:18432
	ds_read_b128 v[192:195], v155 offset:19456


; #define PG8_STAGE(bufoff, gbase, voff) do { _Pragma("unroll") for (int _i = 0; _i < 2; ++_i) \
;         __builtin_amdgcn_global_load_lds((const unsigned*)((const char*)(gbase) + (voff)[_i]), (LAS unsigned*)(lds + (bufoff) + ldsw + _i * 8192), 16, 0, 0); } while (0)
; #define PG8_LDA(dst, b, h) do { _Pragma("unroll") for (int m = 0; m < 4; ++m) _Pragma("unroll") for (int k = 0; k < 2; ++k) dst[m][k] = *(const LAS bf16x8*)(lds + PG8_SA(b, h) + aoff + m * 2048 + k * 1024); } while (0)
; #define PG8_MMA(ai, bj, At, Bt) do { __builtin_amdgcn_s_setprio(1); _Pragma("unroll") for (int m = 0; m < 4; ++m) _Pragma("unroll") for (int n = 0; n < 2; ++n) _Pragma("unroll") for (int k = 0; k < 2; ++k) \
;         acc[ai][bj][m][n] = __builtin_amdgcn_mfma_f32_16x16x32_bf16(Bt[n][k], At[m][k], acc[ai][bj][m][n], 0, 0, 0); __builtin_amdgcn_s_setprio(0); } while (0)
; #define PG8_WAIT_V(n) asm volatile("s_waitcnt vmcnt(" #n ")" ::: "memory")
; #define PG8_WAIT_L(n) asm volatile("s_waitcnt lgkmcnt(" #n ")" ::: "memory")
; #define PG8_BAR __builtin_amdgcn_s_barrier()
; #define PG8_SCHED __builtin_amdgcn_sched_barrier(0)
; template <class Epi, bool ALIGN_EPI>
; __device__ __forceinline__ void gemm_phase(LAS unsigned char* lds, const Gemm g, const StaticOrder& S, const Epi& E, const int tid) {
;     ...
;             PG8_LDA(At, 0, 1); PG8_STAGE(PG8_SB(0, 0), b2, voffB); PG8_STAGE(PG8_SB(0, 1), b2 + hstepB, voffB); PG8_STAGE(PG8_SA(0, 0), a2, voffA);
;             PG8_WAIT_V(8); PG8_WAIT_L(0); PG8_BAR; PG8_MMA(1, 0, At, B0); PG8_MMA(1, 1, At, B1); PG8_BAR; PG8_SCHED;
	global_load_lds_dwordx4 v140, s[34:35]
	s_add_i32 m0, s87, 0x2000
	s_add_u32 s88, s34, 0x4000
	s_addc_u32 s89, s35, 0
	s_add_i32 s87, s90, s56
	global_load_lds_dwordx4 v136, s[34:35]
	s_mov_b32 m0, s87
	ds_read_b128 v[222:225], v155 offset:23552
	global_load_lds_dwordx4 v140, s[88:89]
	s_add_i32 m0, s87, 0x2000
	ds_read_b128 v[218:221], v155 offset:22528
	global_load_lds_dwordx4 v136, s[88:89]
	s_mov_b32 m0, s57
	ds_read_b128 v[214:217], v155 offset:21504
	global_load_lds_dwordx4 v142, s[42:43]
	s_mov_b32 m0, s60
	ds_read_b128 v[196:199], v155 offset:20480
	global_load_lds_dwordx4 v138, s[42:43]
	s_waitcnt vmcnt(8)
	s_waitcnt lgkmcnt(0)
	s_barrier


; #define PG8_MMA(ai, bj, At, Bt) do { __builtin_amdgcn_s_setprio(1); _Pragma("unroll") for (int m = 0; m < 4; ++m) _Pragma("unroll") for (int n = 0; n < 2; ++n) _Pragma("unroll") for (int k = 0; k < 2; ++k) \
;         acc[ai][bj][m][n] = __builtin_amdgcn_mfma_f32_16x16x32_bf16(Bt[n][k], At[m][k], acc[ai][bj][m][n], 0, 0, 0); __builtin_amdgcn_s_setprio(0); } while (0)
; #define PG8_WAIT_V(n) asm volatile("s_waitcnt vmcnt(" #n ")" ::: "memory")
; #define PG8_WAIT_L(n) asm volatile("s_waitcnt lgkmcnt(" #n ")" ::: "memory")
; #define PG8_BAR __builtin_amdgcn_s_barrier()
; #define PG8_SCHED __builtin_amdgcn_sched_barrier(0)
; template <class Epi, bool ALIGN_EPI>
; __device__ __forceinline__ void gemm_phase(LAS unsigned char* lds, const Gemm g, const StaticOrder& S, const Epi& E, const int tid) {
;     ...
;             PG8_WAIT_V(8); PG8_WAIT_L(0); PG8_BAR; PG8_MMA(1, 0, At, B0); PG8_MMA(1, 1, At, B1); PG8_BAR; PG8_SCHED;
	v_mfma_f32_16x16x32_bf16 v[24:27], v[132:135], v[180:183], v[24:27]
	v_mfma_f32_16x16x32_bf16 v[24:27], v[148:151], v[184:187], v[24:27]
	v_mfma_f32_16x16x32_bf16 v[20:23], v[160:163], v[184:187], v[20:23]
	v_mfma_f32_16x16x32_bf16 v[20:23], v[156:159], v[180:183], v[20:23]
	v_mfma_f32_16x16x32_bf16 v[124:127], v[172:175], v[180:183], v[124:127]
	v_mfma_f32_16x16x32_bf16 v[124:127], v[176:179], v[184:187], v[124:127]
	v_mfma_f32_16x16x32_bf16 v[128:131], v[168:171], v[184:187], v[128:131]
	v_mfma_f32_16x16x32_bf16 v[128:131], v[164:167], v[180:183], v[128:131]
	v_mfma_f32_16x16x32_bf16 v[120:123], v[164:167], v[188:191], v[120:123]
	v_mfma_f32_16x16x32_bf16 v[120:123], v[168:171], v[192:195], v[120:123]
	v_mfma_f32_16x16x32_bf16 v[116:119], v[176:179], v[192:195], v[116:119]
	v_mfma_f32_16x16x32_bf16 v[116:119], v[172:175], v[188:191], v[116:119]
	v_mfma_f32_16x16x32_bf16 v[72:75], v[156:159], v[188:191], v[72:75]
	v_mfma_f32_16x16x32_bf16 v[72:75], v[160:163], v[192:195], v[72:75]
	v_mfma_f32_16x16x32_bf16 v[64:67], v[148:151], v[192:195], v[64:67]
	v_mfma_f32_16x16x32_bf16 v[64:67], v[132:135], v[188:191], v[64:67]


; #define PG8_MMA(ai, bj, At, Bt) do { __builtin_amdgcn_s_setprio(1); _Pragma("unroll") for (int m = 0; m < 4; ++m) _Pragma("unroll") for (int n = 0; n < 2; ++n) _Pragma("unroll") for (int k = 0; k < 2; ++k) \
;         acc[ai][bj][m][n] = __builtin_amdgcn_mfma_f32_16x16x32_bf16(Bt[n][k], At[m][k], acc[ai][bj][m][n], 0, 0, 0); __builtin_amdgcn_s_setprio(0); } while (0)
; #define PG8_WAIT_V(n) asm volatile("s_waitcnt vmcnt(" #n ")" ::: "memory")
; #define PG8_WAIT_L(n) asm volatile("s_waitcnt lgkmcnt(" #n ")" ::: "memory")
; #define PG8_BAR __builtin_amdgcn_s_barrier()
; #define PG8_SCHED __builtin_amdgcn_sched_barrier(0)
; template <class Epi, bool ALIGN_EPI>
; __device__ __forceinline__ void gemm_phase(LAS unsigned char* lds, const Gemm g, const StaticOrder& S, const Epi& E, const int tid) {
;     ...
;             PG8_WAIT_V(8); PG8_WAIT_L(0); PG8_BAR; PG8_MMA(1, 0, At, B0); PG8_MMA(1, 1, At, B1); PG8_BAR; PG8_SCHED;
	v_mfma_f32_16x16x32_bf16 v[16:19], v[132:135], v[196:199], v[16:19]
	v_mfma_f32_16x16x32_bf16 v[16:19], v[148:151], v[214:217], v[16:19]
	v_mfma_f32_16x16x32_bf16 v[12:15], v[160:163], v[214:217], v[12:15]
	v_mfma_f32_16x16x32_bf16 v[12:15], v[156:159], v[196:199], v[12:15]
	v_mfma_f32_16x16x32_bf16 v[108:111], v[172:175], v[196:199], v[108:111]
	v_mfma_f32_16x16x32_bf16 v[108:111], v[176:179], v[214:217], v[108:111]
	v_mfma_f32_16x16x32_bf16 v[112:115], v[168:171], v[214:217], v[112:115]
	v_mfma_f32_16x16x32_bf16 v[112:115], v[164:167], v[196:199], v[112:115]
	v_mfma_f32_16x16x32_bf16 v[104:107], v[164:167], v[218:221], v[104:107]
	v_mfma_f32_16x16x32_bf16 v[104:107], v[168:171], v[222:225], v[104:107]
	v_mfma_f32_16x16x32_bf16 v[100:103], v[176:179], v[222:225], v[100:103]
	v_mfma_f32_16x16x32_bf16 v[100:103], v[172:175], v[218:221], v[100:103]
	v_mfma_f32_16x16x32_bf16 v[68:71], v[156:159], v[218:221], v[68:71]
	v_mfma_f32_16x16x32_bf16 v[68:71], v[160:163], v[222:225], v[68:71]
	v_mfma_f32_16x16x32_bf16 v[60:63], v[148:151], v[222:225], v[60:63]
	v_mfma_f32_16x16x32_bf16 v[60:63], v[132:135], v[218:221], v[60:63]

; #define PG8_STAGE(bufoff, gbase, voff) do { _Pragma("unroll") for (int _i = 0; _i < 2; ++_i) \
;         __builtin_amdgcn_global_load_lds((const unsigned*)((const char*)(gbase) + (voff)[_i]), (LAS unsigned*)(lds + (bufoff) + ldsw + _i * 8192), 16, 0, 0); } while (0)
; #define PG8_LDA(dst, b, h) do { _Pragma("unroll") for (int m = 0; m < 4; ++m) _Pragma("unroll") for (int k = 0; k < 2; ++k) dst[m][k] = *(const LAS bf16x8*)(lds + PG8_SA(b, h) + aoff + m * 2048 + k * 1024); } while (0)
; #define PG8_LDB(dst, b, h) do { _Pragma("unroll") for (int n = 0; n < 2; ++n) _Pragma("unroll") for (int k = 0; k < 2; ++k) dst[n][k] = *(const LAS bf16x8*)(lds + PG8_SB(b, h) + boff + n * 2048 + k * 1024); } while (0)
; #define PG8_MMA(ai, bj, At, Bt) do { __builtin_amdgcn_s_setprio(1); _Pragma("unroll") for (int m = 0; m < 4; ++m) _Pragma("unroll") for (int n = 0; n < 2; ++n) _Pragma("unroll") for (int k = 0; k < 2; ++k) \
;         acc[ai][bj][m][n] = __builtin_amdgcn_mfma_f32_16x16x32_bf16(Bt[n][k], At[m][k], acc[ai][bj][m][n], 0, 0, 0); __builtin_amdgcn_s_setprio(0); } while (0)
; #define PG8_WAIT_V(n) asm volatile("s_waitcnt vmcnt(" #n ")" ::: "memory")
; #define PG8_WAIT_L(n) asm volatile("s_waitcnt lgkmcnt(" #n ")" ::: "memory")
; #define PG8_BAR __builtin_amdgcn_s_barrier()
; #define PG8_SCHED __builtin_amdgcn_sched_barrier(0)
; template <class Epi, bool ALIGN_EPI>
; __device__ __forceinline__ void gemm_phase(LAS unsigned char* lds, const Gemm g, const StaticOrder& S, const Epi& E, const int tid) {
;     ...
;             PG8_WAIT_V(8); PG8_WAIT_L(0); PG8_BAR; PG8_MMA(1, 0, At, B0); PG8_MMA(1, 1, At, B1); PG8_BAR; PG8_SCHED;
;             PG8_LDB(B0, 1, 0); PG8_LDB(B1, 1, 1); PG8_SCHED; PG8_LDA(At, 1, 0); PG8_STAGE(PG8_SA(0, 1), a2 + hstepA, voffA);
	s_barrier
	s_add_i32 s87, 0, 0x18000
	v_add_u32_e32 v0, s87, v154
	s_add_i32 s88, 0, 0x1c000
	ds_read_b128 v[132:135], v0
	ds_read_b128 v[148:151], v0 offset:1024
	ds_read_b128 v[156:159], v0 offset:2048
	ds_read_b128 v[160:163], v0 offset:3072
	v_add_u32_e32 v0, s88, v154
	ds_read_b128 v[164:167], v0
	ds_read_b128 v[168:171], v0 offset:1024
	ds_read_b128 v[172:175], v0 offset:2048
	ds_read_b128 v[176:179], v0 offset:3072
	s_add_u32 s42, s42, 0x4000
	s_addc_u32 s43, s43, 0
	s_mov_b32 m0, s61
	ds_read_b128 v[180:183], v155 offset:32768
	ds_read_b128 v[184:187], v155 offset:33792
	ds_read_b128 v[188:191], v155 offset:34816
	ds_read_b128 v[192:195], v155 offset:35840
	ds_read_b128 v[196:199], v155 offset:36864
	ds_read_b128 v[214:217], v155 offset:37888
	ds_read_b128 v[218:221], v155 offset:38912

; #define PG8_STAGE(bufoff, gbase, voff) do { _Pragma("unroll") for (int _i = 0; _i < 2; ++_i) \
;         __builtin_amdgcn_global_load_lds((const unsigned*)((const char*)(gbase) + (voff)[_i]), (LAS unsigned*)(lds + (bufoff) + ldsw + _i * 8192), 16, 0, 0); } while (0)
; #define PG8_LDA(dst, b, h) do { _Pragma("unroll") for (int m = 0; m < 4; ++m) _Pragma("unroll") for (int k = 0; k < 2; ++k) dst[m][k] = *(const LAS bf16x8*)(lds + PG8_SA(b, h) + aoff + m * 2048 + k * 1024); } while (0)
; #define PG8_LDB(dst, b, h) do { _Pragma("unroll") for (int n = 0; n < 2; ++n) _Pragma("unroll") for (int k = 0; k < 2; ++k) dst[n][k] = *(const LAS bf16x8*)(lds + PG8_SB(b, h) + boff + n * 2048 + k * 1024); } while (0)
; #define PG8_MMA(ai, bj, At, Bt) do { __builtin_amdgcn_s_setprio(1); _Pragma("unroll") for (int m = 0; m < 4; ++m) _Pragma("unroll") for (int n = 0; n < 2; ++n) _Pragma("unroll") for (int k = 0; k < 2; ++k) \
;         acc[ai][bj][m][n] = __builtin_amdgcn_mfma_f32_16x16x32_bf16(Bt[n][k], At[m][k], acc[ai][bj][m][n], 0, 0, 0); __builtin_amdgcn_s_setprio(0); } while (0)
; #define PG8_WAIT_V(n) asm volatile("s_waitcnt vmcnt(" #n ")" ::: "memory")
; #define PG8_WAIT_L(n) asm volatile("s_waitcnt lgkmcnt(" #n ")" ::: "memory")
; #define PG8_BAR __builtin_amdgcn_s_barrier()
; #define PG8_SCHED __builtin_amdgcn_sched_barrier(0)
; template <class Epi, bool ALIGN_EPI>
; __device__ __forceinline__ void gemm_phase(LAS unsigned char* lds, const Gemm g, const StaticOrder& S, const Epi& E, const int tid) {
;     ...
;             PG8_LDB(B0, 1, 0); PG8_LDB(B1, 1, 1); PG8_SCHED; PG8_LDA(At, 1, 0); PG8_STAGE(PG8_SA(0, 1), a2 + hstepA, voffA);
;             PG8_WAIT_V(8); PG8_WAIT_L(0); PG8_BAR; PG8_MMA(0, 0, At, B0); PG8_MMA(0, 1, At, B1); PG8_BAR; PG8_SCHED;
	global_load_lds_dwordx4 v142, s[42:43]
	s_mov_b32 m0, s71
	ds_read_b128 v[222:225], v155 offset:39936
	global_load_lds_dwordx4 v138, s[42:43]
	s_waitcnt vmcnt(8)
	s_waitcnt lgkmcnt(0)
	s_barrier


; #define PG8_MMA(ai, bj, At, Bt) do { __builtin_amdgcn_s_setprio(1); _Pragma("unroll") for (int m = 0; m < 4; ++m) _Pragma("unroll") for (int n = 0; n < 2; ++n) _Pragma("unroll") for (int k = 0; k < 2; ++k) \
;         acc[ai][bj][m][n] = __builtin_amdgcn_mfma_f32_16x16x32_bf16(Bt[n][k], At[m][k], acc[ai][bj][m][n], 0, 0, 0); __builtin_amdgcn_s_setprio(0); } while (0)
; #define PG8_WAIT_V(n) asm volatile("s_waitcnt vmcnt(" #n ")" ::: "memory")
; #define PG8_WAIT_L(n) asm volatile("s_waitcnt lgkmcnt(" #n ")" ::: "memory")
; #define PG8_BAR __builtin_amdgcn_s_barrier()
; #define PG8_SCHED __builtin_amdgcn_sched_barrier(0)
; template <class Epi, bool ALIGN_EPI>
; __device__ __forceinline__ void gemm_phase(LAS unsigned char* lds, const Gemm g, const StaticOrder& S, const Epi& E, const int tid) {
;     ...
;             PG8_WAIT_V(8); PG8_WAIT_L(0); PG8_BAR; PG8_MMA(0, 0, At, B0); PG8_MMA(0, 1, At, B1); PG8_BAR; PG8_SCHED;
	v_mfma_f32_16x16x32_bf16 v[6:9], v[132:135], v[180:183], v[8:11]
	v_mfma_f32_16x16x32_bf16 v[8:11], v[148:151], v[184:187], v[6:9]
	v_mfma_f32_16x16x32_bf16 v[56:59], v[160:163], v[184:187], v[56:59]
	v_mfma_f32_16x16x32_bf16 v[56:59], v[156:159], v[180:183], v[56:59]
	v_mfma_f32_16x16x32_bf16 v[28:31], v[172:175], v[180:183], v[28:31]
	v_mfma_f32_16x16x32_bf16 v[28:31], v[176:179], v[184:187], v[28:31]
	v_mfma_f32_16x16x32_bf16 v[2:5], v[164:167], v[180:183], v[2:5]
	v_mfma_f32_16x16x32_bf16 v[4:7], v[168:171], v[184:187], v[2:5]
	v_mfma_f32_16x16x32_bf16 v[96:99], v[168:171], v[192:195], v[96:99]
	v_mfma_f32_16x16x32_bf16 v[96:99], v[164:167], v[188:191], v[96:99]
	v_mfma_f32_16x16x32_bf16 v[92:95], v[172:175], v[188:191], v[92:95]
	v_mfma_f32_16x16x32_bf16 v[92:95], v[176:179], v[192:195], v[92:95]
	v_mfma_f32_16x16x32_bf16 v[48:51], v[160:163], v[192:195], v[48:51]
	v_mfma_f32_16x16x32_bf16 v[48:51], v[156:159], v[188:191], v[48:51]
	v_mfma_f32_16x16x32_bf16 v[52:55], v[132:135], v[188:191], v[52:55]
	v_mfma_f32_16x16x32_bf16 v[52:55], v[148:151], v[192:195], v[52:55]


; #define PG8_MMA(ai, bj, At, Bt) do { __builtin_amdgcn_s_setprio(1); _Pragma("unroll") for (int m = 0; m < 4; ++m) _Pragma("unroll") for (int n = 0; n < 2; ++n) _Pragma("unroll") for (int k = 0; k < 2; ++k) \
;         acc[ai][bj][m][n] = __builtin_amdgcn_mfma_f32_16x16x32_bf16(Bt[n][k], At[m][k], acc[ai][bj][m][n], 0, 0, 0); __builtin_amdgcn_s_setprio(0); } while (0)
; #define PG8_WAIT_V(n) asm volatile("s_waitcnt vmcnt(" #n ")" ::: "memory")
; #define PG8_WAIT_L(n) asm volatile("s_waitcnt lgkmcnt(" #n ")" ::: "memory")
; #define PG8_BAR __builtin_amdgcn_s_barrier()
; #define PG8_SCHED __builtin_amdgcn_sched_barrier(0)
; template <class Epi, bool ALIGN_EPI>
; __device__ __forceinline__ void gemm_phase(LAS unsigned char* lds, const Gemm g, const StaticOrder& S, const Epi& E, const int tid) {
;     ...
;             PG8_WAIT_V(8); PG8_WAIT_L(0); PG8_BAR; PG8_MMA(0, 0, At, B0); PG8_MMA(0, 1, At, B1); PG8_BAR; PG8_SCHED;
	v_mfma_f32_16x16x32_bf16 v[44:47], v[148:151], v[214:217], v[44:47]
	v_mfma_f32_16x16x32_bf16 v[44:47], v[132:135], v[196:199], v[44:47]
	v_mfma_f32_16x16x32_bf16 v[40:43], v[156:159], v[196:199], v[40:43]
	v_mfma_f32_16x16x32_bf16 v[40:43], v[160:163], v[214:217], v[40:43]
	v_mfma_f32_16x16x32_bf16 v[84:87], v[176:179], v[214:217], v[84:87]
	v_mfma_f32_16x16x32_bf16 v[84:87], v[172:175], v[196:199], v[84:87]
	v_mfma_f32_16x16x32_bf16 v[88:91], v[164:167], v[196:199], v[88:91]
	v_mfma_f32_16x16x32_bf16 v[88:91], v[168:171], v[214:217], v[88:91]
	v_mfma_f32_16x16x32_bf16 v[80:83], v[168:171], v[222:225], v[80:83]
	v_mfma_f32_16x16x32_bf16 v[80:83], v[164:167], v[218:221], v[80:83]
	v_mfma_f32_16x16x32_bf16 v[76:79], v[172:175], v[218:221], v[76:79]
	v_mfma_f32_16x16x32_bf16 v[76:79], v[176:179], v[222:225], v[76:79]
	v_mfma_f32_16x16x32_bf16 v[32:35], v[160:163], v[222:225], v[32:35]
	v_mfma_f32_16x16x32_bf16 v[32:35], v[156:159], v[218:221], v[32:35]
	v_mfma_f32_16x16x32_bf16 v[36:39], v[132:135], v[218:221], v[36:39]
	v_mfma_f32_16x16x32_bf16 v[36:39], v[148:151], v[222:225], v[36:39]

; #define PG8_STAGE(bufoff, gbase, voff) do { _Pragma("unroll") for (int _i = 0; _i < 2; ++_i) \
;         __builtin_amdgcn_global_load_lds((const unsigned*)((const char*)(gbase) + (voff)[_i]), (LAS unsigned*)(lds + (bufoff) + ldsw + _i * 8192), 16, 0, 0); } while (0)
; #define PG8_LDA(dst, b, h) do { _Pragma("unroll") for (int m = 0; m < 4; ++m) _Pragma("unroll") for (int k = 0; k < 2; ++k) dst[m][k] = *(const LAS bf16x8*)(lds + PG8_SA(b, h) + aoff + m * 2048 + k * 1024); } while (0)
; #define PG8_MMA(ai, bj, At, Bt) do { __builtin_amdgcn_s_setprio(1); _Pragma("unroll") for (int m = 0; m < 4; ++m) _Pragma("unroll") for (int n = 0; n < 2; ++n) _Pragma("unroll") for (int k = 0; k < 2; ++k) \
;         acc[ai][bj][m][n] = __builtin_amdgcn_mfma_f32_16x16x32_bf16(Bt[n][k], At[m][k], acc[ai][bj][m][n], 0, 0, 0); __builtin_amdgcn_s_setprio(0); } while (0)
; #define PG8_WAIT_V(n) asm volatile("s_waitcnt vmcnt(" #n ")" ::: "memory")
; #define PG8_WAIT_L(n) asm volatile("s_waitcnt lgkmcnt(" #n ")" ::: "memory")
; #define PG8_BAR __builtin_amdgcn_s_barrier()
; #define PG8_SCHED __builtin_amdgcn_sched_barrier(0)
; template <class Epi, bool ALIGN_EPI>
; __device__ __forceinline__ void gemm_phase(LAS unsigned char* lds, const Gemm g, const StaticOrder& S, const Epi& E, const int tid) {
;     ...
;             PG8_WAIT_V(8); PG8_WAIT_L(0); PG8_BAR; PG8_MMA(0, 0, At, B0); PG8_MMA(0, 1, At, B1); PG8_BAR; PG8_SCHED;
;             PG8_LDA(At, 1, 1); PG8_STAGE(PG8_SB(1, 0), b3, voffB); PG8_STAGE(PG8_SB(1, 1), b3 + hstepB, voffB); PG8_STAGE(PG8_SA(1, 0), a3, voffA);
	s_barrier
	s_add_u32 s42, s34, 0x8000
	s_addc_u32 s43, s35, 0
	s_add_i32 s87, s87, s56
	s_mov_b32 m0, s87
	ds_read_b128 v[180:183], v155 offset:49152
	ds_read_b128 v[184:187], v155 offset:50176
	ds_read_b128 v[188:191], v155 offset:51200
	ds_read_b128 v[192:195], v155 offset:52224


; #define PG8_STAGE(bufoff, gbase, voff) do { _Pragma("unroll") for (int _i = 0; _i < 2; ++_i) \
;         __builtin_amdgcn_global_load_lds((const unsigned*)((const char*)(gbase) + (voff)[_i]), (LAS unsigned*)(lds + (bufoff) + ldsw + _i * 8192), 16, 0, 0); } while (0)
; #define PG8_LDA(dst, b, h) do { _Pragma("unroll") for (int m = 0; m < 4; ++m) _Pragma("unroll") for (int k = 0; k < 2; ++k) dst[m][k] = *(const LAS bf16x8*)(lds + PG8_SA(b, h) + aoff + m * 2048 + k * 1024); } while (0)
; #define PG8_MMA(ai, bj, At, Bt) do { __builtin_amdgcn_s_setprio(1); _Pragma("unroll") for (int m = 0; m < 4; ++m) _Pragma("unroll") for (int n = 0; n < 2; ++n) _Pragma("unroll") for (int k = 0; k < 2; ++k) \
;         acc[ai][bj][m][n] = __builtin_amdgcn_mfma_f32_16x16x32_bf16(Bt[n][k], At[m][k], acc[ai][bj][m][n], 0, 0, 0); __builtin_amdgcn_s_setprio(0); } while (0)
; #define PG8_WAIT_V(n) asm volatile("s_waitcnt vmcnt(" #n ")" ::: "memory")
; #define PG8_WAIT_L(n) asm volatile("s_waitcnt lgkmcnt(" #n ")" ::: "memory")
; #define PG8_BAR __builtin_amdgcn_s_barrier()
; #define PG8_SCHED __builtin_amdgcn_sched_barrier(0)
; template <class Epi, bool ALIGN_EPI>
; __device__ __forceinline__ void gemm_phase(LAS unsigned char* lds, const Gemm g, const StaticOrder& S, const Epi& E, const int tid) {
;     ...
;             PG8_LDA(At, 1, 1); PG8_STAGE(PG8_SB(1, 0), b3, voffB); PG8_STAGE(PG8_SB(1, 1), b3 + hstepB, voffB); PG8_STAGE(PG8_SA(1, 0), a3, voffA);
;             PG8_WAIT_V(8); PG8_WAIT_L(0); PG8_BAR; PG8_MMA(1, 0, At, B0); PG8_MMA(1, 1, At, B1); PG8_BAR; PG8_SCHED;
	global_load_lds_dwordx4 v140, s[42:43]
	s_add_i32 m0, s87, 0x2000
	s_add_u32 s34, s34, 0xc000
	s_addc_u32 s35, s35, 0
	global_load_lds_dwordx4 v136, s[42:43]
	s_add_i32 s42, s88, s56
	s_mov_b32 m0, s42
	ds_read_b128 v[222:225], v155 offset:56320
	global_load_lds_dwordx4 v140, s[34:35]
	s_add_i32 m0, s42, 0x2000
	ds_read_b128 v[218:221], v155 offset:55296
	global_load_lds_dwordx4 v136, s[34:35]
	s_mov_b32 m0, s76
	ds_read_b128 v[214:217], v155 offset:54272
	global_load_lds_dwordx4 v142, s[22:23]
	s_mov_b32 m0, s77
	ds_read_b128 v[196:199], v155 offset:53248
	global_load_lds_dwordx4 v138, s[22:23]
	s_waitcnt vmcnt(8)
	s_waitcnt lgkmcnt(0)
	s_barrier


; #define PG8_MMA(ai, bj, At, Bt) do { __builtin_amdgcn_s_setprio(1); _Pragma("unroll") for (int m = 0; m < 4; ++m) _Pragma("unroll") for (int n = 0; n < 2; ++n) _Pragma("unroll") for (int k = 0; k < 2; ++k) \
;         acc[ai][bj][m][n] = __builtin_amdgcn_mfma_f32_16x16x32_bf16(Bt[n][k], At[m][k], acc[ai][bj][m][n], 0, 0, 0); __builtin_amdgcn_s_setprio(0); } while (0)
; #define PG8_WAIT_V(n) asm volatile("s_waitcnt vmcnt(" #n ")" ::: "memory")
; #define PG8_WAIT_L(n) asm volatile("s_waitcnt lgkmcnt(" #n ")" ::: "memory")
; #define PG8_BAR __builtin_amdgcn_s_barrier()
; #define PG8_SCHED __builtin_amdgcn_sched_barrier(0)
; template <class Epi, bool ALIGN_EPI>
; __device__ __forceinline__ void gemm_phase(LAS unsigned char* lds, const Gemm g, const StaticOrder& S, const Epi& E, const int tid) {
;     ...
;             PG8_WAIT_V(8); PG8_WAIT_L(0); PG8_BAR; PG8_MMA(1, 0, At, B0); PG8_MMA(1, 1, At, B1); PG8_BAR; PG8_SCHED;
	v_mfma_f32_16x16x32_bf16 v[24:27], v[132:135], v[180:183], v[24:27]
	v_mfma_f32_16x16x32_bf16 v[24:27], v[148:151], v[184:187], v[24:27]
	v_mfma_f32_16x16x32_bf16 v[20:23], v[160:163], v[184:187], v[20:23]
	v_mfma_f32_16x16x32_bf16 v[20:23], v[156:159], v[180:183], v[20:23]
	v_mfma_f32_16x16x32_bf16 v[124:127], v[172:175], v[180:183], v[124:127]
	v_mfma_f32_16x16x32_bf16 v[124:127], v[176:179], v[184:187], v[124:127]
	v_mfma_f32_16x16x32_bf16 v[128:131], v[168:171], v[184:187], v[128:131]
	v_mfma_f32_16x16x32_bf16 v[128:131], v[164:167], v[180:183], v[128:131]
	v_mfma_f32_16x16x32_bf16 v[120:123], v[164:167], v[188:191], v[120:123]
	v_mfma_f32_16x16x32_bf16 v[120:123], v[168:171], v[192:195], v[120:123]
	v_mfma_f32_16x16x32_bf16 v[116:119], v[176:179], v[192:195], v[116:119]
	v_mfma_f32_16x16x32_bf16 v[116:119], v[172:175], v[188:191], v[116:119]
	v_mfma_f32_16x16x32_bf16 v[72:75], v[156:159], v[188:191], v[72:75]
	v_mfma_f32_16x16x32_bf16 v[72:75], v[160:163], v[192:195], v[72:75]
	v_mfma_f32_16x16x32_bf16 v[64:67], v[148:151], v[192:195], v[64:67]
	v_mfma_f32_16x16x32_bf16 v[64:67], v[132:135], v[188:191], v[64:67]


; #define PG8_MMA(ai, bj, At, Bt) do { __builtin_amdgcn_s_setprio(1); _Pragma("unroll") for (int m = 0; m < 4; ++m) _Pragma("unroll") for (int n = 0; n < 2; ++n) _Pragma("unroll") for (int k = 0; k < 2; ++k) \
;         acc[ai][bj][m][n] = __builtin_amdgcn_mfma_f32_16x16x32_bf16(Bt[n][k], At[m][k], acc[ai][bj][m][n], 0, 0, 0); __builtin_amdgcn_s_setprio(0); } while (0)
; #define PG8_WAIT_V(n) asm volatile("s_waitcnt vmcnt(" #n ")" ::: "memory")
; #define PG8_WAIT_L(n) asm volatile("s_waitcnt lgkmcnt(" #n ")" ::: "memory")
; #define PG8_BAR __builtin_amdgcn_s_barrier()
; #define PG8_SCHED __builtin_amdgcn_sched_barrier(0)
; template <class Epi, bool ALIGN_EPI>
; __device__ __forceinline__ void gemm_phase(LAS unsigned char* lds, const Gemm g, const StaticOrder& S, const Epi& E, const int tid) {
;     ...
;             PG8_WAIT_V(8); PG8_WAIT_L(0); PG8_BAR; PG8_MMA(1, 0, At, B0); PG8_MMA(1, 1, At, B1); PG8_BAR; PG8_SCHED;
	v_mfma_f32_16x16x32_bf16 v[16:19], v[132:135], v[196:199], v[16:19]
	v_mfma_f32_16x16x32_bf16 v[16:19], v[148:151], v[214:217], v[16:19]
	v_mfma_f32_16x16x32_bf16 v[12:15], v[160:163], v[214:217], v[12:15]
	v_mfma_f32_16x16x32_bf16 v[12:15], v[156:159], v[196:199], v[12:15]
	v_mfma_f32_16x16x32_bf16 v[108:111], v[172:175], v[196:199], v[108:111]
	v_mfma_f32_16x16x32_bf16 v[108:111], v[176:179], v[214:217], v[108:111]
	v_mfma_f32_16x16x32_bf16 v[112:115], v[168:171], v[214:217], v[112:115]
	v_mfma_f32_16x16x32_bf16 v[112:115], v[164:167], v[196:199], v[112:115]
	v_mfma_f32_16x16x32_bf16 v[104:107], v[164:167], v[218:221], v[104:107]
	v_mfma_f32_16x16x32_bf16 v[104:107], v[168:171], v[222:225], v[104:107]
	v_mfma_f32_16x16x32_bf16 v[100:103], v[176:179], v[222:225], v[100:103]
	v_mfma_f32_16x16x32_bf16 v[100:103], v[172:175], v[218:221], v[100:103]
	v_mfma_f32_16x16x32_bf16 v[68:71], v[156:159], v[218:221], v[68:71]
	v_mfma_f32_16x16x32_bf16 v[68:71], v[160:163], v[222:225], v[68:71]
	v_mfma_f32_16x16x32_bf16 v[60:63], v[148:151], v[222:225], v[60:63]
	v_mfma_f32_16x16x32_bf16 v[60:63], v[132:135], v[218:221], v[60:63]

; #define PG8_MMA(ai, bj, At, Bt) do { __builtin_amdgcn_s_setprio(1); _Pragma("unroll") for (int m = 0; m < 4; ++m) _Pragma("unroll") for (int n = 0; n < 2; ++n) _Pragma("unroll") for (int k = 0; k < 2; ++k) \
;         acc[ai][bj][m][n] = __builtin_amdgcn_mfma_f32_16x16x32_bf16(Bt[n][k], At[m][k], acc[ai][bj][m][n], 0, 0, 0); __builtin_amdgcn_s_setprio(0); } while (0)
; #define PG8_WAIT_V(n) asm volatile("s_waitcnt vmcnt(" #n ")" ::: "memory")
; #define PG8_WAIT_L(n) asm volatile("s_waitcnt lgkmcnt(" #n ")" ::: "memory")
; #define PG8_BAR __builtin_amdgcn_s_barrier()
; #define PG8_SCHED __builtin_amdgcn_sched_barrier(0)
; template <class Epi, bool ALIGN_EPI>
; __device__ __forceinline__ void gemm_phase(LAS unsigned char* lds, const Gemm g, const StaticOrder& S, const Epi& E, const int tid) {
;     ...
;             PG8_WAIT_V(8); PG8_WAIT_L(0); PG8_BAR; PG8_MMA(1, 0, At, B0); PG8_MMA(1, 1, At, B1); PG8_BAR; PG8_SCHED;
;         }
;         if constexpr (ALIGN_EPI) { if (wr == 0) PG8_BAR; }
;     __device__ __forceinline__ void operator()(f32x4 (&acc)[2][2][4][2], const Unit& u, int wr, int wc, LAS unsigned char* lds, int& rs_pm) const {
;     ...
;                 bf16* const xrow = xb + (((size_t)(u.pm * 32 + u.pn * 4 + (wc >> 1)) * BM + (wr * 64 + fr + ai * HALF + m * 16)) * 64 + (wc & 1) * 32 + 8 * fq);
; #pragma unroll
;                 for (int bj = 0; bj < 2; ++bj) {
;                     const u32x4 xw = *(const u32x4*)(xrow + (size_t)bj * (2 * BM * 64));
	s_barrier
	s_add_i32 s86, s86, 2
	s_add_u32 s84, s84, 0x10000
	s_addc_u32 s85, s85, 0
	s_add_u32 s10, s10, 0x10000
	s_addc_u32 s11, s11, 0
	s_cmpk_gt_u32 s86, 0x55
	s_cbranch_scc0 .LBB0_294
	v_and_b32_e32 v222, 15, v238
	v_lshrrev_b32_e32 v156, 4, v238
	s_lshl_b32 s100, s82, 5
	s_lshl_b32 s101, s83, 2
	v_lshlrev_b32_e32 v222, 7, v222
	s_add_i32 s100, s100, s101
	s_or_b32 s100, s100, s78
	v_lshl_or_b32 v222, v156, 4, v222
	s_ashr_i32 s101, s100, 31
	s_lshl_b64 s[100:101], s[100:101], 15
	s_add_u32 s98, s72, s100
	s_addc_u32 s99, s73, s101
	s_add_u32 s98, s98, s30
	s_addc_u32 s99, s99, s31
	s_lshl_b32 s100, s75, 7
	s_add_u32 s98, s98, s100
	s_addc_u32 s99, s99, 0
	s_lshl_b32 s100, s82, 15
	s_lshl_b32 s101, s75, 7
	s_add_i32 s100, s100, s101
	s_lshl_b32 s101, s83, 4
	s_add_i32 s100, s100, s101
	s_lshl_b32 s101, s74, 2
	s_add_i32 s100, s100, s101
	s_add_u32 s22, s44, s100
	s_addc_u32 s23, s45, 0
	global_load_dwordx4 v[176:179], v222, s[98:99]
	s_add_u32 s100, s98, 0x10000
	s_addc_u32 s101, s99, 0
	global_load_dwordx4 v[180:183], v222, s[100:101]
	global_load_dwordx4 v[184:187], v222, s[98:99] offset:2048
	s_add_u32 s100, s98, 0x10000
	s_addc_u32 s101, s99, 0
	global_load_dwordx4 v[188:191], v222, s[100:101] offset:2048
	s_add_u32 s100, s98, 0x1000
	s_addc_u32 s101, s99, 0
	global_load_dwordx4 v[192:195], v222, s[100:101]
	s_add_u32 s100, s98, 0x11000
	s_addc_u32 s101, s99, 0
	global_load_dwordx4 v[196:199], v222, s[100:101]
	s_add_u32 s100, s98, 0x1000
	s_addc_u32 s101, s99, 0
	global_load_dwordx4 v[214:217], v222, s[100:101] offset:2048
	s_add_u32 s100, s98, 0x11000
	s_addc_u32 s101, s99, 0
	global_load_dwordx4 v[218:221], v222, s[100:101] offset:2048
	s_and_b64 vcc, exec, s[46:47]
	s_cbranch_vccz .LBB0_297
	s_barrier

; #define PG8_STAGE(bufoff, gbase, voff) do { _Pragma("unroll") for (int _i = 0; _i < 2; ++_i) \
;         __builtin_amdgcn_global_load_lds((const unsigned*)((const char*)(gbase) + (voff)[_i]), (LAS unsigned*)(lds + (bufoff) + ldsw + _i * 8192), 16, 0, 0); } while (0)
; #define PG8_LDA(dst, b, h) do { _Pragma("unroll") for (int m = 0; m < 4; ++m) _Pragma("unroll") for (int k = 0; k < 2; ++k) dst[m][k] = *(const LAS bf16x8*)(lds + PG8_SA(b, h) + aoff + m * 2048 + k * 1024); } while (0)
; #define PG8_LDB(dst, b, h) do { _Pragma("unroll") for (int n = 0; n < 2; ++n) _Pragma("unroll") for (int k = 0; k < 2; ++k) dst[n][k] = *(const LAS bf16x8*)(lds + PG8_SB(b, h) + boff + n * 2048 + k * 1024); } while (0)
; #define PG8_SCHED __builtin_amdgcn_sched_barrier(0)
; template <class Epi, bool ALIGN_EPI>
; __device__ __forceinline__ void gemm_phase(LAS unsigned char* lds, const Gemm g, const StaticOrder& S, const Epi& E, const int tid) {
;     ...
;             const bool last = (t == nt - 2);
;             const char* a1 = cA + (size_t)(t + 1) * kstepA;
;             const char* a2 = last ? nA : cA + (size_t)(t + 2) * kstepA; const char* b2 = last ? nB : cB + (size_t)(t + 2) * kstepB;
;             const char* a3 = a2 + kstepA; const char* b3 = b2 + kstepB;
;             PG8_LDB(B0, 0, 0); PG8_LDB(B1, 0, 1); PG8_SCHED; PG8_LDA(At, 0, 0); PG8_STAGE(PG8_SA(1, 1), a1 + hstepA, voffA);
.LBB0_385:
	s_add_u32 s50, s48, 0x4000
	s_addc_u32 s51, s49, 0
	s_cmp_eq_u32 s88, 28
	s_cselect_b32 s54, s84, s50
	s_cselect_b32 s55, s43, s51
	s_cselect_b32 s52, s85, s86
	s_cselect_b32 s53, s41, s87
	s_add_u32 s50, s54, 0x8000
	s_addc_u32 s51, s55, 0
	s_add_i32 s89, 0, 0x10000
	v_add_u32_e32 v0, s89, v167
	s_add_i32 s92, 0, 0x14000
	ds_read_b128 v[132:135], v0
	ds_read_b128 v[136:139], v0 offset:1024
	ds_read_b128 v[152:155], v0 offset:2048
	ds_read_b128 v[156:159], v0 offset:3072
	v_add_u32_e32 v0, s92, v167
	ds_read_b128 v[160:163], v0
	ds_read_b128 v[172:175], v0 offset:1024
	ds_read_b128 v[176:179], v0 offset:2048
	ds_read_b128 v[180:183], v0 offset:3072
	s_add_i32 m0, s71, 0xc000
	ds_read_b128 v[184:187], v171
	ds_read_b128 v[188:191], v171 offset:1024
	ds_read_b128 v[192:195], v171 offset:2048
	ds_read_b128 v[196:199], v171 offset:3072
	ds_read_b128 v[214:217], v171 offset:4096
	ds_read_b128 v[218:221], v171 offset:5120
	ds_read_b128 v[222:225], v171 offset:6144

; #define PG8_STAGE(bufoff, gbase, voff) do { _Pragma("unroll") for (int _i = 0; _i < 2; ++_i) \
;         __builtin_amdgcn_global_load_lds((const unsigned*)((const char*)(gbase) + (voff)[_i]), (LAS unsigned*)(lds + (bufoff) + ldsw + _i * 8192), 16, 0, 0); } while (0)
; #define PG8_LDA(dst, b, h) do { _Pragma("unroll") for (int m = 0; m < 4; ++m) _Pragma("unroll") for (int k = 0; k < 2; ++k) dst[m][k] = *(const LAS bf16x8*)(lds + PG8_SA(b, h) + aoff + m * 2048 + k * 1024); } while (0)
; #define PG8_LDB(dst, b, h) do { _Pragma("unroll") for (int n = 0; n < 2; ++n) _Pragma("unroll") for (int k = 0; k < 2; ++k) dst[n][k] = *(const LAS bf16x8*)(lds + PG8_SB(b, h) + boff + n * 2048 + k * 1024); } while (0)
; #define PG8_MMA(ai, bj, At, Bt) do { __builtin_amdgcn_s_setprio(1); _Pragma("unroll") for (int m = 0; m < 4; ++m) _Pragma("unroll") for (int n = 0; n < 2; ++n) _Pragma("unroll") for (int k = 0; k < 2; ++k) \
;         acc[ai][bj][m][n] = __builtin_amdgcn_mfma_f32_16x16x32_bf16(Bt[n][k], At[m][k], acc[ai][bj][m][n], 0, 0, 0); __builtin_amdgcn_s_setprio(0); } while (0)
; #define PG8_WAIT_V(n) asm volatile("s_waitcnt vmcnt(" #n ")" ::: "memory")
; #define PG8_WAIT_L(n) asm volatile("s_waitcnt lgkmcnt(" #n ")" ::: "memory")
; #define PG8_BAR __builtin_amdgcn_s_barrier()
; #define PG8_SCHED __builtin_amdgcn_sched_barrier(0)
; template <class Epi, bool ALIGN_EPI>
; __device__ __forceinline__ void gemm_phase(LAS unsigned char* lds, const Gemm g, const StaticOrder& S, const Epi& E, const int tid) {
;     ...
;             PG8_LDB(B0, 0, 0); PG8_LDB(B1, 0, 1); PG8_SCHED; PG8_LDA(At, 0, 0); PG8_STAGE(PG8_SA(1, 1), a1 + hstepA, voffA);
;             PG8_WAIT_V(8); PG8_WAIT_L(0); PG8_BAR; PG8_MMA(0, 0, At, B0); PG8_MMA(0, 1, At, B1); PG8_BAR; PG8_SCHED;
	global_load_lds_dwordx4 v148, s[48:49]
	s_add_i32 m0, s71, 0xe000
	ds_read_b128 v[226:229], v171 offset:7168
	global_load_lds_dwordx4 v150, s[48:49]
	s_waitcnt vmcnt(8)
	s_waitcnt lgkmcnt(0)
	s_barrier


; #define PG8_MMA(ai, bj, At, Bt) do { __builtin_amdgcn_s_setprio(1); _Pragma("unroll") for (int m = 0; m < 4; ++m) _Pragma("unroll") for (int n = 0; n < 2; ++n) _Pragma("unroll") for (int k = 0; k < 2; ++k) \
;         acc[ai][bj][m][n] = __builtin_amdgcn_mfma_f32_16x16x32_bf16(Bt[n][k], At[m][k], acc[ai][bj][m][n], 0, 0, 0); __builtin_amdgcn_s_setprio(0); } while (0)
; #define PG8_WAIT_V(n) asm volatile("s_waitcnt vmcnt(" #n ")" ::: "memory")
; #define PG8_WAIT_L(n) asm volatile("s_waitcnt lgkmcnt(" #n ")" ::: "memory")
; #define PG8_BAR __builtin_amdgcn_s_barrier()
; #define PG8_SCHED __builtin_amdgcn_sched_barrier(0)
; template <class Epi, bool ALIGN_EPI>
; __device__ __forceinline__ void gemm_phase(LAS unsigned char* lds, const Gemm g, const StaticOrder& S, const Epi& E, const int tid) {
;     ...
;             PG8_WAIT_V(8); PG8_WAIT_L(0); PG8_BAR; PG8_MMA(0, 0, At, B0); PG8_MMA(0, 1, At, B1); PG8_BAR; PG8_SCHED;
	v_mfma_f32_16x16x32_bf16 v[128:131], v[132:135], v[184:187], v[128:131]
	v_mfma_f32_16x16x32_bf16 v[128:131], v[136:139], v[188:191], v[128:131]
	v_mfma_f32_16x16x32_bf16 v[116:119], v[156:159], v[188:191], v[116:119]
	v_mfma_f32_16x16x32_bf16 v[116:119], v[152:155], v[184:187], v[116:119]
	v_mfma_f32_16x16x32_bf16 v[80:83], v[176:179], v[184:187], v[80:83]
	v_mfma_f32_16x16x32_bf16 v[80:83], v[180:183], v[188:191], v[80:83]
	v_mfma_f32_16x16x32_bf16 v[104:107], v[172:175], v[188:191], v[104:107]
	v_mfma_f32_16x16x32_bf16 v[104:107], v[160:163], v[184:187], v[104:107]
	v_mfma_f32_16x16x32_bf16 v[96:99], v[160:163], v[192:195], v[96:99]
	v_mfma_f32_16x16x32_bf16 v[96:99], v[172:175], v[196:199], v[96:99]
	v_mfma_f32_16x16x32_bf16 v[68:71], v[180:183], v[196:199], v[68:71]
	v_mfma_f32_16x16x32_bf16 v[68:71], v[176:179], v[192:195], v[68:71]
	v_mfma_f32_16x16x32_bf16 v[108:111], v[152:155], v[192:195], v[108:111]
	v_mfma_f32_16x16x32_bf16 v[108:111], v[156:159], v[196:199], v[108:111]
	v_mfma_f32_16x16x32_bf16 v[124:127], v[136:139], v[196:199], v[124:127]
	v_mfma_f32_16x16x32_bf16 v[124:127], v[132:135], v[192:195], v[124:127]


; #define PG8_MMA(ai, bj, At, Bt) do { __builtin_amdgcn_s_setprio(1); _Pragma("unroll") for (int m = 0; m < 4; ++m) _Pragma("unroll") for (int n = 0; n < 2; ++n) _Pragma("unroll") for (int k = 0; k < 2; ++k) \
;         acc[ai][bj][m][n] = __builtin_amdgcn_mfma_f32_16x16x32_bf16(Bt[n][k], At[m][k], acc[ai][bj][m][n], 0, 0, 0); __builtin_amdgcn_s_setprio(0); } while (0)
; #define PG8_WAIT_V(n) asm volatile("s_waitcnt vmcnt(" #n ")" ::: "memory")
; #define PG8_WAIT_L(n) asm volatile("s_waitcnt lgkmcnt(" #n ")" ::: "memory")
; #define PG8_BAR __builtin_amdgcn_s_barrier()
; #define PG8_SCHED __builtin_amdgcn_sched_barrier(0)
; template <class Epi, bool ALIGN_EPI>
; __device__ __forceinline__ void gemm_phase(LAS unsigned char* lds, const Gemm g, const StaticOrder& S, const Epi& E, const int tid) {
;     ...
;             PG8_WAIT_V(8); PG8_WAIT_L(0); PG8_BAR; PG8_MMA(0, 0, At, B0); PG8_MMA(0, 1, At, B1); PG8_BAR; PG8_SCHED;
	v_mfma_f32_16x16x32_bf16 v[120:123], v[132:135], v[214:217], v[120:123]
	v_mfma_f32_16x16x32_bf16 v[120:123], v[136:139], v[218:221], v[120:123]
	v_mfma_f32_16x16x32_bf16 v[100:103], v[156:159], v[218:221], v[100:103]
	v_mfma_f32_16x16x32_bf16 v[100:103], v[152:155], v[214:217], v[100:103]
	v_mfma_f32_16x16x32_bf16 v[60:63], v[176:179], v[214:217], v[60:63]
	v_mfma_f32_16x16x32_bf16 v[60:63], v[180:183], v[218:221], v[60:63]
	v_mfma_f32_16x16x32_bf16 v[88:91], v[172:175], v[218:221], v[88:91]
	v_mfma_f32_16x16x32_bf16 v[88:91], v[160:163], v[214:217], v[88:91]
	v_mfma_f32_16x16x32_bf16 v[76:79], v[160:163], v[222:225], v[76:79]
	v_mfma_f32_16x16x32_bf16 v[76:79], v[172:175], v[226:229], v[76:79]
	v_mfma_f32_16x16x32_bf16 v[48:51], v[180:183], v[226:229], v[48:51]
	v_mfma_f32_16x16x32_bf16 v[48:51], v[176:179], v[222:225], v[48:51]
	v_mfma_f32_16x16x32_bf16 v[92:95], v[152:155], v[222:225], v[92:95]
	v_mfma_f32_16x16x32_bf16 v[92:95], v[156:159], v[226:229], v[92:95]
	v_mfma_f32_16x16x32_bf16 v[112:115], v[136:139], v[226:229], v[112:115]
	v_mfma_f32_16x16x32_bf16 v[112:115], v[132:135], v[222:225], v[112:115]

; #define PG8_STAGE(bufoff, gbase, voff) do { _Pragma("unroll") for (int _i = 0; _i < 2; ++_i) \
;         __builtin_amdgcn_global_load_lds((const unsigned*)((const char*)(gbase) + (voff)[_i]), (LAS unsigned*)(lds + (bufoff) + ldsw + _i * 8192), 16, 0, 0); } while (0)
; #define PG8_LDA(dst, b, h) do { _Pragma("unroll") for (int m = 0; m < 4; ++m) _Pragma("unroll") for (int k = 0; k < 2; ++k) dst[m][k] = *(const LAS bf16x8*)(lds + PG8_SA(b, h) + aoff + m * 2048 + k * 1024); } while (0)
; #define PG8_MMA(ai, bj, At, Bt) do { __builtin_amdgcn_s_setprio(1); _Pragma("unroll") for (int m = 0; m < 4; ++m) _Pragma("unroll") for (int n = 0; n < 2; ++n) _Pragma("unroll") for (int k = 0; k < 2; ++k) \
;         acc[ai][bj][m][n] = __builtin_amdgcn_mfma_f32_16x16x32_bf16(Bt[n][k], At[m][k], acc[ai][bj][m][n], 0, 0, 0); __builtin_amdgcn_s_setprio(0); } while (0)
; #define PG8_WAIT_V(n) asm volatile("s_waitcnt vmcnt(" #n ")" ::: "memory")
; #define PG8_WAIT_L(n) asm volatile("s_waitcnt lgkmcnt(" #n ")" ::: "memory")
; #define PG8_BAR __builtin_amdgcn_s_barrier()
; #define PG8_SCHED __builtin_amdgcn_sched_barrier(0)
; template <class Epi, bool ALIGN_EPI>
; __device__ __forceinline__ void gemm_phase(LAS unsigned char* lds, const Gemm g, const StaticOrder& S, const Epi& E, const int tid) {
;     ...
;             PG8_WAIT_V(8); PG8_WAIT_L(0); PG8_BAR; PG8_MMA(0, 0, At, B0); PG8_MMA(0, 1, At, B1); PG8_BAR; PG8_SCHED;
;             PG8_LDA(At, 0, 1); PG8_STAGE(PG8_SB(0, 0), b2, voffB); PG8_STAGE(PG8_SB(0, 1), b2 + hstepB, voffB); PG8_STAGE(PG8_SA(0, 0), a2, voffA);
	s_barrier
	s_add_i32 s89, s89, s61
	s_mov_b32 m0, s89
	ds_read_b128 v[184:187], v171 offset:16384
	ds_read_b128 v[188:191], v171 offset:17408
	ds_read_b128 v[192:195], v171 offset:18432
	ds_read_b128 v[196:199], v171 offset:19456


; #define PG8_STAGE(bufoff, gbase, voff) do { _Pragma("unroll") for (int _i = 0; _i < 2; ++_i) \
;         __builtin_amdgcn_global_load_lds((const unsigned*)((const char*)(gbase) + (voff)[_i]), (LAS unsigned*)(lds + (bufoff) + ldsw + _i * 8192), 16, 0, 0); } while (0)
; #define PG8_LDA(dst, b, h) do { _Pragma("unroll") for (int m = 0; m < 4; ++m) _Pragma("unroll") for (int k = 0; k < 2; ++k) dst[m][k] = *(const LAS bf16x8*)(lds + PG8_SA(b, h) + aoff + m * 2048 + k * 1024); } while (0)
; #define PG8_MMA(ai, bj, At, Bt) do { __builtin_amdgcn_s_setprio(1); _Pragma("unroll") for (int m = 0; m < 4; ++m) _Pragma("unroll") for (int n = 0; n < 2; ++n) _Pragma("unroll") for (int k = 0; k < 2; ++k) \
;         acc[ai][bj][m][n] = __builtin_amdgcn_mfma_f32_16x16x32_bf16(Bt[n][k], At[m][k], acc[ai][bj][m][n], 0, 0, 0); __builtin_amdgcn_s_setprio(0); } while (0)
; #define PG8_WAIT_V(n) asm volatile("s_waitcnt vmcnt(" #n ")" ::: "memory")
; #define PG8_WAIT_L(n) asm volatile("s_waitcnt lgkmcnt(" #n ")" ::: "memory")
; #define PG8_BAR __builtin_amdgcn_s_barrier()
; #define PG8_SCHED __builtin_amdgcn_sched_barrier(0)
; template <class Epi, bool ALIGN_EPI>
; __device__ __forceinline__ void gemm_phase(LAS unsigned char* lds, const Gemm g, const StaticOrder& S, const Epi& E, const int tid) {
;     ...
;             PG8_LDA(At, 0, 1); PG8_STAGE(PG8_SB(0, 0), b2, voffB); PG8_STAGE(PG8_SB(0, 1), b2 + hstepB, voffB); PG8_STAGE(PG8_SA(0, 0), a2, voffA);
;             PG8_WAIT_V(8); PG8_WAIT_L(0); PG8_BAR; PG8_MMA(1, 0, At, B0); PG8_MMA(1, 1, At, B1); PG8_BAR; PG8_SCHED;
	global_load_lds_dwordx4 v144, s[52:53]
	s_add_i32 m0, s89, 0x2000
	s_add_u32 s90, s52, 0x4000
	s_addc_u32 s91, s53, 0
	s_add_i32 s89, s92, s61
	global_load_lds_dwordx4 v140, s[52:53]
	s_mov_b32 m0, s89
	ds_read_b128 v[226:229], v171 offset:23552
	global_load_lds_dwordx4 v144, s[90:91]
	s_add_i32 m0, s89, 0x2000
	ds_read_b128 v[222:225], v171 offset:22528
	global_load_lds_dwordx4 v140, s[90:91]
	s_mov_b32 m0, s71
	ds_read_b128 v[218:221], v171 offset:21504
	global_load_lds_dwordx4 v146, s[54:55]
	s_mov_b32 m0, s72
	ds_read_b128 v[214:217], v171 offset:20480
	global_load_lds_dwordx4 v142, s[54:55]
	s_waitcnt vmcnt(8)
	s_waitcnt lgkmcnt(0)
	s_barrier


; #define PG8_MMA(ai, bj, At, Bt) do { __builtin_amdgcn_s_setprio(1); _Pragma("unroll") for (int m = 0; m < 4; ++m) _Pragma("unroll") for (int n = 0; n < 2; ++n) _Pragma("unroll") for (int k = 0; k < 2; ++k) \
;         acc[ai][bj][m][n] = __builtin_amdgcn_mfma_f32_16x16x32_bf16(Bt[n][k], At[m][k], acc[ai][bj][m][n], 0, 0, 0); __builtin_amdgcn_s_setprio(0); } while (0)
; #define PG8_WAIT_V(n) asm volatile("s_waitcnt vmcnt(" #n ")" ::: "memory")
; #define PG8_WAIT_L(n) asm volatile("s_waitcnt lgkmcnt(" #n ")" ::: "memory")
; #define PG8_BAR __builtin_amdgcn_s_barrier()
; #define PG8_SCHED __builtin_amdgcn_sched_barrier(0)
; template <class Epi, bool ALIGN_EPI>
; __device__ __forceinline__ void gemm_phase(LAS unsigned char* lds, const Gemm g, const StaticOrder& S, const Epi& E, const int tid) {
;     ...
;             PG8_WAIT_V(8); PG8_WAIT_L(0); PG8_BAR; PG8_MMA(1, 0, At, B0); PG8_MMA(1, 1, At, B1); PG8_BAR; PG8_SCHED;
	v_mfma_f32_16x16x32_bf16 v[84:87], v[132:135], v[184:187], v[84:87]
	v_mfma_f32_16x16x32_bf16 v[84:87], v[136:139], v[188:191], v[84:87]
	v_mfma_f32_16x16x32_bf16 v[56:59], v[156:159], v[188:191], v[56:59]
	v_mfma_f32_16x16x32_bf16 v[56:59], v[152:155], v[184:187], v[56:59]
	v_mfma_f32_16x16x32_bf16 v[20:23], v[176:179], v[184:187], v[20:23]
	v_mfma_f32_16x16x32_bf16 v[20:23], v[180:183], v[188:191], v[20:23]
	v_mfma_f32_16x16x32_bf16 v[40:43], v[172:175], v[188:191], v[40:43]
	v_mfma_f32_16x16x32_bf16 v[40:43], v[160:163], v[184:187], v[40:43]
	v_mfma_f32_16x16x32_bf16 v[32:35], v[160:163], v[192:195], v[32:35]
	v_mfma_f32_16x16x32_bf16 v[32:35], v[172:175], v[196:199], v[32:35]
	v_mfma_f32_16x16x32_bf16 v[12:15], v[180:183], v[196:199], v[12:15]
	v_mfma_f32_16x16x32_bf16 v[12:15], v[176:179], v[192:195], v[12:15]
	v_mfma_f32_16x16x32_bf16 v[44:47], v[152:155], v[192:195], v[44:47]
	v_mfma_f32_16x16x32_bf16 v[44:47], v[156:159], v[196:199], v[44:47]
	v_mfma_f32_16x16x32_bf16 v[72:75], v[136:139], v[196:199], v[72:75]
	v_mfma_f32_16x16x32_bf16 v[72:75], v[132:135], v[192:195], v[72:75]


; #define PG8_MMA(ai, bj, At, Bt) do { __builtin_amdgcn_s_setprio(1); _Pragma("unroll") for (int m = 0; m < 4; ++m) _Pragma("unroll") for (int n = 0; n < 2; ++n) _Pragma("unroll") for (int k = 0; k < 2; ++k) \
;         acc[ai][bj][m][n] = __builtin_amdgcn_mfma_f32_16x16x32_bf16(Bt[n][k], At[m][k], acc[ai][bj][m][n], 0, 0, 0); __builtin_amdgcn_s_setprio(0); } while (0)
; #define PG8_WAIT_V(n) asm volatile("s_waitcnt vmcnt(" #n ")" ::: "memory")
; #define PG8_WAIT_L(n) asm volatile("s_waitcnt lgkmcnt(" #n ")" ::: "memory")
; #define PG8_BAR __builtin_amdgcn_s_barrier()
; #define PG8_SCHED __builtin_amdgcn_sched_barrier(0)
; template <class Epi, bool ALIGN_EPI>
; __device__ __forceinline__ void gemm_phase(LAS unsigned char* lds, const Gemm g, const StaticOrder& S, const Epi& E, const int tid) {
;     ...
;             PG8_WAIT_V(8); PG8_WAIT_L(0); PG8_BAR; PG8_MMA(1, 0, At, B0); PG8_MMA(1, 1, At, B1); PG8_BAR; PG8_SCHED;
	v_mfma_f32_16x16x32_bf16 v[64:67], v[132:135], v[214:217], v[64:67]
	v_mfma_f32_16x16x32_bf16 v[64:67], v[136:139], v[218:221], v[64:67]
	v_mfma_f32_16x16x32_bf16 v[36:39], v[156:159], v[218:221], v[36:39]
	v_mfma_f32_16x16x32_bf16 v[36:39], v[152:155], v[214:217], v[36:39]
	v_mfma_f32_16x16x32_bf16 v[8:11], v[176:179], v[214:217], v[8:11]
	v_mfma_f32_16x16x32_bf16 v[8:11], v[180:183], v[218:221], v[8:11]
	v_mfma_f32_16x16x32_bf16 v[24:27], v[172:175], v[218:221], v[24:27]
	v_mfma_f32_16x16x32_bf16 v[24:27], v[160:163], v[214:217], v[24:27]
	v_mfma_f32_16x16x32_bf16 v[16:19], v[160:163], v[222:225], v[16:19]
	v_mfma_f32_16x16x32_bf16 v[16:19], v[172:175], v[226:229], v[16:19]
	v_mfma_f32_16x16x32_bf16 v[2:5], v[176:179], v[222:225], v[4:7]
	v_mfma_f32_16x16x32_bf16 v[2:5], v[180:183], v[226:229], v[2:5]
	v_mfma_f32_16x16x32_bf16 v[28:31], v[156:159], v[226:229], v[28:31]
	v_mfma_f32_16x16x32_bf16 v[28:31], v[152:155], v[222:225], v[28:31]
	v_mfma_f32_16x16x32_bf16 v[52:55], v[132:135], v[222:225], v[52:55]
	v_mfma_f32_16x16x32_bf16 v[52:55], v[136:139], v[226:229], v[52:55]

; #define PG8_STAGE(bufoff, gbase, voff) do { _Pragma("unroll") for (int _i = 0; _i < 2; ++_i) \
;         __builtin_amdgcn_global_load_lds((const unsigned*)((const char*)(gbase) + (voff)[_i]), (LAS unsigned*)(lds + (bufoff) + ldsw + _i * 8192), 16, 0, 0); } while (0)
; #define PG8_LDA(dst, b, h) do { _Pragma("unroll") for (int m = 0; m < 4; ++m) _Pragma("unroll") for (int k = 0; k < 2; ++k) dst[m][k] = *(const LAS bf16x8*)(lds + PG8_SA(b, h) + aoff + m * 2048 + k * 1024); } while (0)
; #define PG8_LDB(dst, b, h) do { _Pragma("unroll") for (int n = 0; n < 2; ++n) _Pragma("unroll") for (int k = 0; k < 2; ++k) dst[n][k] = *(const LAS bf16x8*)(lds + PG8_SB(b, h) + boff + n * 2048 + k * 1024); } while (0)
; #define PG8_MMA(ai, bj, At, Bt) do { __builtin_amdgcn_s_setprio(1); _Pragma("unroll") for (int m = 0; m < 4; ++m) _Pragma("unroll") for (int n = 0; n < 2; ++n) _Pragma("unroll") for (int k = 0; k < 2; ++k) \
;         acc[ai][bj][m][n] = __builtin_amdgcn_mfma_f32_16x16x32_bf16(Bt[n][k], At[m][k], acc[ai][bj][m][n], 0, 0, 0); __builtin_amdgcn_s_setprio(0); } while (0)
; #define PG8_WAIT_V(n) asm volatile("s_waitcnt vmcnt(" #n ")" ::: "memory")
; #define PG8_WAIT_L(n) asm volatile("s_waitcnt lgkmcnt(" #n ")" ::: "memory")
; #define PG8_BAR __builtin_amdgcn_s_barrier()
; #define PG8_SCHED __builtin_amdgcn_sched_barrier(0)
; template <class Epi, bool ALIGN_EPI>
; __device__ __forceinline__ void gemm_phase(LAS unsigned char* lds, const Gemm g, const StaticOrder& S, const Epi& E, const int tid) {
;     ...
;             PG8_WAIT_V(8); PG8_WAIT_L(0); PG8_BAR; PG8_MMA(1, 0, At, B0); PG8_MMA(1, 1, At, B1); PG8_BAR; PG8_SCHED;
;             PG8_LDB(B0, 1, 0); PG8_LDB(B1, 1, 1); PG8_SCHED; PG8_LDA(At, 1, 0); PG8_STAGE(PG8_SA(0, 1), a2 + hstepA, voffA);
	s_barrier
	s_add_i32 s89, 0, 0x18000
	v_add_u32_e32 v0, s89, v167
	s_add_i32 s90, 0, 0x1c000
	ds_read_b128 v[132:135], v0
	ds_read_b128 v[136:139], v0 offset:1024
	ds_read_b128 v[152:155], v0 offset:2048
	ds_read_b128 v[156:159], v0 offset:3072
	v_add_u32_e32 v0, s90, v167
	ds_read_b128 v[160:163], v0
	ds_read_b128 v[172:175], v0 offset:1024
	ds_read_b128 v[176:179], v0 offset:2048
	ds_read_b128 v[180:183], v0 offset:3072
	s_add_u32 s54, s54, 0x4000
	s_addc_u32 s55, s55, 0
	s_mov_b32 m0, s73
	ds_read_b128 v[184:187], v171 offset:32768
	ds_read_b128 v[188:191], v171 offset:33792
	ds_read_b128 v[192:195], v171 offset:34816
	ds_read_b128 v[196:199], v171 offset:35840
	ds_read_b128 v[214:217], v171 offset:36864
	ds_read_b128 v[218:221], v171 offset:37888
	ds_read_b128 v[222:225], v171 offset:38912

; #define PG8_STAGE(bufoff, gbase, voff) do { _Pragma("unroll") for (int _i = 0; _i < 2; ++_i) \
;         __builtin_amdgcn_global_load_lds((const unsigned*)((const char*)(gbase) + (voff)[_i]), (LAS unsigned*)(lds + (bufoff) + ldsw + _i * 8192), 16, 0, 0); } while (0)
; #define PG8_LDA(dst, b, h) do { _Pragma("unroll") for (int m = 0; m < 4; ++m) _Pragma("unroll") for (int k = 0; k < 2; ++k) dst[m][k] = *(const LAS bf16x8*)(lds + PG8_SA(b, h) + aoff + m * 2048 + k * 1024); } while (0)
; #define PG8_LDB(dst, b, h) do { _Pragma("unroll") for (int n = 0; n < 2; ++n) _Pragma("unroll") for (int k = 0; k < 2; ++k) dst[n][k] = *(const LAS bf16x8*)(lds + PG8_SB(b, h) + boff + n * 2048 + k * 1024); } while (0)
; #define PG8_MMA(ai, bj, At, Bt) do { __builtin_amdgcn_s_setprio(1); _Pragma("unroll") for (int m = 0; m < 4; ++m) _Pragma("unroll") for (int n = 0; n < 2; ++n) _Pragma("unroll") for (int k = 0; k < 2; ++k) \
;         acc[ai][bj][m][n] = __builtin_amdgcn_mfma_f32_16x16x32_bf16(Bt[n][k], At[m][k], acc[ai][bj][m][n], 0, 0, 0); __builtin_amdgcn_s_setprio(0); } while (0)
; #define PG8_WAIT_V(n) asm volatile("s_waitcnt vmcnt(" #n ")" ::: "memory")
; #define PG8_WAIT_L(n) asm volatile("s_waitcnt lgkmcnt(" #n ")" ::: "memory")
; #define PG8_BAR __builtin_amdgcn_s_barrier()
; #define PG8_SCHED __builtin_amdgcn_sched_barrier(0)
; template <class Epi, bool ALIGN_EPI>
; __device__ __forceinline__ void gemm_phase(LAS unsigned char* lds, const Gemm g, const StaticOrder& S, const Epi& E, const int tid) {
;     ...
;             PG8_LDB(B0, 1, 0); PG8_LDB(B1, 1, 1); PG8_SCHED; PG8_LDA(At, 1, 0); PG8_STAGE(PG8_SA(0, 1), a2 + hstepA, voffA);
;             PG8_WAIT_V(8); PG8_WAIT_L(0); PG8_BAR; PG8_MMA(0, 0, At, B0); PG8_MMA(0, 1, At, B1); PG8_BAR; PG8_SCHED;
	global_load_lds_dwordx4 v146, s[54:55]
	s_mov_b32 m0, s74
	ds_read_b128 v[226:229], v171 offset:39936
	global_load_lds_dwordx4 v142, s[54:55]
	s_waitcnt vmcnt(8)
	s_waitcnt lgkmcnt(0)
	s_barrier


; #define PG8_MMA(ai, bj, At, Bt) do { __builtin_amdgcn_s_setprio(1); _Pragma("unroll") for (int m = 0; m < 4; ++m) _Pragma("unroll") for (int n = 0; n < 2; ++n) _Pragma("unroll") for (int k = 0; k < 2; ++k) \
;         acc[ai][bj][m][n] = __builtin_amdgcn_mfma_f32_16x16x32_bf16(Bt[n][k], At[m][k], acc[ai][bj][m][n], 0, 0, 0); __builtin_amdgcn_s_setprio(0); } while (0)
; #define PG8_WAIT_V(n) asm volatile("s_waitcnt vmcnt(" #n ")" ::: "memory")
; #define PG8_WAIT_L(n) asm volatile("s_waitcnt lgkmcnt(" #n ")" ::: "memory")
; #define PG8_BAR __builtin_amdgcn_s_barrier()
; #define PG8_SCHED __builtin_amdgcn_sched_barrier(0)
; template <class Epi, bool ALIGN_EPI>
; __device__ __forceinline__ void gemm_phase(LAS unsigned char* lds, const Gemm g, const StaticOrder& S, const Epi& E, const int tid) {
;     ...
;             PG8_WAIT_V(8); PG8_WAIT_L(0); PG8_BAR; PG8_MMA(0, 0, At, B0); PG8_MMA(0, 1, At, B1); PG8_BAR; PG8_SCHED;
	v_mfma_f32_16x16x32_bf16 v[128:131], v[132:135], v[184:187], v[128:131]
	v_mfma_f32_16x16x32_bf16 v[128:131], v[136:139], v[188:191], v[128:131]
	v_mfma_f32_16x16x32_bf16 v[116:119], v[156:159], v[188:191], v[116:119]
	v_mfma_f32_16x16x32_bf16 v[116:119], v[152:155], v[184:187], v[116:119]
	v_mfma_f32_16x16x32_bf16 v[80:83], v[176:179], v[184:187], v[80:83]
	v_mfma_f32_16x16x32_bf16 v[80:83], v[180:183], v[188:191], v[80:83]
	v_mfma_f32_16x16x32_bf16 v[104:107], v[172:175], v[188:191], v[104:107]
	v_mfma_f32_16x16x32_bf16 v[104:107], v[160:163], v[184:187], v[104:107]
	v_mfma_f32_16x16x32_bf16 v[96:99], v[160:163], v[192:195], v[96:99]
	v_mfma_f32_16x16x32_bf16 v[96:99], v[172:175], v[196:199], v[96:99]
	v_mfma_f32_16x16x32_bf16 v[68:71], v[180:183], v[196:199], v[68:71]
	v_mfma_f32_16x16x32_bf16 v[68:71], v[176:179], v[192:195], v[68:71]
	v_mfma_f32_16x16x32_bf16 v[108:111], v[152:155], v[192:195], v[108:111]
	v_mfma_f32_16x16x32_bf16 v[108:111], v[156:159], v[196:199], v[108:111]
	v_mfma_f32_16x16x32_bf16 v[124:127], v[136:139], v[196:199], v[124:127]
	v_mfma_f32_16x16x32_bf16 v[124:127], v[132:135], v[192:195], v[124:127]


; #define PG8_MMA(ai, bj, At, Bt) do { __builtin_amdgcn_s_setprio(1); _Pragma("unroll") for (int m = 0; m < 4; ++m) _Pragma("unroll") for (int n = 0; n < 2; ++n) _Pragma("unroll") for (int k = 0; k < 2; ++k) \
;         acc[ai][bj][m][n] = __builtin_amdgcn_mfma_f32_16x16x32_bf16(Bt[n][k], At[m][k], acc[ai][bj][m][n], 0, 0, 0); __builtin_amdgcn_s_setprio(0); } while (0)
; #define PG8_WAIT_V(n) asm volatile("s_waitcnt vmcnt(" #n ")" ::: "memory")
; #define PG8_WAIT_L(n) asm volatile("s_waitcnt lgkmcnt(" #n ")" ::: "memory")
; #define PG8_BAR __builtin_amdgcn_s_barrier()
; #define PG8_SCHED __builtin_amdgcn_sched_barrier(0)
; template <class Epi, bool ALIGN_EPI>
; __device__ __forceinline__ void gemm_phase(LAS unsigned char* lds, const Gemm g, const StaticOrder& S, const Epi& E, const int tid) {
;     ...
;             PG8_WAIT_V(8); PG8_WAIT_L(0); PG8_BAR; PG8_MMA(0, 0, At, B0); PG8_MMA(0, 1, At, B1); PG8_BAR; PG8_SCHED;
	v_mfma_f32_16x16x32_bf16 v[120:123], v[132:135], v[214:217], v[120:123]
	v_mfma_f32_16x16x32_bf16 v[120:123], v[136:139], v[218:221], v[120:123]
	v_mfma_f32_16x16x32_bf16 v[100:103], v[156:159], v[218:221], v[100:103]
	v_mfma_f32_16x16x32_bf16 v[100:103], v[152:155], v[214:217], v[100:103]
	v_mfma_f32_16x16x32_bf16 v[60:63], v[176:179], v[214:217], v[60:63]
	v_mfma_f32_16x16x32_bf16 v[60:63], v[180:183], v[218:221], v[60:63]
	v_mfma_f32_16x16x32_bf16 v[88:91], v[172:175], v[218:221], v[88:91]
	v_mfma_f32_16x16x32_bf16 v[88:91], v[160:163], v[214:217], v[88:91]
	v_mfma_f32_16x16x32_bf16 v[76:79], v[160:163], v[222:225], v[76:79]
	v_mfma_f32_16x16x32_bf16 v[76:79], v[172:175], v[226:229], v[76:79]
	v_mfma_f32_16x16x32_bf16 v[48:51], v[180:183], v[226:229], v[48:51]
	v_mfma_f32_16x16x32_bf16 v[48:51], v[176:179], v[222:225], v[48:51]
	v_mfma_f32_16x16x32_bf16 v[92:95], v[152:155], v[222:225], v[92:95]
	v_mfma_f32_16x16x32_bf16 v[92:95], v[156:159], v[226:229], v[92:95]
	v_mfma_f32_16x16x32_bf16 v[112:115], v[136:139], v[226:229], v[112:115]
	v_mfma_f32_16x16x32_bf16 v[112:115], v[132:135], v[222:225], v[112:115]

; #define PG8_STAGE(bufoff, gbase, voff) do { _Pragma("unroll") for (int _i = 0; _i < 2; ++_i) \
;         __builtin_amdgcn_global_load_lds((const unsigned*)((const char*)(gbase) + (voff)[_i]), (LAS unsigned*)(lds + (bufoff) + ldsw + _i * 8192), 16, 0, 0); } while (0)
; #define PG8_LDA(dst, b, h) do { _Pragma("unroll") for (int m = 0; m < 4; ++m) _Pragma("unroll") for (int k = 0; k < 2; ++k) dst[m][k] = *(const LAS bf16x8*)(lds + PG8_SA(b, h) + aoff + m * 2048 + k * 1024); } while (0)
; #define PG8_MMA(ai, bj, At, Bt) do { __builtin_amdgcn_s_setprio(1); _Pragma("unroll") for (int m = 0; m < 4; ++m) _Pragma("unroll") for (int n = 0; n < 2; ++n) _Pragma("unroll") for (int k = 0; k < 2; ++k) \
;         acc[ai][bj][m][n] = __builtin_amdgcn_mfma_f32_16x16x32_bf16(Bt[n][k], At[m][k], acc[ai][bj][m][n], 0, 0, 0); __builtin_amdgcn_s_setprio(0); } while (0)
; #define PG8_WAIT_V(n) asm volatile("s_waitcnt vmcnt(" #n ")" ::: "memory")
; #define PG8_WAIT_L(n) asm volatile("s_waitcnt lgkmcnt(" #n ")" ::: "memory")
; #define PG8_BAR __builtin_amdgcn_s_barrier()
; #define PG8_SCHED __builtin_amdgcn_sched_barrier(0)
; template <class Epi, bool ALIGN_EPI>
; __device__ __forceinline__ void gemm_phase(LAS unsigned char* lds, const Gemm g, const StaticOrder& S, const Epi& E, const int tid) {
;     ...
;             PG8_WAIT_V(8); PG8_WAIT_L(0); PG8_BAR; PG8_MMA(0, 0, At, B0); PG8_MMA(0, 1, At, B1); PG8_BAR; PG8_SCHED;
;             PG8_LDA(At, 1, 1); PG8_STAGE(PG8_SB(1, 0), b3, voffB); PG8_STAGE(PG8_SB(1, 1), b3 + hstepB, voffB); PG8_STAGE(PG8_SA(1, 0), a3, voffA);
	s_barrier
	s_add_u32 s54, s52, 0x8000
	s_addc_u32 s55, s53, 0
	s_add_i32 s89, s89, s61
	s_mov_b32 m0, s89
	ds_read_b128 v[184:187], v171 offset:49152
	ds_read_b128 v[188:191], v171 offset:50176
	ds_read_b128 v[192:195], v171 offset:51200
	ds_read_b128 v[196:199], v171 offset:52224


; #define PG8_STAGE(bufoff, gbase, voff) do { _Pragma("unroll") for (int _i = 0; _i < 2; ++_i) \
;         __builtin_amdgcn_global_load_lds((const unsigned*)((const char*)(gbase) + (voff)[_i]), (LAS unsigned*)(lds + (bufoff) + ldsw + _i * 8192), 16, 0, 0); } while (0)
; #define PG8_LDA(dst, b, h) do { _Pragma("unroll") for (int m = 0; m < 4; ++m) _Pragma("unroll") for (int k = 0; k < 2; ++k) dst[m][k] = *(const LAS bf16x8*)(lds + PG8_SA(b, h) + aoff + m * 2048 + k * 1024); } while (0)
; #define PG8_MMA(ai, bj, At, Bt) do { __builtin_amdgcn_s_setprio(1); _Pragma("unroll") for (int m = 0; m < 4; ++m) _Pragma("unroll") for (int n = 0; n < 2; ++n) _Pragma("unroll") for (int k = 0; k < 2; ++k) \
;         acc[ai][bj][m][n] = __builtin_amdgcn_mfma_f32_16x16x32_bf16(Bt[n][k], At[m][k], acc[ai][bj][m][n], 0, 0, 0); __builtin_amdgcn_s_setprio(0); } while (0)
; #define PG8_WAIT_V(n) asm volatile("s_waitcnt vmcnt(" #n ")" ::: "memory")
; #define PG8_WAIT_L(n) asm volatile("s_waitcnt lgkmcnt(" #n ")" ::: "memory")
; #define PG8_BAR __builtin_amdgcn_s_barrier()
; #define PG8_SCHED __builtin_amdgcn_sched_barrier(0)
; template <class Epi, bool ALIGN_EPI>
; __device__ __forceinline__ void gemm_phase(LAS unsigned char* lds, const Gemm g, const StaticOrder& S, const Epi& E, const int tid) {
;     ...
;             PG8_LDA(At, 1, 1); PG8_STAGE(PG8_SB(1, 0), b3, voffB); PG8_STAGE(PG8_SB(1, 1), b3 + hstepB, voffB); PG8_STAGE(PG8_SA(1, 0), a3, voffA);
;             PG8_WAIT_V(8); PG8_WAIT_L(0); PG8_BAR; PG8_MMA(1, 0, At, B0); PG8_MMA(1, 1, At, B1); PG8_BAR; PG8_SCHED;
	global_load_lds_dwordx4 v144, s[54:55]
	s_add_i32 m0, s89, 0x2000
	s_add_u32 s52, s52, 0xc000
	s_addc_u32 s53, s53, 0
	global_load_lds_dwordx4 v140, s[54:55]
	s_add_i32 s54, s90, s61
	s_mov_b32 m0, s54
	ds_read_b128 v[226:229], v171 offset:56320
	global_load_lds_dwordx4 v144, s[52:53]
	s_add_i32 m0, s54, 0x2000
	ds_read_b128 v[222:225], v171 offset:55296
	global_load_lds_dwordx4 v140, s[52:53]
	s_mov_b32 m0, s77
	ds_read_b128 v[218:221], v171 offset:54272
	global_load_lds_dwordx4 v146, s[50:51]
	s_mov_b32 m0, s78
	ds_read_b128 v[214:217], v171 offset:53248
	global_load_lds_dwordx4 v142, s[50:51]
	s_waitcnt vmcnt(8)
	s_waitcnt lgkmcnt(0)
	s_barrier


; #define PG8_MMA(ai, bj, At, Bt) do { __builtin_amdgcn_s_setprio(1); _Pragma("unroll") for (int m = 0; m < 4; ++m) _Pragma("unroll") for (int n = 0; n < 2; ++n) _Pragma("unroll") for (int k = 0; k < 2; ++k) \
;         acc[ai][bj][m][n] = __builtin_amdgcn_mfma_f32_16x16x32_bf16(Bt[n][k], At[m][k], acc[ai][bj][m][n], 0, 0, 0); __builtin_amdgcn_s_setprio(0); } while (0)
; #define PG8_WAIT_V(n) asm volatile("s_waitcnt vmcnt(" #n ")" ::: "memory")
; #define PG8_WAIT_L(n) asm volatile("s_waitcnt lgkmcnt(" #n ")" ::: "memory")
; #define PG8_BAR __builtin_amdgcn_s_barrier()
; #define PG8_SCHED __builtin_amdgcn_sched_barrier(0)
; template <class Epi, bool ALIGN_EPI>
; __device__ __forceinline__ void gemm_phase(LAS unsigned char* lds, const Gemm g, const StaticOrder& S, const Epi& E, const int tid) {
;     ...
;             PG8_WAIT_V(8); PG8_WAIT_L(0); PG8_BAR; PG8_MMA(1, 0, At, B0); PG8_MMA(1, 1, At, B1); PG8_BAR; PG8_SCHED;
	v_mfma_f32_16x16x32_bf16 v[84:87], v[132:135], v[184:187], v[84:87]
	v_mfma_f32_16x16x32_bf16 v[84:87], v[136:139], v[188:191], v[84:87]
	v_mfma_f32_16x16x32_bf16 v[56:59], v[156:159], v[188:191], v[56:59]
	v_mfma_f32_16x16x32_bf16 v[56:59], v[152:155], v[184:187], v[56:59]
	v_mfma_f32_16x16x32_bf16 v[20:23], v[176:179], v[184:187], v[20:23]
	v_mfma_f32_16x16x32_bf16 v[20:23], v[180:183], v[188:191], v[20:23]
	v_mfma_f32_16x16x32_bf16 v[40:43], v[172:175], v[188:191], v[40:43]
	v_mfma_f32_16x16x32_bf16 v[40:43], v[160:163], v[184:187], v[40:43]
	v_mfma_f32_16x16x32_bf16 v[32:35], v[160:163], v[192:195], v[32:35]
	v_mfma_f32_16x16x32_bf16 v[32:35], v[172:175], v[196:199], v[32:35]
	v_mfma_f32_16x16x32_bf16 v[12:15], v[180:183], v[196:199], v[12:15]
	v_mfma_f32_16x16x32_bf16 v[12:15], v[176:179], v[192:195], v[12:15]
	v_mfma_f32_16x16x32_bf16 v[44:47], v[152:155], v[192:195], v[44:47]
	v_mfma_f32_16x16x32_bf16 v[44:47], v[156:159], v[196:199], v[44:47]
	v_mfma_f32_16x16x32_bf16 v[72:75], v[136:139], v[196:199], v[72:75]
	v_mfma_f32_16x16x32_bf16 v[72:75], v[132:135], v[192:195], v[72:75]


; #define PG8_MMA(ai, bj, At, Bt) do { __builtin_amdgcn_s_setprio(1); _Pragma("unroll") for (int m = 0; m < 4; ++m) _Pragma("unroll") for (int n = 0; n < 2; ++n) _Pragma("unroll") for (int k = 0; k < 2; ++k) \
;         acc[ai][bj][m][n] = __builtin_amdgcn_mfma_f32_16x16x32_bf16(Bt[n][k], At[m][k], acc[ai][bj][m][n], 0, 0, 0); __builtin_amdgcn_s_setprio(0); } while (0)
; #define PG8_WAIT_V(n) asm volatile("s_waitcnt vmcnt(" #n ")" ::: "memory")
; #define PG8_WAIT_L(n) asm volatile("s_waitcnt lgkmcnt(" #n ")" ::: "memory")
; #define PG8_BAR __builtin_amdgcn_s_barrier()
; #define PG8_SCHED __builtin_amdgcn_sched_barrier(0)
; template <class Epi, bool ALIGN_EPI>
; __device__ __forceinline__ void gemm_phase(LAS unsigned char* lds, const Gemm g, const StaticOrder& S, const Epi& E, const int tid) {
;     ...
;             PG8_WAIT_V(8); PG8_WAIT_L(0); PG8_BAR; PG8_MMA(1, 0, At, B0); PG8_MMA(1, 1, At, B1); PG8_BAR; PG8_SCHED;
	v_mfma_f32_16x16x32_bf16 v[64:67], v[132:135], v[214:217], v[64:67]
	v_mfma_f32_16x16x32_bf16 v[64:67], v[136:139], v[218:221], v[64:67]
	v_mfma_f32_16x16x32_bf16 v[36:39], v[156:159], v[218:221], v[36:39]
	v_mfma_f32_16x16x32_bf16 v[36:39], v[152:155], v[214:217], v[36:39]
	v_mfma_f32_16x16x32_bf16 v[6:9], v[176:179], v[214:217], v[8:11]
	v_mfma_f32_16x16x32_bf16 v[8:11], v[180:183], v[218:221], v[6:9]
	v_mfma_f32_16x16x32_bf16 v[24:27], v[172:175], v[218:221], v[24:27]
	v_mfma_f32_16x16x32_bf16 v[24:27], v[160:163], v[214:217], v[24:27]
	v_mfma_f32_16x16x32_bf16 v[16:19], v[160:163], v[222:225], v[16:19]
	v_mfma_f32_16x16x32_bf16 v[16:19], v[172:175], v[226:229], v[16:19]
	v_mfma_f32_16x16x32_bf16 v[2:5], v[176:179], v[222:225], v[2:5]
	v_mfma_f32_16x16x32_bf16 v[4:7], v[180:183], v[226:229], v[2:5]
	v_mfma_f32_16x16x32_bf16 v[28:31], v[156:159], v[226:229], v[28:31]
	v_mfma_f32_16x16x32_bf16 v[28:31], v[152:155], v[222:225], v[28:31]
	v_mfma_f32_16x16x32_bf16 v[52:55], v[132:135], v[222:225], v[52:55]
	v_mfma_f32_16x16x32_bf16 v[52:55], v[136:139], v[226:229], v[52:55]

; #define PG8_MMA(ai, bj, At, Bt) do { __builtin_amdgcn_s_setprio(1); _Pragma("unroll") for (int m = 0; m < 4; ++m) _Pragma("unroll") for (int n = 0; n < 2; ++n) _Pragma("unroll") for (int k = 0; k < 2; ++k) \
;         acc[ai][bj][m][n] = __builtin_amdgcn_mfma_f32_16x16x32_bf16(Bt[n][k], At[m][k], acc[ai][bj][m][n], 0, 0, 0); __builtin_amdgcn_s_setprio(0); } while (0)
; #define PG8_WAIT_V(n) asm volatile("s_waitcnt vmcnt(" #n ")" ::: "memory")
; #define PG8_WAIT_L(n) asm volatile("s_waitcnt lgkmcnt(" #n ")" ::: "memory")
; #define PG8_BAR __builtin_amdgcn_s_barrier()
; #define PG8_SCHED __builtin_amdgcn_sched_barrier(0)
; template <class Epi, bool ALIGN_EPI>
; __device__ __forceinline__ void gemm_phase(LAS unsigned char* lds, const Gemm g, const StaticOrder& S, const Epi& E, const int tid) {
;     ...
;         for (int t = 0; t < nt; t += 2) {
;     ...
;             PG8_WAIT_V(8); PG8_WAIT_L(0); PG8_BAR; PG8_MMA(1, 0, At, B0); PG8_MMA(1, 1, At, B1); PG8_BAR; PG8_SCHED;
;         }
;         if constexpr (ALIGN_EPI) { if (wr == 0) PG8_BAR; }
	s_barrier
	s_add_i32 s88, s88, 2
	s_add_u32 s48, s48, 0x10000
	s_addc_u32 s49, s49, 0
	s_add_u32 s86, s86, 0x10000
	s_addc_u32 s87, s87, 0
	s_cmp_gt_u32 s88, 29
	s_cbranch_scc0 .LBB0_385
	s_and_b64 vcc, exec, s[34:35]
	s_cbranch_vccz .LBB0_388
	s_barrier

; #define PG8_STAGE(bufoff, gbase, voff) do { _Pragma("unroll") for (int _i = 0; _i < 2; ++_i) \
;         __builtin_amdgcn_global_load_lds((const unsigned*)((const char*)(gbase) + (voff)[_i]), (LAS unsigned*)(lds + (bufoff) + ldsw + _i * 8192), 16, 0, 0); } while (0)
; #define PG8_LDA(dst, b, h) do { _Pragma("unroll") for (int m = 0; m < 4; ++m) _Pragma("unroll") for (int k = 0; k < 2; ++k) dst[m][k] = *(const LAS bf16x8*)(lds + PG8_SA(b, h) + aoff + m * 2048 + k * 1024); } while (0)
; #define PG8_LDB(dst, b, h) do { _Pragma("unroll") for (int n = 0; n < 2; ++n) _Pragma("unroll") for (int k = 0; k < 2; ++k) dst[n][k] = *(const LAS bf16x8*)(lds + PG8_SB(b, h) + boff + n * 2048 + k * 1024); } while (0)
; #define PG8_SCHED __builtin_amdgcn_sched_barrier(0)
; template <class Epi, bool ALIGN_EPI>
; __device__ __forceinline__ void gemm_phase(LAS unsigned char* lds, const Gemm g, const StaticOrder& S, const Epi& E, const int tid) {
;     ...
;             const bool last = (t == nt - 2);
;             const char* a1 = cA + (size_t)(t + 1) * kstepA;
;             const char* a2 = last ? nA : cA + (size_t)(t + 2) * kstepA; const char* b2 = last ? nB : cB + (size_t)(t + 2) * kstepB;
;             const char* a3 = a2 + kstepA; const char* b3 = b2 + kstepB;
;             PG8_LDB(B0, 0, 0); PG8_LDB(B1, 0, 1); PG8_SCHED; PG8_LDA(At, 0, 0); PG8_STAGE(PG8_SA(1, 1), a1 + hstepA, voffA);
.LBB0_847:
	s_add_u32 s22, s10, 0xfff80080
	s_addc_u32 s23, s11, -1
	s_add_i32 s87, 0, 0x10000
	s_cmp_eq_u32 s86, 28
	s_cselect_b32 s35, s49, s23
	s_cselect_b32 s34, s82, s22
	v_add_u32_e32 v0, s87, v154
	s_cselect_b32 s23, s47, s85
	s_cselect_b32 s22, s83, s84
	s_add_i32 s90, 0, 0x14000
	s_waitcnt lgkmcnt(0)
	ds_read_b128 v[132:135], v0
	ds_read_b128 v[148:151], v0 offset:1024
	ds_read_b128 v[156:159], v0 offset:2048
	ds_read_b128 v[160:163], v0 offset:3072
	v_add_u32_e32 v0, s90, v154
	ds_read_b128 v[164:167], v0
	ds_read_b128 v[168:171], v0 offset:1024
	ds_read_b128 v[172:175], v0 offset:2048
	ds_read_b128 v[176:179], v0 offset:3072
	s_add_i32 m0, s70, 0xc000
	ds_read_b128 v[180:183], v155
	ds_read_b128 v[184:187], v155 offset:1024
	ds_read_b128 v[188:191], v155 offset:2048
	ds_read_b128 v[192:195], v155 offset:3072
	ds_read_b128 v[196:199], v155 offset:4096
	ds_read_b128 v[214:217], v155 offset:5120
	ds_read_b128 v[218:221], v155 offset:6144

; #define PG8_STAGE(bufoff, gbase, voff) do { _Pragma("unroll") for (int _i = 0; _i < 2; ++_i) \
;         __builtin_amdgcn_global_load_lds((const unsigned*)((const char*)(gbase) + (voff)[_i]), (LAS unsigned*)(lds + (bufoff) + ldsw + _i * 8192), 16, 0, 0); } while (0)
; #define PG8_LDA(dst, b, h) do { _Pragma("unroll") for (int m = 0; m < 4; ++m) _Pragma("unroll") for (int k = 0; k < 2; ++k) dst[m][k] = *(const LAS bf16x8*)(lds + PG8_SA(b, h) + aoff + m * 2048 + k * 1024); } while (0)
; #define PG8_LDB(dst, b, h) do { _Pragma("unroll") for (int n = 0; n < 2; ++n) _Pragma("unroll") for (int k = 0; k < 2; ++k) dst[n][k] = *(const LAS bf16x8*)(lds + PG8_SB(b, h) + boff + n * 2048 + k * 1024); } while (0)
; #define PG8_MMA(ai, bj, At, Bt) do { __builtin_amdgcn_s_setprio(1); _Pragma("unroll") for (int m = 0; m < 4; ++m) _Pragma("unroll") for (int n = 0; n < 2; ++n) _Pragma("unroll") for (int k = 0; k < 2; ++k) \
;         acc[ai][bj][m][n] = __builtin_amdgcn_mfma_f32_16x16x32_bf16(Bt[n][k], At[m][k], acc[ai][bj][m][n], 0, 0, 0); __builtin_amdgcn_s_setprio(0); } while (0)
; #define PG8_WAIT_V(n) asm volatile("s_waitcnt vmcnt(" #n ")" ::: "memory")
; #define PG8_WAIT_L(n) asm volatile("s_waitcnt lgkmcnt(" #n ")" ::: "memory")
; #define PG8_BAR __builtin_amdgcn_s_barrier()
; #define PG8_SCHED __builtin_amdgcn_sched_barrier(0)
; template <class Epi, bool ALIGN_EPI>
; __device__ __forceinline__ void gemm_phase(LAS unsigned char* lds, const Gemm g, const StaticOrder& S, const Epi& E, const int tid) {
;     ...
;             PG8_LDB(B0, 0, 0); PG8_LDB(B1, 0, 1); PG8_SCHED; PG8_LDA(At, 0, 0); PG8_STAGE(PG8_SA(1, 1), a1 + hstepA, voffA);
;             PG8_WAIT_V(8); PG8_WAIT_L(0); PG8_BAR; PG8_MMA(0, 0, At, B0); PG8_MMA(0, 1, At, B1); PG8_BAR; PG8_SCHED;
	global_load_lds_dwordx4 v144, s[10:11]
	s_add_i32 m0, s70, 0xe000
	ds_read_b128 v[222:225], v155 offset:7168
	global_load_lds_dwordx4 v146, s[10:11]
	s_waitcnt vmcnt(8)
	s_waitcnt lgkmcnt(0)
	s_barrier


; #define PG8_MMA(ai, bj, At, Bt) do { __builtin_amdgcn_s_setprio(1); _Pragma("unroll") for (int m = 0; m < 4; ++m) _Pragma("unroll") for (int n = 0; n < 2; ++n) _Pragma("unroll") for (int k = 0; k < 2; ++k) \
;         acc[ai][bj][m][n] = __builtin_amdgcn_mfma_f32_16x16x32_bf16(Bt[n][k], At[m][k], acc[ai][bj][m][n], 0, 0, 0); __builtin_amdgcn_s_setprio(0); } while (0)
; #define PG8_WAIT_V(n) asm volatile("s_waitcnt vmcnt(" #n ")" ::: "memory")
; #define PG8_WAIT_L(n) asm volatile("s_waitcnt lgkmcnt(" #n ")" ::: "memory")
; #define PG8_BAR __builtin_amdgcn_s_barrier()
; #define PG8_SCHED __builtin_amdgcn_sched_barrier(0)
; template <class Epi, bool ALIGN_EPI>
; __device__ __forceinline__ void gemm_phase(LAS unsigned char* lds, const Gemm g, const StaticOrder& S, const Epi& E, const int tid) {
;     ...
;             PG8_WAIT_V(8); PG8_WAIT_L(0); PG8_BAR; PG8_MMA(0, 0, At, B0); PG8_MMA(0, 1, At, B1); PG8_BAR; PG8_SCHED;
	v_mfma_f32_16x16x32_bf16 v[8:11], v[132:135], v[180:183], v[8:11]
	v_mfma_f32_16x16x32_bf16 v[8:11], v[148:151], v[184:187], v[8:11]
	v_mfma_f32_16x16x32_bf16 v[56:59], v[160:163], v[184:187], v[56:59]
	v_mfma_f32_16x16x32_bf16 v[56:59], v[156:159], v[180:183], v[56:59]
	v_mfma_f32_16x16x32_bf16 v[28:31], v[172:175], v[180:183], v[28:31]
	v_mfma_f32_16x16x32_bf16 v[28:31], v[176:179], v[184:187], v[28:31]
	v_mfma_f32_16x16x32_bf16 v[2:5], v[164:167], v[180:183], v[4:7]
	v_mfma_f32_16x16x32_bf16 v[2:5], v[168:171], v[184:187], v[2:5]
	v_mfma_f32_16x16x32_bf16 v[96:99], v[168:171], v[192:195], v[96:99]
	v_mfma_f32_16x16x32_bf16 v[96:99], v[164:167], v[188:191], v[96:99]
	v_mfma_f32_16x16x32_bf16 v[92:95], v[172:175], v[188:191], v[92:95]
	v_mfma_f32_16x16x32_bf16 v[92:95], v[176:179], v[192:195], v[92:95]
	v_mfma_f32_16x16x32_bf16 v[48:51], v[160:163], v[192:195], v[48:51]
	v_mfma_f32_16x16x32_bf16 v[48:51], v[156:159], v[188:191], v[48:51]
	v_mfma_f32_16x16x32_bf16 v[52:55], v[132:135], v[188:191], v[52:55]
	v_mfma_f32_16x16x32_bf16 v[52:55], v[148:151], v[192:195], v[52:55]


; #define PG8_MMA(ai, bj, At, Bt) do { __builtin_amdgcn_s_setprio(1); _Pragma("unroll") for (int m = 0; m < 4; ++m) _Pragma("unroll") for (int n = 0; n < 2; ++n) _Pragma("unroll") for (int k = 0; k < 2; ++k) \
;         acc[ai][bj][m][n] = __builtin_amdgcn_mfma_f32_16x16x32_bf16(Bt[n][k], At[m][k], acc[ai][bj][m][n], 0, 0, 0); __builtin_amdgcn_s_setprio(0); } while (0)
; #define PG8_WAIT_V(n) asm volatile("s_waitcnt vmcnt(" #n ")" ::: "memory")
; #define PG8_WAIT_L(n) asm volatile("s_waitcnt lgkmcnt(" #n ")" ::: "memory")
; #define PG8_BAR __builtin_amdgcn_s_barrier()
; #define PG8_SCHED __builtin_amdgcn_sched_barrier(0)
; template <class Epi, bool ALIGN_EPI>
; __device__ __forceinline__ void gemm_phase(LAS unsigned char* lds, const Gemm g, const StaticOrder& S, const Epi& E, const int tid) {
;     ...
;             PG8_WAIT_V(8); PG8_WAIT_L(0); PG8_BAR; PG8_MMA(0, 0, At, B0); PG8_MMA(0, 1, At, B1); PG8_BAR; PG8_SCHED;
	v_mfma_f32_16x16x32_bf16 v[44:47], v[148:151], v[214:217], v[44:47]
	v_mfma_f32_16x16x32_bf16 v[44:47], v[132:135], v[196:199], v[44:47]
	v_mfma_f32_16x16x32_bf16 v[40:43], v[156:159], v[196:199], v[40:43]
	v_mfma_f32_16x16x32_bf16 v[40:43], v[160:163], v[214:217], v[40:43]
	v_mfma_f32_16x16x32_bf16 v[84:87], v[176:179], v[214:217], v[84:87]
	v_mfma_f32_16x16x32_bf16 v[84:87], v[172:175], v[196:199], v[84:87]
	v_mfma_f32_16x16x32_bf16 v[88:91], v[164:167], v[196:199], v[88:91]
	v_mfma_f32_16x16x32_bf16 v[88:91], v[168:171], v[214:217], v[88:91]
	v_mfma_f32_16x16x32_bf16 v[80:83], v[168:171], v[222:225], v[80:83]
	v_mfma_f32_16x16x32_bf16 v[80:83], v[164:167], v[218:221], v[80:83]
	v_mfma_f32_16x16x32_bf16 v[76:79], v[172:175], v[218:221], v[76:79]
	v_mfma_f32_16x16x32_bf16 v[76:79], v[176:179], v[222:225], v[76:79]
	v_mfma_f32_16x16x32_bf16 v[32:35], v[160:163], v[222:225], v[32:35]
	v_mfma_f32_16x16x32_bf16 v[32:35], v[156:159], v[218:221], v[32:35]
	v_mfma_f32_16x16x32_bf16 v[36:39], v[132:135], v[218:221], v[36:39]
	v_mfma_f32_16x16x32_bf16 v[36:39], v[148:151], v[222:225], v[36:39]

; #define PG8_STAGE(bufoff, gbase, voff) do { _Pragma("unroll") for (int _i = 0; _i < 2; ++_i) \
;         __builtin_amdgcn_global_load_lds((const unsigned*)((const char*)(gbase) + (voff)[_i]), (LAS unsigned*)(lds + (bufoff) + ldsw + _i * 8192), 16, 0, 0); } while (0)
; #define PG8_LDA(dst, b, h) do { _Pragma("unroll") for (int m = 0; m < 4; ++m) _Pragma("unroll") for (int k = 0; k < 2; ++k) dst[m][k] = *(const LAS bf16x8*)(lds + PG8_SA(b, h) + aoff + m * 2048 + k * 1024); } while (0)
; #define PG8_MMA(ai, bj, At, Bt) do { __builtin_amdgcn_s_setprio(1); _Pragma("unroll") for (int m = 0; m < 4; ++m) _Pragma("unroll") for (int n = 0; n < 2; ++n) _Pragma("unroll") for (int k = 0; k < 2; ++k) \
;         acc[ai][bj][m][n] = __builtin_amdgcn_mfma_f32_16x16x32_bf16(Bt[n][k], At[m][k], acc[ai][bj][m][n], 0, 0, 0); __builtin_amdgcn_s_setprio(0); } while (0)
; #define PG8_WAIT_V(n) asm volatile("s_waitcnt vmcnt(" #n ")" ::: "memory")
; #define PG8_WAIT_L(n) asm volatile("s_waitcnt lgkmcnt(" #n ")" ::: "memory")
; #define PG8_BAR __builtin_amdgcn_s_barrier()
; #define PG8_SCHED __builtin_amdgcn_sched_barrier(0)
; template <class Epi, bool ALIGN_EPI>
; __device__ __forceinline__ void gemm_phase(LAS unsigned char* lds, const Gemm g, const StaticOrder& S, const Epi& E, const int tid) {
;     ...
;             PG8_WAIT_V(8); PG8_WAIT_L(0); PG8_BAR; PG8_MMA(0, 0, At, B0); PG8_MMA(0, 1, At, B1); PG8_BAR; PG8_SCHED;
;             PG8_LDA(At, 0, 1); PG8_STAGE(PG8_SB(0, 0), b2, voffB); PG8_STAGE(PG8_SB(0, 1), b2 + hstepB, voffB); PG8_STAGE(PG8_SA(0, 0), a2, voffA);
	s_barrier
	s_add_i32 s87, s87, s61
	s_mov_b32 m0, s87
	ds_read_b128 v[180:183], v155 offset:16384
	ds_read_b128 v[184:187], v155 offset:17408
	ds_read_b128 v[188:191], v155 offset:18432
	ds_read_b128 v[192:195], v155 offset:19456
	ds_read_b128 v[196:199], v155 offset:20480
	ds_read_b128 v[214:217], v155 offset:21504


; #define PG8_STAGE(bufoff, gbase, voff) do { _Pragma("unroll") for (int _i = 0; _i < 2; ++_i) \
;         __builtin_amdgcn_global_load_lds((const unsigned*)((const char*)(gbase) + (voff)[_i]), (LAS unsigned*)(lds + (bufoff) + ldsw + _i * 8192), 16, 0, 0); } while (0)
; #define PG8_LDA(dst, b, h) do { _Pragma("unroll") for (int m = 0; m < 4; ++m) _Pragma("unroll") for (int k = 0; k < 2; ++k) dst[m][k] = *(const LAS bf16x8*)(lds + PG8_SA(b, h) + aoff + m * 2048 + k * 1024); } while (0)
; #define PG8_MMA(ai, bj, At, Bt) do { __builtin_amdgcn_s_setprio(1); _Pragma("unroll") for (int m = 0; m < 4; ++m) _Pragma("unroll") for (int n = 0; n < 2; ++n) _Pragma("unroll") for (int k = 0; k < 2; ++k) \
;         acc[ai][bj][m][n] = __builtin_amdgcn_mfma_f32_16x16x32_bf16(Bt[n][k], At[m][k], acc[ai][bj][m][n], 0, 0, 0); __builtin_amdgcn_s_setprio(0); } while (0)
; #define PG8_WAIT_V(n) asm volatile("s_waitcnt vmcnt(" #n ")" ::: "memory")
; #define PG8_WAIT_L(n) asm volatile("s_waitcnt lgkmcnt(" #n ")" ::: "memory")
; #define PG8_BAR __builtin_amdgcn_s_barrier()
; #define PG8_SCHED __builtin_amdgcn_sched_barrier(0)
; template <class Epi, bool ALIGN_EPI>
; __device__ __forceinline__ void gemm_phase(LAS unsigned char* lds, const Gemm g, const StaticOrder& S, const Epi& E, const int tid) {
;     ...
;             PG8_LDA(At, 0, 1); PG8_STAGE(PG8_SB(0, 0), b2, voffB); PG8_STAGE(PG8_SB(0, 1), b2 + hstepB, voffB); PG8_STAGE(PG8_SA(0, 0), a2, voffA);
;             PG8_WAIT_V(8); PG8_WAIT_L(0); PG8_BAR; PG8_MMA(1, 0, At, B0); PG8_MMA(1, 1, At, B1); PG8_BAR; PG8_SCHED;
	global_load_lds_dwordx4 v140, s[22:23]
	s_add_i32 m0, s87, 0x2000
	s_add_u32 s88, s22, 0x4000
	s_addc_u32 s89, s23, 0
	s_add_i32 s87, s90, s61
	global_load_lds_dwordx4 v136, s[22:23]
	s_mov_b32 m0, s87
	v_lshl_add_u64 v[152:153], s[34:35], 0, v[142:143]
	global_load_lds_dwordx4 v140, s[88:89]
	s_add_i32 m0, s87, 0x2000
	v_lshl_add_u64 v[200:201], s[34:35], 0, v[138:139]
	global_load_lds_dwordx4 v136, s[88:89]
	s_mov_b32 m0, s70
	ds_read_b128 v[222:225], v155 offset:23552
	global_load_lds_dwordx4 v[152:153], off
	s_mov_b32 m0, s71
	ds_read_b128 v[218:221], v155 offset:22528
	global_load_lds_dwordx4 v[200:201], off
	s_waitcnt vmcnt(8)
	s_waitcnt lgkmcnt(0)
	s_barrier


; #define PG8_MMA(ai, bj, At, Bt) do { __builtin_amdgcn_s_setprio(1); _Pragma("unroll") for (int m = 0; m < 4; ++m) _Pragma("unroll") for (int n = 0; n < 2; ++n) _Pragma("unroll") for (int k = 0; k < 2; ++k) \
;         acc[ai][bj][m][n] = __builtin_amdgcn_mfma_f32_16x16x32_bf16(Bt[n][k], At[m][k], acc[ai][bj][m][n], 0, 0, 0); __builtin_amdgcn_s_setprio(0); } while (0)
; #define PG8_WAIT_V(n) asm volatile("s_waitcnt vmcnt(" #n ")" ::: "memory")
; #define PG8_WAIT_L(n) asm volatile("s_waitcnt lgkmcnt(" #n ")" ::: "memory")
; #define PG8_BAR __builtin_amdgcn_s_barrier()
; #define PG8_SCHED __builtin_amdgcn_sched_barrier(0)
; template <class Epi, bool ALIGN_EPI>
; __device__ __forceinline__ void gemm_phase(LAS unsigned char* lds, const Gemm g, const StaticOrder& S, const Epi& E, const int tid) {
;     ...
;             PG8_WAIT_V(8); PG8_WAIT_L(0); PG8_BAR; PG8_MMA(1, 0, At, B0); PG8_MMA(1, 1, At, B1); PG8_BAR; PG8_SCHED;
	v_mfma_f32_16x16x32_bf16 v[24:27], v[132:135], v[180:183], v[24:27]
	v_mfma_f32_16x16x32_bf16 v[24:27], v[148:151], v[184:187], v[24:27]
	v_mfma_f32_16x16x32_bf16 v[20:23], v[160:163], v[184:187], v[20:23]
	v_mfma_f32_16x16x32_bf16 v[20:23], v[156:159], v[180:183], v[20:23]
	v_mfma_f32_16x16x32_bf16 v[124:127], v[172:175], v[180:183], v[124:127]
	v_mfma_f32_16x16x32_bf16 v[124:127], v[176:179], v[184:187], v[124:127]
	v_mfma_f32_16x16x32_bf16 v[128:131], v[168:171], v[184:187], v[128:131]
	v_mfma_f32_16x16x32_bf16 v[128:131], v[164:167], v[180:183], v[128:131]
	v_mfma_f32_16x16x32_bf16 v[120:123], v[164:167], v[188:191], v[120:123]
	v_mfma_f32_16x16x32_bf16 v[120:123], v[168:171], v[192:195], v[120:123]
	v_mfma_f32_16x16x32_bf16 v[116:119], v[176:179], v[192:195], v[116:119]
	v_mfma_f32_16x16x32_bf16 v[116:119], v[172:175], v[188:191], v[116:119]
	v_mfma_f32_16x16x32_bf16 v[72:75], v[156:159], v[188:191], v[72:75]
	v_mfma_f32_16x16x32_bf16 v[72:75], v[160:163], v[192:195], v[72:75]
	v_mfma_f32_16x16x32_bf16 v[64:67], v[148:151], v[192:195], v[64:67]
	v_mfma_f32_16x16x32_bf16 v[64:67], v[132:135], v[188:191], v[64:67]


; #define PG8_MMA(ai, bj, At, Bt) do { __builtin_amdgcn_s_setprio(1); _Pragma("unroll") for (int m = 0; m < 4; ++m) _Pragma("unroll") for (int n = 0; n < 2; ++n) _Pragma("unroll") for (int k = 0; k < 2; ++k) \
;         acc[ai][bj][m][n] = __builtin_amdgcn_mfma_f32_16x16x32_bf16(Bt[n][k], At[m][k], acc[ai][bj][m][n], 0, 0, 0); __builtin_amdgcn_s_setprio(0); } while (0)
; #define PG8_WAIT_V(n) asm volatile("s_waitcnt vmcnt(" #n ")" ::: "memory")
; #define PG8_WAIT_L(n) asm volatile("s_waitcnt lgkmcnt(" #n ")" ::: "memory")
; #define PG8_BAR __builtin_amdgcn_s_barrier()
; #define PG8_SCHED __builtin_amdgcn_sched_barrier(0)
; template <class Epi, bool ALIGN_EPI>
; __device__ __forceinline__ void gemm_phase(LAS unsigned char* lds, const Gemm g, const StaticOrder& S, const Epi& E, const int tid) {
;     ...
;             PG8_WAIT_V(8); PG8_WAIT_L(0); PG8_BAR; PG8_MMA(1, 0, At, B0); PG8_MMA(1, 1, At, B1); PG8_BAR; PG8_SCHED;
	v_mfma_f32_16x16x32_bf16 v[16:19], v[132:135], v[196:199], v[16:19]
	v_mfma_f32_16x16x32_bf16 v[16:19], v[148:151], v[214:217], v[16:19]
	v_mfma_f32_16x16x32_bf16 v[12:15], v[160:163], v[214:217], v[12:15]
	v_mfma_f32_16x16x32_bf16 v[12:15], v[156:159], v[196:199], v[12:15]
	v_mfma_f32_16x16x32_bf16 v[108:111], v[172:175], v[196:199], v[108:111]
	v_mfma_f32_16x16x32_bf16 v[108:111], v[176:179], v[214:217], v[108:111]
	v_mfma_f32_16x16x32_bf16 v[112:115], v[168:171], v[214:217], v[112:115]
	v_mfma_f32_16x16x32_bf16 v[112:115], v[164:167], v[196:199], v[112:115]
	v_mfma_f32_16x16x32_bf16 v[104:107], v[164:167], v[218:221], v[104:107]
	v_mfma_f32_16x16x32_bf16 v[104:107], v[168:171], v[222:225], v[104:107]
	v_mfma_f32_16x16x32_bf16 v[100:103], v[176:179], v[222:225], v[100:103]
	v_mfma_f32_16x16x32_bf16 v[100:103], v[172:175], v[218:221], v[100:103]
	v_mfma_f32_16x16x32_bf16 v[68:71], v[156:159], v[218:221], v[68:71]
	v_mfma_f32_16x16x32_bf16 v[68:71], v[160:163], v[222:225], v[68:71]
	v_mfma_f32_16x16x32_bf16 v[60:63], v[148:151], v[222:225], v[60:63]
	v_mfma_f32_16x16x32_bf16 v[60:63], v[132:135], v[218:221], v[60:63]

; #define PG8_STAGE(bufoff, gbase, voff) do { _Pragma("unroll") for (int _i = 0; _i < 2; ++_i) \
;         __builtin_amdgcn_global_load_lds((const unsigned*)((const char*)(gbase) + (voff)[_i]), (LAS unsigned*)(lds + (bufoff) + ldsw + _i * 8192), 16, 0, 0); } while (0)
; #define PG8_LDA(dst, b, h) do { _Pragma("unroll") for (int m = 0; m < 4; ++m) _Pragma("unroll") for (int k = 0; k < 2; ++k) dst[m][k] = *(const LAS bf16x8*)(lds + PG8_SA(b, h) + aoff + m * 2048 + k * 1024); } while (0)
; #define PG8_LDB(dst, b, h) do { _Pragma("unroll") for (int n = 0; n < 2; ++n) _Pragma("unroll") for (int k = 0; k < 2; ++k) dst[n][k] = *(const LAS bf16x8*)(lds + PG8_SB(b, h) + boff + n * 2048 + k * 1024); } while (0)
; #define PG8_MMA(ai, bj, At, Bt) do { __builtin_amdgcn_s_setprio(1); _Pragma("unroll") for (int m = 0; m < 4; ++m) _Pragma("unroll") for (int n = 0; n < 2; ++n) _Pragma("unroll") for (int k = 0; k < 2; ++k) \
;         acc[ai][bj][m][n] = __builtin_amdgcn_mfma_f32_16x16x32_bf16(Bt[n][k], At[m][k], acc[ai][bj][m][n], 0, 0, 0); __builtin_amdgcn_s_setprio(0); } while (0)
; #define PG8_WAIT_V(n) asm volatile("s_waitcnt vmcnt(" #n ")" ::: "memory")
; #define PG8_WAIT_L(n) asm volatile("s_waitcnt lgkmcnt(" #n ")" ::: "memory")
; #define PG8_BAR __builtin_amdgcn_s_barrier()
; #define PG8_SCHED __builtin_amdgcn_sched_barrier(0)
; template <class Epi, bool ALIGN_EPI>
; __device__ __forceinline__ void gemm_phase(LAS unsigned char* lds, const Gemm g, const StaticOrder& S, const Epi& E, const int tid) {
;     ...
;             PG8_WAIT_V(8); PG8_WAIT_L(0); PG8_BAR; PG8_MMA(1, 0, At, B0); PG8_MMA(1, 1, At, B1); PG8_BAR; PG8_SCHED;
;             PG8_LDB(B0, 1, 0); PG8_LDB(B1, 1, 1); PG8_SCHED; PG8_LDA(At, 1, 0); PG8_STAGE(PG8_SA(0, 1), a2 + hstepA, voffA);
	s_barrier
	s_add_i32 s87, 0, 0x18000
	v_add_u32_e32 v0, s87, v154
	s_add_i32 s88, 0, 0x1c000
	ds_read_b128 v[132:135], v0
	ds_read_b128 v[148:151], v0 offset:1024
	ds_read_b128 v[156:159], v0 offset:2048
	ds_read_b128 v[160:163], v0 offset:3072
	v_add_u32_e32 v0, s88, v154
	ds_read_b128 v[164:167], v0
	ds_read_b128 v[168:171], v0 offset:1024
	ds_read_b128 v[172:175], v0 offset:2048
	ds_read_b128 v[176:179], v0 offset:3072
	s_add_u32 s34, s34, 0x80000
	s_addc_u32 s35, s35, 0
	s_mov_b32 m0, s72
	ds_read_b128 v[180:183], v155 offset:32768
	ds_read_b128 v[184:187], v155 offset:33792
	ds_read_b128 v[188:191], v155 offset:34816
	ds_read_b128 v[192:195], v155 offset:35840
	ds_read_b128 v[196:199], v155 offset:36864
	ds_read_b128 v[214:217], v155 offset:37888
	ds_read_b128 v[218:221], v155 offset:38912

; #define PG8_STAGE(bufoff, gbase, voff) do { _Pragma("unroll") for (int _i = 0; _i < 2; ++_i) \
;         __builtin_amdgcn_global_load_lds((const unsigned*)((const char*)(gbase) + (voff)[_i]), (LAS unsigned*)(lds + (bufoff) + ldsw + _i * 8192), 16, 0, 0); } while (0)
; #define PG8_LDA(dst, b, h) do { _Pragma("unroll") for (int m = 0; m < 4; ++m) _Pragma("unroll") for (int k = 0; k < 2; ++k) dst[m][k] = *(const LAS bf16x8*)(lds + PG8_SA(b, h) + aoff + m * 2048 + k * 1024); } while (0)
; #define PG8_LDB(dst, b, h) do { _Pragma("unroll") for (int n = 0; n < 2; ++n) _Pragma("unroll") for (int k = 0; k < 2; ++k) dst[n][k] = *(const LAS bf16x8*)(lds + PG8_SB(b, h) + boff + n * 2048 + k * 1024); } while (0)
; #define PG8_MMA(ai, bj, At, Bt) do { __builtin_amdgcn_s_setprio(1); _Pragma("unroll") for (int m = 0; m < 4; ++m) _Pragma("unroll") for (int n = 0; n < 2; ++n) _Pragma("unroll") for (int k = 0; k < 2; ++k) \
;         acc[ai][bj][m][n] = __builtin_amdgcn_mfma_f32_16x16x32_bf16(Bt[n][k], At[m][k], acc[ai][bj][m][n], 0, 0, 0); __builtin_amdgcn_s_setprio(0); } while (0)
; #define PG8_WAIT_V(n) asm volatile("s_waitcnt vmcnt(" #n ")" ::: "memory")
; #define PG8_WAIT_L(n) asm volatile("s_waitcnt lgkmcnt(" #n ")" ::: "memory")
; #define PG8_BAR __builtin_amdgcn_s_barrier()
; #define PG8_SCHED __builtin_amdgcn_sched_barrier(0)
; template <class Epi, bool ALIGN_EPI>
; __device__ __forceinline__ void gemm_phase(LAS unsigned char* lds, const Gemm g, const StaticOrder& S, const Epi& E, const int tid) {
;     ...
;             PG8_LDB(B0, 1, 0); PG8_LDB(B1, 1, 1); PG8_SCHED; PG8_LDA(At, 1, 0); PG8_STAGE(PG8_SA(0, 1), a2 + hstepA, voffA);
;             PG8_WAIT_V(8); PG8_WAIT_L(0); PG8_BAR; PG8_MMA(0, 0, At, B0); PG8_MMA(0, 1, At, B1); PG8_BAR; PG8_SCHED;
	global_load_lds_dwordx4 v142, s[34:35]
	s_mov_b32 m0, s73
	ds_read_b128 v[222:225], v155 offset:39936
	global_load_lds_dwordx4 v138, s[34:35]
	s_waitcnt vmcnt(8)
	s_waitcnt lgkmcnt(0)
	s_barrier


; #define PG8_MMA(ai, bj, At, Bt) do { __builtin_amdgcn_s_setprio(1); _Pragma("unroll") for (int m = 0; m < 4; ++m) _Pragma("unroll") for (int n = 0; n < 2; ++n) _Pragma("unroll") for (int k = 0; k < 2; ++k) \
;         acc[ai][bj][m][n] = __builtin_amdgcn_mfma_f32_16x16x32_bf16(Bt[n][k], At[m][k], acc[ai][bj][m][n], 0, 0, 0); __builtin_amdgcn_s_setprio(0); } while (0)
; #define PG8_WAIT_V(n) asm volatile("s_waitcnt vmcnt(" #n ")" ::: "memory")
; #define PG8_WAIT_L(n) asm volatile("s_waitcnt lgkmcnt(" #n ")" ::: "memory")
; #define PG8_BAR __builtin_amdgcn_s_barrier()
; #define PG8_SCHED __builtin_amdgcn_sched_barrier(0)
; template <class Epi, bool ALIGN_EPI>
; __device__ __forceinline__ void gemm_phase(LAS unsigned char* lds, const Gemm g, const StaticOrder& S, const Epi& E, const int tid) {
;     ...
;             PG8_WAIT_V(8); PG8_WAIT_L(0); PG8_BAR; PG8_MMA(0, 0, At, B0); PG8_MMA(0, 1, At, B1); PG8_BAR; PG8_SCHED;
	v_mfma_f32_16x16x32_bf16 v[6:9], v[132:135], v[180:183], v[8:11]
	v_mfma_f32_16x16x32_bf16 v[8:11], v[148:151], v[184:187], v[6:9]
	v_mfma_f32_16x16x32_bf16 v[56:59], v[160:163], v[184:187], v[56:59]
	v_mfma_f32_16x16x32_bf16 v[56:59], v[156:159], v[180:183], v[56:59]
	v_mfma_f32_16x16x32_bf16 v[28:31], v[172:175], v[180:183], v[28:31]
	v_mfma_f32_16x16x32_bf16 v[28:31], v[176:179], v[184:187], v[28:31]
	v_mfma_f32_16x16x32_bf16 v[2:5], v[164:167], v[180:183], v[2:5]
	v_mfma_f32_16x16x32_bf16 v[4:7], v[168:171], v[184:187], v[2:5]
	v_mfma_f32_16x16x32_bf16 v[96:99], v[168:171], v[192:195], v[96:99]
	v_mfma_f32_16x16x32_bf16 v[96:99], v[164:167], v[188:191], v[96:99]
	v_mfma_f32_16x16x32_bf16 v[92:95], v[172:175], v[188:191], v[92:95]
	v_mfma_f32_16x16x32_bf16 v[92:95], v[176:179], v[192:195], v[92:95]
	v_mfma_f32_16x16x32_bf16 v[48:51], v[160:163], v[192:195], v[48:51]
	v_mfma_f32_16x16x32_bf16 v[48:51], v[156:159], v[188:191], v[48:51]
	v_mfma_f32_16x16x32_bf16 v[52:55], v[132:135], v[188:191], v[52:55]
	v_mfma_f32_16x16x32_bf16 v[52:55], v[148:151], v[192:195], v[52:55]


; #define PG8_MMA(ai, bj, At, Bt) do { __builtin_amdgcn_s_setprio(1); _Pragma("unroll") for (int m = 0; m < 4; ++m) _Pragma("unroll") for (int n = 0; n < 2; ++n) _Pragma("unroll") for (int k = 0; k < 2; ++k) \
;         acc[ai][bj][m][n] = __builtin_amdgcn_mfma_f32_16x16x32_bf16(Bt[n][k], At[m][k], acc[ai][bj][m][n], 0, 0, 0); __builtin_amdgcn_s_setprio(0); } while (0)
; #define PG8_WAIT_V(n) asm volatile("s_waitcnt vmcnt(" #n ")" ::: "memory")
; #define PG8_WAIT_L(n) asm volatile("s_waitcnt lgkmcnt(" #n ")" ::: "memory")
; #define PG8_BAR __builtin_amdgcn_s_barrier()
; #define PG8_SCHED __builtin_amdgcn_sched_barrier(0)
; template <class Epi, bool ALIGN_EPI>
; __device__ __forceinline__ void gemm_phase(LAS unsigned char* lds, const Gemm g, const StaticOrder& S, const Epi& E, const int tid) {
;     ...
;             PG8_WAIT_V(8); PG8_WAIT_L(0); PG8_BAR; PG8_MMA(0, 0, At, B0); PG8_MMA(0, 1, At, B1); PG8_BAR; PG8_SCHED;
	v_mfma_f32_16x16x32_bf16 v[44:47], v[148:151], v[214:217], v[44:47]
	v_mfma_f32_16x16x32_bf16 v[44:47], v[132:135], v[196:199], v[44:47]
	v_mfma_f32_16x16x32_bf16 v[40:43], v[156:159], v[196:199], v[40:43]
	v_mfma_f32_16x16x32_bf16 v[40:43], v[160:163], v[214:217], v[40:43]
	v_mfma_f32_16x16x32_bf16 v[84:87], v[176:179], v[214:217], v[84:87]
	v_mfma_f32_16x16x32_bf16 v[84:87], v[172:175], v[196:199], v[84:87]
	v_mfma_f32_16x16x32_bf16 v[88:91], v[164:167], v[196:199], v[88:91]
	v_mfma_f32_16x16x32_bf16 v[88:91], v[168:171], v[214:217], v[88:91]
	v_mfma_f32_16x16x32_bf16 v[80:83], v[168:171], v[222:225], v[80:83]
	v_mfma_f32_16x16x32_bf16 v[80:83], v[164:167], v[218:221], v[80:83]
	v_mfma_f32_16x16x32_bf16 v[76:79], v[172:175], v[218:221], v[76:79]
	v_mfma_f32_16x16x32_bf16 v[76:79], v[176:179], v[222:225], v[76:79]
	v_mfma_f32_16x16x32_bf16 v[32:35], v[160:163], v[222:225], v[32:35]
	v_mfma_f32_16x16x32_bf16 v[32:35], v[156:159], v[218:221], v[32:35]
	v_mfma_f32_16x16x32_bf16 v[36:39], v[132:135], v[218:221], v[36:39]
	v_mfma_f32_16x16x32_bf16 v[36:39], v[148:151], v[222:225], v[36:39]

; #define PG8_STAGE(bufoff, gbase, voff) do { _Pragma("unroll") for (int _i = 0; _i < 2; ++_i) \
;         __builtin_amdgcn_global_load_lds((const unsigned*)((const char*)(gbase) + (voff)[_i]), (LAS unsigned*)(lds + (bufoff) + ldsw + _i * 8192), 16, 0, 0); } while (0)
; #define PG8_LDA(dst, b, h) do { _Pragma("unroll") for (int m = 0; m < 4; ++m) _Pragma("unroll") for (int k = 0; k < 2; ++k) dst[m][k] = *(const LAS bf16x8*)(lds + PG8_SA(b, h) + aoff + m * 2048 + k * 1024); } while (0)
; #define PG8_MMA(ai, bj, At, Bt) do { __builtin_amdgcn_s_setprio(1); _Pragma("unroll") for (int m = 0; m < 4; ++m) _Pragma("unroll") for (int n = 0; n < 2; ++n) _Pragma("unroll") for (int k = 0; k < 2; ++k) \
;         acc[ai][bj][m][n] = __builtin_amdgcn_mfma_f32_16x16x32_bf16(Bt[n][k], At[m][k], acc[ai][bj][m][n], 0, 0, 0); __builtin_amdgcn_s_setprio(0); } while (0)
; #define PG8_WAIT_V(n) asm volatile("s_waitcnt vmcnt(" #n ")" ::: "memory")
; #define PG8_WAIT_L(n) asm volatile("s_waitcnt lgkmcnt(" #n ")" ::: "memory")
; #define PG8_BAR __builtin_amdgcn_s_barrier()
; #define PG8_SCHED __builtin_amdgcn_sched_barrier(0)
; template <class Epi, bool ALIGN_EPI>
; __device__ __forceinline__ void gemm_phase(LAS unsigned char* lds, const Gemm g, const StaticOrder& S, const Epi& E, const int tid) {
;     ...
;             PG8_WAIT_V(8); PG8_WAIT_L(0); PG8_BAR; PG8_MMA(0, 0, At, B0); PG8_MMA(0, 1, At, B1); PG8_BAR; PG8_SCHED;
;             PG8_LDA(At, 1, 1); PG8_STAGE(PG8_SB(1, 0), b3, voffB); PG8_STAGE(PG8_SB(1, 1), b3 + hstepB, voffB); PG8_STAGE(PG8_SA(1, 0), a3, voffA);
	s_barrier
	s_add_u32 s34, s22, 0x8000
	s_addc_u32 s35, s23, 0
	s_add_i32 s87, s87, s61
	s_mov_b32 m0, s87
	ds_read_b128 v[180:183], v155 offset:49152
	ds_read_b128 v[184:187], v155 offset:50176
	ds_read_b128 v[188:191], v155 offset:51200
	ds_read_b128 v[192:195], v155 offset:52224


; #define PG8_STAGE(bufoff, gbase, voff) do { _Pragma("unroll") for (int _i = 0; _i < 2; ++_i) \
;         __builtin_amdgcn_global_load_lds((const unsigned*)((const char*)(gbase) + (voff)[_i]), (LAS unsigned*)(lds + (bufoff) + ldsw + _i * 8192), 16, 0, 0); } while (0)
; #define PG8_LDA(dst, b, h) do { _Pragma("unroll") for (int m = 0; m < 4; ++m) _Pragma("unroll") for (int k = 0; k < 2; ++k) dst[m][k] = *(const LAS bf16x8*)(lds + PG8_SA(b, h) + aoff + m * 2048 + k * 1024); } while (0)
; #define PG8_MMA(ai, bj, At, Bt) do { __builtin_amdgcn_s_setprio(1); _Pragma("unroll") for (int m = 0; m < 4; ++m) _Pragma("unroll") for (int n = 0; n < 2; ++n) _Pragma("unroll") for (int k = 0; k < 2; ++k) \
;         acc[ai][bj][m][n] = __builtin_amdgcn_mfma_f32_16x16x32_bf16(Bt[n][k], At[m][k], acc[ai][bj][m][n], 0, 0, 0); __builtin_amdgcn_s_setprio(0); } while (0)
; #define PG8_WAIT_V(n) asm volatile("s_waitcnt vmcnt(" #n ")" ::: "memory")
; #define PG8_WAIT_L(n) asm volatile("s_waitcnt lgkmcnt(" #n ")" ::: "memory")
; #define PG8_BAR __builtin_amdgcn_s_barrier()
; #define PG8_SCHED __builtin_amdgcn_sched_barrier(0)
; template <class Epi, bool ALIGN_EPI>
; __device__ __forceinline__ void gemm_phase(LAS unsigned char* lds, const Gemm g, const StaticOrder& S, const Epi& E, const int tid) {
;     ...
;             PG8_LDA(At, 1, 1); PG8_STAGE(PG8_SB(1, 0), b3, voffB); PG8_STAGE(PG8_SB(1, 1), b3 + hstepB, voffB); PG8_STAGE(PG8_SA(1, 0), a3, voffA);
;             PG8_WAIT_V(8); PG8_WAIT_L(0); PG8_BAR; PG8_MMA(1, 0, At, B0); PG8_MMA(1, 1, At, B1); PG8_BAR; PG8_SCHED;
	global_load_lds_dwordx4 v140, s[34:35]
	s_add_i32 m0, s87, 0x2000
	s_add_u32 s22, s22, 0xc000
	s_addc_u32 s23, s23, 0
	global_load_lds_dwordx4 v136, s[34:35]
	s_add_i32 s34, s88, s61
	s_mov_b32 m0, s34
	ds_read_b128 v[222:225], v155 offset:56320
	global_load_lds_dwordx4 v140, s[22:23]
	s_add_i32 m0, s34, 0x2000
	ds_read_b128 v[218:221], v155 offset:55296
	global_load_lds_dwordx4 v136, s[22:23]
	v_lshl_add_u64 v[2:3], v[152:153], 0, s[6:7]
	s_mov_b32 m0, s78
	ds_read_b128 v[214:217], v155 offset:54272
	global_load_lds_dwordx4 v[2:3], off
	v_lshl_add_u64 v[2:3], v[200:201], 0, s[6:7]
	s_mov_b32 m0, s79
	ds_read_b128 v[196:199], v155 offset:53248
	global_load_lds_dwordx4 v[2:3], off
	s_waitcnt vmcnt(8)
	s_waitcnt lgkmcnt(0)
	s_barrier


; #define PG8_MMA(ai, bj, At, Bt) do { __builtin_amdgcn_s_setprio(1); _Pragma("unroll") for (int m = 0; m < 4; ++m) _Pragma("unroll") for (int n = 0; n < 2; ++n) _Pragma("unroll") for (int k = 0; k < 2; ++k) \
;         acc[ai][bj][m][n] = __builtin_amdgcn_mfma_f32_16x16x32_bf16(Bt[n][k], At[m][k], acc[ai][bj][m][n], 0, 0, 0); __builtin_amdgcn_s_setprio(0); } while (0)
; #define PG8_WAIT_V(n) asm volatile("s_waitcnt vmcnt(" #n ")" ::: "memory")
; #define PG8_WAIT_L(n) asm volatile("s_waitcnt lgkmcnt(" #n ")" ::: "memory")
; #define PG8_BAR __builtin_amdgcn_s_barrier()
; #define PG8_SCHED __builtin_amdgcn_sched_barrier(0)
; template <class Epi, bool ALIGN_EPI>
; __device__ __forceinline__ void gemm_phase(LAS unsigned char* lds, const Gemm g, const StaticOrder& S, const Epi& E, const int tid) {
;     ...
;             PG8_WAIT_V(8); PG8_WAIT_L(0); PG8_BAR; PG8_MMA(1, 0, At, B0); PG8_MMA(1, 1, At, B1); PG8_BAR; PG8_SCHED;
	v_mfma_f32_16x16x32_bf16 v[24:27], v[132:135], v[180:183], v[24:27]
	v_mfma_f32_16x16x32_bf16 v[24:27], v[148:151], v[184:187], v[24:27]
	v_mfma_f32_16x16x32_bf16 v[20:23], v[160:163], v[184:187], v[20:23]
	v_mfma_f32_16x16x32_bf16 v[20:23], v[156:159], v[180:183], v[20:23]
	v_mfma_f32_16x16x32_bf16 v[124:127], v[172:175], v[180:183], v[124:127]
	v_mfma_f32_16x16x32_bf16 v[124:127], v[176:179], v[184:187], v[124:127]
	v_mfma_f32_16x16x32_bf16 v[128:131], v[168:171], v[184:187], v[128:131]
	v_mfma_f32_16x16x32_bf16 v[128:131], v[164:167], v[180:183], v[128:131]
	v_mfma_f32_16x16x32_bf16 v[120:123], v[164:167], v[188:191], v[120:123]
	v_mfma_f32_16x16x32_bf16 v[120:123], v[168:171], v[192:195], v[120:123]
	v_mfma_f32_16x16x32_bf16 v[116:119], v[176:179], v[192:195], v[116:119]
	v_mfma_f32_16x16x32_bf16 v[116:119], v[172:175], v[188:191], v[116:119]
	v_mfma_f32_16x16x32_bf16 v[72:75], v[156:159], v[188:191], v[72:75]
	v_mfma_f32_16x16x32_bf16 v[72:75], v[160:163], v[192:195], v[72:75]
	v_mfma_f32_16x16x32_bf16 v[64:67], v[148:151], v[192:195], v[64:67]
	v_mfma_f32_16x16x32_bf16 v[64:67], v[132:135], v[188:191], v[64:67]


; #define PG8_MMA(ai, bj, At, Bt) do { __builtin_amdgcn_s_setprio(1); _Pragma("unroll") for (int m = 0; m < 4; ++m) _Pragma("unroll") for (int n = 0; n < 2; ++n) _Pragma("unroll") for (int k = 0; k < 2; ++k) \
;         acc[ai][bj][m][n] = __builtin_amdgcn_mfma_f32_16x16x32_bf16(Bt[n][k], At[m][k], acc[ai][bj][m][n], 0, 0, 0); __builtin_amdgcn_s_setprio(0); } while (0)
; #define PG8_WAIT_V(n) asm volatile("s_waitcnt vmcnt(" #n ")" ::: "memory")
; #define PG8_WAIT_L(n) asm volatile("s_waitcnt lgkmcnt(" #n ")" ::: "memory")
; #define PG8_BAR __builtin_amdgcn_s_barrier()
; #define PG8_SCHED __builtin_amdgcn_sched_barrier(0)
; template <class Epi, bool ALIGN_EPI>
; __device__ __forceinline__ void gemm_phase(LAS unsigned char* lds, const Gemm g, const StaticOrder& S, const Epi& E, const int tid) {
;     ...
;             PG8_WAIT_V(8); PG8_WAIT_L(0); PG8_BAR; PG8_MMA(1, 0, At, B0); PG8_MMA(1, 1, At, B1); PG8_BAR; PG8_SCHED;
	v_mfma_f32_16x16x32_bf16 v[16:19], v[132:135], v[196:199], v[16:19]
	v_mfma_f32_16x16x32_bf16 v[16:19], v[148:151], v[214:217], v[16:19]
	v_mfma_f32_16x16x32_bf16 v[12:15], v[160:163], v[214:217], v[12:15]
	v_mfma_f32_16x16x32_bf16 v[12:15], v[156:159], v[196:199], v[12:15]
	v_mfma_f32_16x16x32_bf16 v[108:111], v[172:175], v[196:199], v[108:111]
	v_mfma_f32_16x16x32_bf16 v[108:111], v[176:179], v[214:217], v[108:111]
	v_mfma_f32_16x16x32_bf16 v[112:115], v[168:171], v[214:217], v[112:115]
	v_mfma_f32_16x16x32_bf16 v[112:115], v[164:167], v[196:199], v[112:115]
	v_mfma_f32_16x16x32_bf16 v[104:107], v[164:167], v[218:221], v[104:107]
	v_mfma_f32_16x16x32_bf16 v[104:107], v[168:171], v[222:225], v[104:107]
	v_mfma_f32_16x16x32_bf16 v[100:103], v[176:179], v[222:225], v[100:103]
	v_mfma_f32_16x16x32_bf16 v[100:103], v[172:175], v[218:221], v[100:103]
	v_mfma_f32_16x16x32_bf16 v[68:71], v[156:159], v[218:221], v[68:71]
	v_mfma_f32_16x16x32_bf16 v[68:71], v[160:163], v[222:225], v[68:71]
	v_mfma_f32_16x16x32_bf16 v[60:63], v[148:151], v[222:225], v[60:63]
	v_mfma_f32_16x16x32_bf16 v[60:63], v[132:135], v[218:221], v[60:63]

; #define PG8_MMA(ai, bj, At, Bt) do { __builtin_amdgcn_s_setprio(1); _Pragma("unroll") for (int m = 0; m < 4; ++m) _Pragma("unroll") for (int n = 0; n < 2; ++n) _Pragma("unroll") for (int k = 0; k < 2; ++k) \
;         acc[ai][bj][m][n] = __builtin_amdgcn_mfma_f32_16x16x32_bf16(Bt[n][k], At[m][k], acc[ai][bj][m][n], 0, 0, 0); __builtin_amdgcn_s_setprio(0); } while (0)
; #define PG8_WAIT_V(n) asm volatile("s_waitcnt vmcnt(" #n ")" ::: "memory")
; #define PG8_WAIT_L(n) asm volatile("s_waitcnt lgkmcnt(" #n ")" ::: "memory")
; #define PG8_BAR __builtin_amdgcn_s_barrier()
; #define PG8_SCHED __builtin_amdgcn_sched_barrier(0)
; template <class Epi, bool ALIGN_EPI>
; __device__ __forceinline__ void gemm_phase(LAS unsigned char* lds, const Gemm g, const StaticOrder& S, const Epi& E, const int tid) {
;     ...
;             PG8_WAIT_V(8); PG8_WAIT_L(0); PG8_BAR; PG8_MMA(1, 0, At, B0); PG8_MMA(1, 1, At, B1); PG8_BAR; PG8_SCHED;
;         }
;         if constexpr (ALIGN_EPI) { if (wr == 0) PG8_BAR; }
;     __device__ __forceinline__ void operator()(f32x4 (&acc)[2][2][4][2], const Unit& u, int wr, int wc, LAS unsigned char* lds, int& rs_pm) const {
;     ...
;                 bf16* const xrow = xb + (((size_t)(u.pm * 32 + u.pn * 4 + (wc >> 1)) * BM + (wr * 64 + fr + ai * HALF + m * 16)) * 64 + (wc & 1) * 32 + 8 * fq);
; #pragma unroll
;                 for (int bj = 0; bj < 2; ++bj) {
;                     const u32x4 xw = *(const u32x4*)(xrow + (size_t)bj * (2 * BM * 64));
	s_barrier
	s_add_i32 s86, s86, 2
	s_add_u32 s10, s10, 0x100
	s_addc_u32 s11, s11, 0
	s_add_u32 s84, s84, 0x10000
	s_addc_u32 s85, s85, 0
	s_cmp_gt_u32 s86, 29
	s_cbranch_scc0 .LBB0_847
	v_and_b32_e32 v222, 15, v238
	v_lshrrev_b32_e32 v156, 4, v238
	s_lshl_b32 s100, s40, 5
	s_lshl_b32 s101, s41, 2
	v_lshlrev_b32_e32 v222, 7, v222
	s_add_i32 s100, s100, s101
	s_or_b32 s100, s100, s80
	v_lshl_or_b32 v222, v156, 4, v222
	s_ashr_i32 s101, s100, 31
	s_lshl_b64 s[100:101], s[100:101], 15
	s_add_u32 s98, s74, s100
	s_addc_u32 s99, s75, s101
	s_add_u32 s98, s98, s30
	s_addc_u32 s99, s99, s31
	s_lshl_b32 s100, s77, 7
	s_add_u32 s98, s98, s100
	s_addc_u32 s99, s99, 0
	s_lshl_b32 s100, s40, 15
	s_lshl_b32 s101, s77, 7
	s_add_i32 s100, s100, s101
	s_lshl_b32 s101, s41, 4
	s_add_i32 s100, s100, s101
	s_lshl_b32 s101, s76, 2
	s_add_i32 s100, s100, s101
	s_add_u32 s22, s42, s100
	s_addc_u32 s23, s43, 0
	global_load_dwordx4 v[176:179], v222, s[98:99]
	s_add_u32 s100, s98, 0x10000
	s_addc_u32 s101, s99, 0
	global_load_dwordx4 v[180:183], v222, s[100:101]
	global_load_dwordx4 v[184:187], v222, s[98:99] offset:2048
	s_add_u32 s100, s98, 0x10000
	s_addc_u32 s101, s99, 0
	global_load_dwordx4 v[188:191], v222, s[100:101] offset:2048
	s_add_u32 s100, s98, 0x1000
	s_addc_u32 s101, s99, 0
	global_load_dwordx4 v[192:195], v222, s[100:101]
	s_add_u32 s100, s98, 0x11000
	s_addc_u32 s101, s99, 0
	global_load_dwordx4 v[196:199], v222, s[100:101]
	s_add_u32 s100, s98, 0x1000
	s_addc_u32 s101, s99, 0
	global_load_dwordx4 v[214:217], v222, s[100:101] offset:2048
	s_add_u32 s100, s98, 0x11000
	s_addc_u32 s101, s99, 0
	global_load_dwordx4 v[218:221], v222, s[100:101] offset:2048
	s_and_b64 vcc, exec, s[44:45]
	s_cbranch_vccz .LBB0_850
	s_barrier
